# GEMM K-loops: 30 duplicate s_waitcnt lgkmcnt(0) (compiler copy right after the inline-asm one) deleted
# baseline (speedup 1.0000x reference)
; #define G8_STAGE(bufoff, gbase) do { _Pragma("unroll") for (int _i = 0; _i < 2; ++_i) \
;     __builtin_amdgcn_global_load_lds((const unsigned*)((const char*)(gbase) + voffA[_i]), (LAS unsigned*)(lds + (bufoff) + ldsw + _i * 8192), 16, 0, 0); } while (0)
; #define G8_WAIT_V(n) asm volatile("s_waitcnt vmcnt(" #n ")" ::: "memory")
; #define G8_WAIT_L(n) asm volatile("s_waitcnt lgkmcnt(" #n ")" ::: "memory")
; template <class Epi>
; __device__ __forceinline__ void gemm_phase(LAS unsigned char* lds, const h16* A, const h16* Bt, int K, const Order& S, const Epi& E) {
;     ...
;     for (int t = 0; t < nt; t += 2) {
;       const bool last = (t == nt - 2);
;       const char* a1 = cA + (size_t)(t + 1) * kstep;
;       const char* a2 = last ? nA : cA + (size_t)(t + 2) * kstep;
;       const char* b2 = last ? nB : cB + (size_t)(t + 2) * kstep;
;       const char* a3 = a2 + kstep;
;       const char* b3 = b2 + kstep;
;       if (Epi::MID_T >= 0 && t == Epi::MID_T) E.mid(acc, ui, wr, fr);
;       G8_LDB(B0, 0, 0); G8_SCHED; G8_LDA(At, 0, 0); G8_STAGE(G8_SA(1, 1), a1 + hstep);
;       G8_WAIT_L(8); G8_BAR; G8_WAIT_L(0); G8_MMA(0, 0, At, B0); G8_BAR; G8_SCHED;
;       G8_LDB(B1, 0, 1); G8_STAGE(G8_SB(0, 0), b2);
;       G8_BAR; G8_WAIT_L(0); G8_MMA(0, 1, At, B1); G8_BAR;
;       G8_LDA(At, 0, 1); G8_STAGE(G8_SA(0, 0), a2);
;       G8_BAR; G8_WAIT_L(0); G8_MMA(1, 0, At, B0); G8_BAR; G8_SCHED;
;       G8_STAGE(G8_SB(0, 1), b2 + hstep);
;       G8_WAIT_V(6); G8_BAR; G8_MMA(1, 1, At, B1); G8_BAR;
;       G8_LDB(B0, 1, 0); G8_SCHED; G8_LDA(At, 1, 0); G8_STAGE(G8_SA(0, 1), a2 + hstep);
;       G8_WAIT_L(8); G8_BAR; G8_WAIT_L(0); G8_MMA(0, 0, At, B0); G8_BAR; G8_SCHED;
;       G8_LDB(B1, 1, 1); G8_STAGE(G8_SB(1, 0), b3);
;       G8_BAR; G8_WAIT_L(0); G8_MMA(0, 1, At, B1); G8_BAR;
;       G8_LDA(At, 1, 1); G8_STAGE(G8_SA(1, 0), a3);
;       G8_BAR; G8_WAIT_L(0); G8_MMA(1, 0, At, B0); G8_BAR; G8_SCHED;
;       G8_STAGE(G8_SB(1, 1), b3 + hstep);
;       G8_WAIT_V(6); G8_BAR; G8_MMA(1, 1, At, B1); G8_BAR;
;   __device__ __forceinline__ void operator()(const f32x4 (&acc)[2][2][4][2], const g8::Unit& u, int ui, int wr, int wc, int fr, int fq) const {
;     const int hs = u.pn * 4 + wc;
;     int gi = -1;
;     if (hs < 4) gi = 0; else if (hs < 6) gi = 1; else if (hs >= 16 && hs < 20) gi = 2; else if (hs == 22) gi = 4; else if (hs == 24) gi = 5;
.LBB0_195:
	s_add_u32 s12, s10, 0xfffc0080
	s_addc_u32 s13, s11, -1
	s_cmp_eq_u32 s54, 12
	s_cselect_b32 s15, s19, s13
	s_cselect_b32 s14, s25, s12
	s_cselect_b32 s13, s17, s53
	s_cselect_b32 s12, s26, s27
	s_mov_b32 m0, s50
	v_lshl_add_u64 v[140:141], s[10:11], 0, v[136:137]
	ds_read_b128 v[202:205], v159
	ds_read_b128 v[206:209], v159 offset:1024
	ds_read_b128 v[210:213], v159 offset:2048
	ds_read_b128 v[214:217], v159 offset:3072
	ds_read_b128 v[218:221], v159 offset:4096
	ds_read_b128 v[222:225], v159 offset:5120
	ds_read_b128 v[226:229], v159 offset:6144
	ds_read_b128 v[230:233], v159 offset:7168
	global_load_lds_dwordx4 v[140:141], off
	v_lshl_add_u64 v[140:141], s[10:11], 0, v[138:139]
	s_mov_b32 m0, s51
	s_nop 0
	global_load_lds_dwordx4 v[140:141], off
	s_waitcnt lgkmcnt(8)
	s_barrier
	s_waitcnt lgkmcnt(0)
	v_mfma_f32_16x16x32_f16 v[126:129], v[152:155], v[202:205], v[126:129]
	v_mfma_f32_16x16x32_f16 v[122:125], v[182:185], v[202:205], v[122:125]
	v_mfma_f32_16x16x32_f16 v[110:113], v[152:155], v[210:213], v[110:113]
	v_mfma_f32_16x16x32_f16 v[106:109], v[182:185], v[210:213], v[106:109]
	v_mfma_f32_16x16x32_f16 v[94:97], v[152:155], v[218:221], v[94:97]
	v_mfma_f32_16x16x32_f16 v[90:93], v[182:185], v[218:221], v[90:93]
	v_mfma_f32_16x16x32_f16 v[78:81], v[152:155], v[226:229], v[78:81]
	v_mfma_f32_16x16x32_f16 v[74:77], v[182:185], v[226:229], v[74:77]
	v_mfma_f32_16x16x32_f16 v[126:129], v[178:181], v[206:209], v[126:129]
	v_mfma_f32_16x16x32_f16 v[122:125], v[186:189], v[206:209], v[122:125]
	v_mfma_f32_16x16x32_f16 v[110:113], v[178:181], v[214:217], v[110:113]
	v_mfma_f32_16x16x32_f16 v[106:109], v[186:189], v[214:217], v[106:109]
	v_mfma_f32_16x16x32_f16 v[94:97], v[178:181], v[222:225], v[94:97]
	v_mfma_f32_16x16x32_f16 v[90:93], v[186:189], v[222:225], v[90:93]
	v_mfma_f32_16x16x32_f16 v[78:81], v[178:181], v[230:233], v[78:81]
	v_mfma_f32_16x16x32_f16 v[74:77], v[186:189], v[230:233], v[74:77]
	s_barrier
	s_mov_b32 m0, s36
	v_lshl_add_u64 v[140:141], s[12:13], 0, v[132:133]
	ds_read_b128 v[234:237], v165
	ds_read_b128 v[238:241], v166
	ds_read_b128 v[242:245], v167
	ds_read_b128 v[246:249], v168
	global_load_lds_dwordx4 v[140:141], off
	v_lshl_add_u64 v[156:157], s[12:13], 0, v[130:131]
	s_mov_b32 m0, s37
	s_nop 0
	global_load_lds_dwordx4 v[156:157], off
	s_barrier
	s_waitcnt lgkmcnt(0)
	v_mfma_f32_16x16x32_f16 v[118:121], v[234:237], v[202:205], v[118:121]
	v_mfma_f32_16x16x32_f16 v[114:117], v[242:245], v[202:205], v[114:117]
	v_mfma_f32_16x16x32_f16 v[102:105], v[234:237], v[210:213], v[102:105]
	v_mfma_f32_16x16x32_f16 v[98:101], v[242:245], v[210:213], v[98:101]
	v_mfma_f32_16x16x32_f16 v[86:89], v[234:237], v[218:221], v[86:89]
	v_mfma_f32_16x16x32_f16 v[82:85], v[242:245], v[218:221], v[82:85]
	v_mfma_f32_16x16x32_f16 v[70:73], v[234:237], v[226:229], v[70:73]
	v_mfma_f32_16x16x32_f16 v[66:69], v[242:245], v[226:229], v[66:69]
	v_mfma_f32_16x16x32_f16 v[118:121], v[238:241], v[206:209], v[118:121]
	v_mfma_f32_16x16x32_f16 v[114:117], v[246:249], v[206:209], v[114:117]
	v_mfma_f32_16x16x32_f16 v[102:105], v[238:241], v[214:217], v[102:105]
	v_mfma_f32_16x16x32_f16 v[98:101], v[246:249], v[214:217], v[98:101]
	v_mfma_f32_16x16x32_f16 v[86:89], v[238:241], v[222:225], v[86:89]
	v_mfma_f32_16x16x32_f16 v[82:85], v[246:249], v[222:225], v[82:85]
	v_mfma_f32_16x16x32_f16 v[70:73], v[238:241], v[230:233], v[70:73]
	v_mfma_f32_16x16x32_f16 v[66:69], v[246:249], v[230:233], v[66:69]
	s_mov_b32 m0, s35
	v_lshl_add_u64 v[250:251], s[14:15], 0, v[132:133]
	s_barrier
	ds_read_b128 v[202:205], v159 offset:16384
	ds_read_b128 v[206:209], v159 offset:17408
	ds_read_b128 v[210:213], v159 offset:18432
	ds_read_b128 v[214:217], v159 offset:19456
	ds_read_b128 v[218:221], v159 offset:20480
	ds_read_b128 v[222:225], v159 offset:21504
	ds_read_b128 v[226:229], v159 offset:22528
	ds_read_b128 v[230:233], v159 offset:23552
	global_load_lds_dwordx4 v[250:251], off
	v_lshl_add_u64 v[252:253], s[14:15], 0, v[130:131]
	s_mov_b32 m0, s38
	s_nop 0
	global_load_lds_dwordx4 v[252:253], off
	s_waitcnt vmcnt(10)
	s_barrier
	s_waitcnt lgkmcnt(0)
	v_mfma_f32_16x16x32_f16 v[62:65], v[152:155], v[202:205], v[62:65]
	v_mfma_f32_16x16x32_f16 v[58:61], v[182:185], v[202:205], v[58:61]
	v_mfma_f32_16x16x32_f16 v[46:49], v[152:155], v[210:213], v[46:49]
	v_mfma_f32_16x16x32_f16 v[42:45], v[182:185], v[210:213], v[42:45]
	v_mfma_f32_16x16x32_f16 v[30:33], v[152:155], v[218:221], v[30:33]
	v_mfma_f32_16x16x32_f16 v[26:29], v[182:185], v[218:221], v[26:29]
	v_mfma_f32_16x16x32_f16 v[14:17], v[152:155], v[226:229], v[14:17]
	v_mfma_f32_16x16x32_f16 v[10:13], v[182:185], v[226:229], v[10:13]
	v_mfma_f32_16x16x32_f16 v[62:65], v[178:181], v[206:209], v[62:65]
	v_mfma_f32_16x16x32_f16 v[58:61], v[186:189], v[206:209], v[58:61]
	v_mfma_f32_16x16x32_f16 v[46:49], v[178:181], v[214:217], v[46:49]
	v_mfma_f32_16x16x32_f16 v[42:45], v[186:189], v[214:217], v[42:45]
	v_mfma_f32_16x16x32_f16 v[30:33], v[178:181], v[222:225], v[30:33]
	v_mfma_f32_16x16x32_f16 v[26:29], v[186:189], v[222:225], v[26:29]
	v_mfma_f32_16x16x32_f16 v[14:17], v[178:181], v[230:233], v[14:17]
	v_mfma_f32_16x16x32_f16 v[10:13], v[186:189], v[230:233], v[10:13]
	s_barrier
	s_add_u32 s56, s12, 0x40000
	s_addc_u32 s57, s13, 0
	s_mov_b32 m0, s39
	v_lshl_add_u64 v[152:153], s[56:57], 0, v[132:133]
	global_load_lds_dwordx4 v[152:153], off
	v_lshl_add_u64 v[152:153], s[56:57], 0, v[130:131]
	s_mov_b32 m0, s40
	s_nop 0
	global_load_lds_dwordx4 v[152:153], off
	ds_read_b128 v[152:155], v169
	ds_read_b128 v[178:181], v170
	ds_read_b128 v[182:185], v171
	ds_read_b128 v[186:189], v172
	s_waitcnt vmcnt(6)
	s_barrier
; #define G8_STAGE(bufoff, gbase) do { _Pragma("unroll") for (int _i = 0; _i < 2; ++_i) \
;     __builtin_amdgcn_global_load_lds((const unsigned*)((const char*)(gbase) + voffA[_i]), (LAS unsigned*)(lds + (bufoff) + ldsw + _i * 8192), 16, 0, 0); } while (0)
; #define G8_LDA(dst, b, h) do { _Pragma("unroll") for (int m = 0; m < 4; ++m) _Pragma("unroll") for (int k = 0; k < 2; ++k) dst[m][k] = *(const LAS h16x8*)(lds + G8_SA(b, h) + aoff + m * 2048 + k * 1024); } while (0)
; #define G8_LDB(dst, b, h) do { _Pragma("unroll") for (int n = 0; n < 2; ++n) _Pragma("unroll") for (int k = 0; k < 2; ++k) dst[n][k] = *(const LAS h16x8*)(lds + G8_SB(b, h) + boff + n * 2048 + k * 1024); } while (0)
; #define G8_MMA(ai, bj, At, Bt_) do { __builtin_amdgcn_s_setprio(1); _Pragma("unroll") for (int m = 0; m < 4; ++m) _Pragma("unroll") for (int n = 0; n < 2; ++n) _Pragma("unroll") for (int k = 0; k < 2; ++k) \
;     acc[ai][bj][m][n] = __builtin_amdgcn_mfma_f32_16x16x32_f16(Bt_[n][k], At[m][k], acc[ai][bj][m][n], 0, 0, 0); __builtin_amdgcn_s_setprio(0); } while (0)
; #define G8_WAIT_V(n) asm volatile("s_waitcnt vmcnt(" #n ")" ::: "memory")
; #define G8_WAIT_L(n) asm volatile("s_waitcnt lgkmcnt(" #n ")" ::: "memory")
; #define G8_BAR __builtin_amdgcn_s_barrier()
; #define G8_SCHED __builtin_amdgcn_sched_barrier(0)
; template <class Epi>
; __device__ __forceinline__ void gemm_phase(LAS unsigned char* lds, const h16* A, const h16* Bt, int K, const Order& S, const Epi& E) {
;     ...
;       G8_LDA(At, 0, 1); G8_STAGE(G8_SA(0, 0), a2);
;       G8_BAR; G8_WAIT_L(0); G8_MMA(1, 0, At, B0); G8_BAR; G8_SCHED;
;       G8_STAGE(G8_SB(0, 1), b2 + hstep);
;       G8_WAIT_V(6); G8_BAR; G8_MMA(1, 1, At, B1); G8_BAR;
;       G8_LDB(B0, 1, 0); G8_SCHED; G8_LDA(At, 1, 0); G8_STAGE(G8_SA(0, 1), a2 + hstep);
;       G8_WAIT_L(8); G8_BAR; G8_WAIT_L(0); G8_MMA(0, 0, At, B0); G8_BAR; G8_SCHED;
;       G8_LDB(B1, 1, 1); G8_STAGE(G8_SB(1, 0), b3);
;       G8_BAR; G8_WAIT_L(0); G8_MMA(0, 1, At, B1); G8_BAR;
;       G8_LDA(At, 1, 1); G8_STAGE(G8_SA(1, 0), a3);
;       G8_BAR; G8_WAIT_L(0); G8_MMA(1, 0, At, B0); G8_BAR; G8_SCHED;
;       G8_STAGE(G8_SB(1, 1), b3 + hstep);
;       G8_WAIT_V(6); G8_BAR; G8_MMA(1, 1, At, B1); G8_BAR;
	v_mfma_f32_16x16x32_f16 v[54:57], v[234:237], v[202:205], v[54:57]
	v_mfma_f32_16x16x32_f16 v[50:53], v[242:245], v[202:205], v[50:53]
	v_mfma_f32_16x16x32_f16 v[38:41], v[234:237], v[210:213], v[38:41]
	v_mfma_f32_16x16x32_f16 v[34:37], v[242:245], v[210:213], v[34:37]
	v_mfma_f32_16x16x32_f16 v[22:25], v[234:237], v[218:221], v[22:25]
	v_mfma_f32_16x16x32_f16 v[18:21], v[242:245], v[218:221], v[18:21]
	v_mfma_f32_16x16x32_f16 v[6:9], v[234:237], v[226:229], v[6:9]
	v_mfma_f32_16x16x32_f16 v[2:5], v[242:245], v[226:229], v[2:5]
	v_mfma_f32_16x16x32_f16 v[54:57], v[238:241], v[206:209], v[54:57]
	v_mfma_f32_16x16x32_f16 v[50:53], v[246:249], v[206:209], v[50:53]
	v_mfma_f32_16x16x32_f16 v[38:41], v[238:241], v[214:217], v[38:41]
	v_mfma_f32_16x16x32_f16 v[34:37], v[246:249], v[214:217], v[34:37]
	v_mfma_f32_16x16x32_f16 v[22:25], v[238:241], v[222:225], v[22:25]
	v_mfma_f32_16x16x32_f16 v[18:21], v[246:249], v[222:225], v[18:21]
	v_mfma_f32_16x16x32_f16 v[6:9], v[238:241], v[230:233], v[6:9]
	v_mfma_f32_16x16x32_f16 v[2:5], v[246:249], v[230:233], v[2:5]
	s_barrier
	s_add_u32 s14, s14, 0x40000
	s_addc_u32 s15, s15, 0
	s_mov_b32 m0, s41
	v_lshl_add_u64 v[234:235], s[14:15], 0, v[132:133]
	ds_read_b128 v[202:205], v159 offset:32768
	ds_read_b128 v[206:209], v159 offset:33792
	ds_read_b128 v[210:213], v159 offset:34816
	ds_read_b128 v[214:217], v159 offset:35840
	ds_read_b128 v[218:221], v159 offset:36864
	ds_read_b128 v[222:225], v159 offset:37888
	ds_read_b128 v[226:229], v159 offset:38912
	ds_read_b128 v[230:233], v159 offset:39936
	global_load_lds_dwordx4 v[234:235], off
	v_lshl_add_u64 v[234:235], s[14:15], 0, v[130:131]
	s_mov_b32 m0, s42
	s_nop 0
	global_load_lds_dwordx4 v[234:235], off
	s_waitcnt lgkmcnt(8)
	s_barrier
	s_waitcnt lgkmcnt(0)
	v_mfma_f32_16x16x32_f16 v[126:129], v[152:155], v[202:205], v[126:129]
	v_mfma_f32_16x16x32_f16 v[122:125], v[182:185], v[202:205], v[122:125]
	v_mfma_f32_16x16x32_f16 v[110:113], v[152:155], v[210:213], v[110:113]
	v_mfma_f32_16x16x32_f16 v[106:109], v[182:185], v[210:213], v[106:109]
	v_mfma_f32_16x16x32_f16 v[94:97], v[152:155], v[218:221], v[94:97]
	v_mfma_f32_16x16x32_f16 v[90:93], v[182:185], v[218:221], v[90:93]
	v_mfma_f32_16x16x32_f16 v[78:81], v[152:155], v[226:229], v[78:81]
	v_mfma_f32_16x16x32_f16 v[74:77], v[182:185], v[226:229], v[74:77]
	v_mfma_f32_16x16x32_f16 v[126:129], v[178:181], v[206:209], v[126:129]
	v_mfma_f32_16x16x32_f16 v[122:125], v[186:189], v[206:209], v[122:125]
	v_mfma_f32_16x16x32_f16 v[110:113], v[178:181], v[214:217], v[110:113]
	v_mfma_f32_16x16x32_f16 v[106:109], v[186:189], v[214:217], v[106:109]
	v_mfma_f32_16x16x32_f16 v[94:97], v[178:181], v[222:225], v[94:97]
	v_mfma_f32_16x16x32_f16 v[90:93], v[186:189], v[222:225], v[90:93]
	v_mfma_f32_16x16x32_f16 v[78:81], v[178:181], v[230:233], v[78:81]
	v_mfma_f32_16x16x32_f16 v[74:77], v[186:189], v[230:233], v[74:77]
	s_barrier
	s_mov_b32 m0, s44
	v_lshl_add_u64 v[140:141], v[140:141], 0, s[94:95]
	ds_read_b128 v[234:237], v173
	ds_read_b128 v[238:241], v174
	ds_read_b128 v[242:245], v175
	ds_read_b128 v[246:249], v176
	global_load_lds_dwordx4 v[140:141], off
	v_lshl_add_u64 v[140:141], v[156:157], 0, s[94:95]
	s_mov_b32 m0, s45
	s_nop 0
	global_load_lds_dwordx4 v[140:141], off
	s_barrier
	s_waitcnt lgkmcnt(0)
	v_mfma_f32_16x16x32_f16 v[118:121], v[234:237], v[202:205], v[118:121]
	v_mfma_f32_16x16x32_f16 v[114:117], v[242:245], v[202:205], v[114:117]
	v_mfma_f32_16x16x32_f16 v[102:105], v[234:237], v[210:213], v[102:105]
	v_mfma_f32_16x16x32_f16 v[98:101], v[242:245], v[210:213], v[98:101]
	v_mfma_f32_16x16x32_f16 v[86:89], v[234:237], v[218:221], v[86:89]
	v_mfma_f32_16x16x32_f16 v[82:85], v[242:245], v[218:221], v[82:85]
	v_mfma_f32_16x16x32_f16 v[70:73], v[234:237], v[226:229], v[70:73]
	v_mfma_f32_16x16x32_f16 v[66:69], v[242:245], v[226:229], v[66:69]
	v_mfma_f32_16x16x32_f16 v[118:121], v[238:241], v[206:209], v[118:121]
	v_mfma_f32_16x16x32_f16 v[114:117], v[246:249], v[206:209], v[114:117]
	v_mfma_f32_16x16x32_f16 v[102:105], v[238:241], v[214:217], v[102:105]
	v_mfma_f32_16x16x32_f16 v[98:101], v[246:249], v[214:217], v[98:101]
	v_mfma_f32_16x16x32_f16 v[86:89], v[238:241], v[222:225], v[86:89]
	v_mfma_f32_16x16x32_f16 v[82:85], v[246:249], v[222:225], v[82:85]
	v_mfma_f32_16x16x32_f16 v[70:73], v[238:241], v[230:233], v[70:73]
	v_mfma_f32_16x16x32_f16 v[66:69], v[246:249], v[230:233], v[66:69]
	s_mov_b32 m0, s46
	v_lshl_add_u64 v[140:141], v[250:251], 0, s[94:95]
	s_barrier
; #define G8_STAGE(bufoff, gbase) do { _Pragma("unroll") for (int _i = 0; _i < 2; ++_i) \
;     __builtin_amdgcn_global_load_lds((const unsigned*)((const char*)(gbase) + voffA[_i]), (LAS unsigned*)(lds + (bufoff) + ldsw + _i * 8192), 16, 0, 0); } while (0)
; #define G8_LDA(dst, b, h) do { _Pragma("unroll") for (int m = 0; m < 4; ++m) _Pragma("unroll") for (int k = 0; k < 2; ++k) dst[m][k] = *(const LAS h16x8*)(lds + G8_SA(b, h) + aoff + m * 2048 + k * 1024); } while (0)
; #define G8_LDB(dst, b, h) do { _Pragma("unroll") for (int n = 0; n < 2; ++n) _Pragma("unroll") for (int k = 0; k < 2; ++k) dst[n][k] = *(const LAS h16x8*)(lds + G8_SB(b, h) + boff + n * 2048 + k * 1024); } while (0)
; #define G8_MMA(ai, bj, At, Bt_) do { __builtin_amdgcn_s_setprio(1); _Pragma("unroll") for (int m = 0; m < 4; ++m) _Pragma("unroll") for (int n = 0; n < 2; ++n) _Pragma("unroll") for (int k = 0; k < 2; ++k) \
;     acc[ai][bj][m][n] = __builtin_amdgcn_mfma_f32_16x16x32_f16(Bt_[n][k], At[m][k], acc[ai][bj][m][n], 0, 0, 0); __builtin_amdgcn_s_setprio(0); } while (0)
; #define G8_WAIT_V(n) asm volatile("s_waitcnt vmcnt(" #n ")" ::: "memory")
; #define G8_WAIT_L(n) asm volatile("s_waitcnt lgkmcnt(" #n ")" ::: "memory")
; #define G8_BAR __builtin_amdgcn_s_barrier()
; #define G8_SCHED __builtin_amdgcn_sched_barrier(0)
; template <class Epi>
; __device__ __forceinline__ void gemm_phase(LAS unsigned char* lds, const h16* A, const h16* Bt, int K, const Order& S, const Epi& E) {
;     ...
;       G8_LDB(B0, 1, 0); G8_SCHED; G8_LDA(At, 1, 0); G8_STAGE(G8_SA(0, 1), a2 + hstep);
;       G8_WAIT_L(8); G8_BAR; G8_WAIT_L(0); G8_MMA(0, 0, At, B0); G8_BAR; G8_SCHED;
;       G8_LDB(B1, 1, 1); G8_STAGE(G8_SB(1, 0), b3);
;       G8_BAR; G8_WAIT_L(0); G8_MMA(0, 1, At, B1); G8_BAR;
;       G8_LDA(At, 1, 1); G8_STAGE(G8_SA(1, 0), a3);
;       G8_BAR; G8_WAIT_L(0); G8_MMA(1, 0, At, B0); G8_BAR; G8_SCHED;
;       G8_STAGE(G8_SB(1, 1), b3 + hstep);
;       G8_WAIT_V(6); G8_BAR; G8_MMA(1, 1, At, B1); G8_BAR;
;     }
;   __device__ __forceinline__ void operator()(const f32x4 (&acc)[2][2][4][2], const g8::Unit& u, int ui, int wr, int wc, int fr, int fq) const {
;     const int hs = u.pn * 4 + wc;
;     int gi = -1;
;     if (hs < 4) gi = 0; else if (hs < 6) gi = 1; else if (hs >= 16 && hs < 20) gi = 2; else if (hs == 22) gi = 4; else if (hs == 24) gi = 5;
	ds_read_b128 v[202:205], v159 offset:49152
	ds_read_b128 v[206:209], v159 offset:50176
	ds_read_b128 v[210:213], v159 offset:51200
	ds_read_b128 v[214:217], v159 offset:52224
	ds_read_b128 v[218:221], v159 offset:53248
	ds_read_b128 v[222:225], v159 offset:54272
	ds_read_b128 v[226:229], v159 offset:55296
	ds_read_b128 v[230:233], v159 offset:56320
	global_load_lds_dwordx4 v[140:141], off
	v_lshl_add_u64 v[140:141], v[252:253], 0, s[94:95]
	s_mov_b32 m0, s47
	s_nop 0
	global_load_lds_dwordx4 v[140:141], off
	s_waitcnt vmcnt(10)
	s_barrier
	s_waitcnt lgkmcnt(0)
	v_mfma_f32_16x16x32_f16 v[62:65], v[152:155], v[202:205], v[62:65]
	v_mfma_f32_16x16x32_f16 v[58:61], v[182:185], v[202:205], v[58:61]
	v_mfma_f32_16x16x32_f16 v[46:49], v[152:155], v[210:213], v[46:49]
	v_mfma_f32_16x16x32_f16 v[42:45], v[182:185], v[210:213], v[42:45]
	v_mfma_f32_16x16x32_f16 v[30:33], v[152:155], v[218:221], v[30:33]
	v_mfma_f32_16x16x32_f16 v[26:29], v[182:185], v[218:221], v[26:29]
	v_mfma_f32_16x16x32_f16 v[14:17], v[152:155], v[226:229], v[14:17]
	v_mfma_f32_16x16x32_f16 v[10:13], v[182:185], v[226:229], v[10:13]
	v_mfma_f32_16x16x32_f16 v[62:65], v[178:181], v[206:209], v[62:65]
	v_mfma_f32_16x16x32_f16 v[58:61], v[186:189], v[206:209], v[58:61]
	v_mfma_f32_16x16x32_f16 v[46:49], v[178:181], v[214:217], v[46:49]
	v_mfma_f32_16x16x32_f16 v[42:45], v[186:189], v[214:217], v[42:45]
	v_mfma_f32_16x16x32_f16 v[30:33], v[178:181], v[222:225], v[30:33]
	v_mfma_f32_16x16x32_f16 v[26:29], v[186:189], v[222:225], v[26:29]
	v_mfma_f32_16x16x32_f16 v[14:17], v[178:181], v[230:233], v[14:17]
	v_mfma_f32_16x16x32_f16 v[10:13], v[186:189], v[230:233], v[10:13]
	s_barrier
	s_add_u32 s12, s12, 0x40080
	s_addc_u32 s13, s13, 0
	s_mov_b32 m0, s48
	v_lshl_add_u64 v[140:141], s[12:13], 0, v[132:133]
	global_load_lds_dwordx4 v[140:141], off
	v_lshl_add_u64 v[140:141], s[12:13], 0, v[130:131]
	s_mov_b32 m0, s49
	s_nop 0
	global_load_lds_dwordx4 v[140:141], off
	ds_read_b128 v[152:155], v161
	ds_read_b128 v[178:181], v162
	ds_read_b128 v[182:185], v163
	ds_read_b128 v[186:189], v164
	s_waitcnt vmcnt(6)
	s_barrier
	v_mfma_f32_16x16x32_f16 v[54:57], v[234:237], v[202:205], v[54:57]
	v_mfma_f32_16x16x32_f16 v[50:53], v[242:245], v[202:205], v[50:53]
	v_mfma_f32_16x16x32_f16 v[38:41], v[234:237], v[210:213], v[38:41]
	v_mfma_f32_16x16x32_f16 v[34:37], v[242:245], v[210:213], v[34:37]
	v_mfma_f32_16x16x32_f16 v[22:25], v[234:237], v[218:221], v[22:25]
	v_mfma_f32_16x16x32_f16 v[18:21], v[242:245], v[218:221], v[18:21]
	v_mfma_f32_16x16x32_f16 v[6:9], v[234:237], v[226:229], v[6:9]
	v_mfma_f32_16x16x32_f16 v[2:5], v[242:245], v[226:229], v[2:5]
	v_mfma_f32_16x16x32_f16 v[54:57], v[238:241], v[206:209], v[54:57]
	v_mfma_f32_16x16x32_f16 v[50:53], v[246:249], v[206:209], v[50:53]
	v_mfma_f32_16x16x32_f16 v[38:41], v[238:241], v[214:217], v[38:41]
	v_mfma_f32_16x16x32_f16 v[34:37], v[246:249], v[214:217], v[34:37]
	v_mfma_f32_16x16x32_f16 v[22:25], v[238:241], v[222:225], v[22:25]
	v_mfma_f32_16x16x32_f16 v[18:21], v[246:249], v[222:225], v[18:21]
	v_mfma_f32_16x16x32_f16 v[6:9], v[238:241], v[230:233], v[6:9]
	v_mfma_f32_16x16x32_f16 v[2:5], v[246:249], v[230:233], v[2:5]
	s_add_i32 s54, s54, 2
	s_add_u32 s10, s10, 0x100
	s_addc_u32 s11, s11, 0
	s_add_u32 s27, s27, 0x100
	s_addc_u32 s53, s53, 0
	s_cmp_gt_u32 s54, 13
	s_barrier
	s_cbranch_scc0 .LBB0_195
	s_waitcnt lgkmcnt(0)
	s_lshl_b32 s10, s24, 2
	s_or_b32 s19, s10, s43
	s_cmp_lt_i32 s19, 4
	s_cbranch_scc1 .LBB0_203
	s_cmp_lt_u32 s19, 6
	s_cbranch_scc1 .LBB0_204
	s_cmp_eq_u32 s24, 4
	s_cbranch_scc1 .LBB0_205
	s_cmp_lt_i32 s19, 24
	s_cbranch_scc1 .LBB0_206
	s_cmp_eq_u32 s19, 24
	s_mov_b64 s[10:11], -1
	s_cbranch_scc0 .LBB0_202
	s_mov_b64 s[10:11], 0

; #define G8_STAGE(bufoff, gbase) do { _Pragma("unroll") for (int _i = 0; _i < 2; ++_i) \
;     __builtin_amdgcn_global_load_lds((const unsigned*)((const char*)(gbase) + voffA[_i]), (LAS unsigned*)(lds + (bufoff) + ldsw + _i * 8192), 16, 0, 0); } while (0)
; #define G8_LDA(dst, b, h) do { _Pragma("unroll") for (int m = 0; m < 4; ++m) _Pragma("unroll") for (int k = 0; k < 2; ++k) dst[m][k] = *(const LAS h16x8*)(lds + G8_SA(b, h) + aoff + m * 2048 + k * 1024); } while (0)
; #define G8_LDB(dst, b, h) do { _Pragma("unroll") for (int n = 0; n < 2; ++n) _Pragma("unroll") for (int k = 0; k < 2; ++k) dst[n][k] = *(const LAS h16x8*)(lds + G8_SB(b, h) + boff + n * 2048 + k * 1024); } while (0)
; #define G8_MMA(ai, bj, At, Bt_) do { __builtin_amdgcn_s_setprio(1); _Pragma("unroll") for (int m = 0; m < 4; ++m) _Pragma("unroll") for (int n = 0; n < 2; ++n) _Pragma("unroll") for (int k = 0; k < 2; ++k) \
;     acc[ai][bj][m][n] = __builtin_amdgcn_mfma_f32_16x16x32_f16(Bt_[n][k], At[m][k], acc[ai][bj][m][n], 0, 0, 0); __builtin_amdgcn_s_setprio(0); } while (0)
; #define G8_WAIT_V(n) asm volatile("s_waitcnt vmcnt(" #n ")" ::: "memory")
; #define G8_WAIT_L(n) asm volatile("s_waitcnt lgkmcnt(" #n ")" ::: "memory")
; #define G8_BAR __builtin_amdgcn_s_barrier()
; template <class Epi>
; __device__ __forceinline__ void gemm_phase(LAS unsigned char* lds, const h16* A, const h16* Bt, int K, const Order& S, const Epi& E) {
;     ...
;     for (int t = 0; t < nt; t += 2) {
;       const bool last = (t == nt - 2);
;       const char* a1 = cA + (size_t)(t + 1) * kstep;
;       const char* a2 = last ? nA : cA + (size_t)(t + 2) * kstep;
;       const char* b2 = last ? nB : cB + (size_t)(t + 2) * kstep;
;       const char* a3 = a2 + kstep;
;       const char* b3 = b2 + kstep;
;       if (Epi::MID_T >= 0 && t == Epi::MID_T) E.mid(acc, ui, wr, fr);
;       G8_LDB(B0, 0, 0); G8_SCHED; G8_LDA(At, 0, 0); G8_STAGE(G8_SA(1, 1), a1 + hstep);
;       G8_WAIT_L(8); G8_BAR; G8_WAIT_L(0); G8_MMA(0, 0, At, B0); G8_BAR; G8_SCHED;
;       G8_LDB(B1, 0, 1); G8_STAGE(G8_SB(0, 0), b2);
;       G8_BAR; G8_WAIT_L(0); G8_MMA(0, 1, At, B1); G8_BAR;
;       G8_LDA(At, 0, 1); G8_STAGE(G8_SA(0, 0), a2);
;       G8_BAR; G8_WAIT_L(0); G8_MMA(1, 0, At, B0); G8_BAR; G8_SCHED;
;       G8_STAGE(G8_SB(0, 1), b2 + hstep);
;       G8_WAIT_V(6); G8_BAR; G8_MMA(1, 1, At, B1); G8_BAR;
.LBB0_2284:
	v_or_b32_e32 v34, 0x10000, v171
	v_add_u32_e32 v46, 0x10400, v171
	v_add_u32_e32 v50, 0x10800, v171
	v_add_u32_e32 v160, 0x10c00, v171
	ds_read_b128 v[34:37], v34
	ds_read_b128 v[46:49], v46
	ds_read_b128 v[50:53], v50
	ds_read_b128 v[160:163], v160
	s_add_u32 s26, s24, 0xfffe0080
	s_addc_u32 s27, s25, -1
	s_cmp_eq_u32 s55, 4
	s_cselect_b32 s29, s3, s27
	s_cselect_b32 s28, s17, s26
	s_cselect_b32 s27, s15, s54
	s_cselect_b32 s26, s23, s53
	v_lshl_add_u64 v[168:169], s[24:25], 0, v[156:157]
	s_add_i32 m0, s37, 0xc000
	ds_read_b128 v[164:167], v170
	ds_read_b128 v[174:177], v170 offset:1024
	ds_read_b128 v[178:181], v170 offset:2048
	ds_read_b128 v[182:185], v170 offset:3072
	ds_read_b128 v[186:189], v170 offset:4096
	ds_read_b128 v[202:205], v170 offset:5120
	ds_read_b128 v[206:209], v170 offset:6144
	ds_read_b128 v[210:213], v170 offset:7168
	global_load_lds_dwordx4 v[168:169], off
	v_lshl_add_u64 v[168:169], s[24:25], 0, v[158:159]
	s_add_i32 m0, s37, 0xe000
	s_nop 0
	global_load_lds_dwordx4 v[168:169], off
	s_waitcnt lgkmcnt(8)
	s_barrier
	s_waitcnt lgkmcnt(0)
	v_mfma_f32_16x16x32_f16 v[62:65], v[34:37], v[164:167], v[62:65]
	v_mfma_f32_16x16x32_f16 v[138:141], v[50:53], v[164:167], v[138:141]
	v_mfma_f32_16x16x32_f16 v[122:125], v[34:37], v[178:181], v[122:125]
	v_mfma_f32_16x16x32_f16 v[126:129], v[50:53], v[178:181], v[126:129]
	v_mfma_f32_16x16x32_f16 v[106:109], v[34:37], v[186:189], v[106:109]
	v_mfma_f32_16x16x32_f16 v[110:113], v[50:53], v[186:189], v[110:113]
	v_mfma_f32_16x16x32_f16 v[90:93], v[34:37], v[206:209], v[90:93]
	v_mfma_f32_16x16x32_f16 v[94:97], v[50:53], v[206:209], v[94:97]
	v_mfma_f32_16x16x32_f16 v[62:65], v[46:49], v[174:177], v[62:65]
	v_mfma_f32_16x16x32_f16 v[138:141], v[160:163], v[174:177], v[138:141]
	v_mfma_f32_16x16x32_f16 v[122:125], v[46:49], v[182:185], v[122:125]
	v_mfma_f32_16x16x32_f16 v[126:129], v[160:163], v[182:185], v[126:129]
	v_mfma_f32_16x16x32_f16 v[106:109], v[46:49], v[202:205], v[106:109]
	v_mfma_f32_16x16x32_f16 v[110:113], v[160:163], v[202:205], v[110:113]
	v_mfma_f32_16x16x32_f16 v[90:93], v[46:49], v[210:213], v[90:93]
	v_mfma_f32_16x16x32_f16 v[94:97], v[160:163], v[210:213], v[94:97]
	s_barrier
	v_or_b32_e32 v168, 0x14000, v171
	v_add_u32_e32 v169, 0x14400, v171
	ds_read_b128 v[214:217], v168
	ds_read_b128 v[218:221], v169
	v_add_u32_e32 v168, 0x14800, v171
	v_add_u32_e32 v169, 0x14c00, v171
	s_mov_b32 m0, s38
	ds_read_b128 v[222:225], v168
	ds_read_b128 v[226:229], v169
	v_lshl_add_u64 v[168:169], s[26:27], 0, v[0:1]
	global_load_lds_dwordx4 v[168:169], off
	v_lshl_add_u64 v[230:231], s[26:27], 0, v[152:153]
	s_mov_b32 m0, s39
	s_nop 0
	global_load_lds_dwordx4 v[230:231], off
	s_barrier
	s_waitcnt lgkmcnt(0)
	v_mfma_f32_16x16x32_f16 v[130:133], v[214:217], v[164:167], v[130:133]
	v_mfma_f32_16x16x32_f16 v[134:137], v[222:225], v[164:167], v[134:137]
	v_mfma_f32_16x16x32_f16 v[114:117], v[214:217], v[178:181], v[114:117]
	v_mfma_f32_16x16x32_f16 v[118:121], v[222:225], v[178:181], v[118:121]
	v_mfma_f32_16x16x32_f16 v[98:101], v[214:217], v[186:189], v[98:101]
	v_mfma_f32_16x16x32_f16 v[102:105], v[222:225], v[186:189], v[102:105]
	v_mfma_f32_16x16x32_f16 v[82:85], v[214:217], v[206:209], v[82:85]
	v_mfma_f32_16x16x32_f16 v[86:89], v[222:225], v[206:209], v[86:89]
	v_mfma_f32_16x16x32_f16 v[130:133], v[218:221], v[174:177], v[130:133]
	v_mfma_f32_16x16x32_f16 v[134:137], v[226:229], v[174:177], v[134:137]
	v_mfma_f32_16x16x32_f16 v[114:117], v[218:221], v[182:185], v[114:117]
	v_mfma_f32_16x16x32_f16 v[118:121], v[226:229], v[182:185], v[118:121]
	v_mfma_f32_16x16x32_f16 v[98:101], v[218:221], v[202:205], v[98:101]
	v_mfma_f32_16x16x32_f16 v[102:105], v[226:229], v[202:205], v[102:105]
	v_mfma_f32_16x16x32_f16 v[82:85], v[218:221], v[210:213], v[82:85]
	v_mfma_f32_16x16x32_f16 v[86:89], v[226:229], v[210:213], v[86:89]
	s_mov_b32 m0, s37
	v_lshl_add_u64 v[232:233], s[28:29], 0, v[0:1]
	s_barrier
	ds_read_b128 v[164:167], v170 offset:16384
	ds_read_b128 v[174:177], v170 offset:17408
	ds_read_b128 v[178:181], v170 offset:18432
	ds_read_b128 v[182:185], v170 offset:19456
	ds_read_b128 v[186:189], v170 offset:20480
	ds_read_b128 v[202:205], v170 offset:21504
	ds_read_b128 v[206:209], v170 offset:22528
	ds_read_b128 v[210:213], v170 offset:23552
	global_load_lds_dwordx4 v[232:233], off
	v_lshl_add_u64 v[234:235], s[28:29], 0, v[152:153]
	s_mov_b32 m0, s40
	s_nop 0
	global_load_lds_dwordx4 v[234:235], off
	s_barrier
	s_waitcnt lgkmcnt(0)
	v_mfma_f32_16x16x32_f16 v[74:77], v[34:37], v[164:167], v[74:77]
	v_mfma_f32_16x16x32_f16 v[78:81], v[50:53], v[164:167], v[78:81]
	v_mfma_f32_16x16x32_f16 v[54:57], v[34:37], v[178:181], v[54:57]
	v_mfma_f32_16x16x32_f16 v[58:61], v[50:53], v[178:181], v[58:61]
	v_mfma_f32_16x16x32_f16 v[26:29], v[34:37], v[186:189], v[26:29]
	v_mfma_f32_16x16x32_f16 v[30:33], v[50:53], v[186:189], v[30:33]
	v_mfma_f32_16x16x32_f16 v[10:13], v[34:37], v[206:209], v[10:13]
	v_mfma_f32_16x16x32_f16 v[14:17], v[50:53], v[206:209], v[14:17]
	v_mfma_f32_16x16x32_f16 v[74:77], v[46:49], v[174:177], v[74:77]
	v_mfma_f32_16x16x32_f16 v[78:81], v[160:163], v[174:177], v[78:81]
	v_mfma_f32_16x16x32_f16 v[54:57], v[46:49], v[182:185], v[54:57]
	v_mfma_f32_16x16x32_f16 v[58:61], v[160:163], v[182:185], v[58:61]
	v_mfma_f32_16x16x32_f16 v[26:29], v[46:49], v[202:205], v[26:29]
	v_mfma_f32_16x16x32_f16 v[30:33], v[160:163], v[202:205], v[30:33]
	v_mfma_f32_16x16x32_f16 v[10:13], v[46:49], v[210:213], v[10:13]
	v_mfma_f32_16x16x32_f16 v[14:17], v[160:163], v[210:213], v[14:17]
	s_barrier
; #define G8_STAGE(bufoff, gbase) do { _Pragma("unroll") for (int _i = 0; _i < 2; ++_i) \
;     __builtin_amdgcn_global_load_lds((const unsigned*)((const char*)(gbase) + voffA[_i]), (LAS unsigned*)(lds + (bufoff) + ldsw + _i * 8192), 16, 0, 0); } while (0)
; #define G8_LDA(dst, b, h) do { _Pragma("unroll") for (int m = 0; m < 4; ++m) _Pragma("unroll") for (int k = 0; k < 2; ++k) dst[m][k] = *(const LAS h16x8*)(lds + G8_SA(b, h) + aoff + m * 2048 + k * 1024); } while (0)
; #define G8_LDB(dst, b, h) do { _Pragma("unroll") for (int n = 0; n < 2; ++n) _Pragma("unroll") for (int k = 0; k < 2; ++k) dst[n][k] = *(const LAS h16x8*)(lds + G8_SB(b, h) + boff + n * 2048 + k * 1024); } while (0)
; #define G8_MMA(ai, bj, At, Bt_) do { __builtin_amdgcn_s_setprio(1); _Pragma("unroll") for (int m = 0; m < 4; ++m) _Pragma("unroll") for (int n = 0; n < 2; ++n) _Pragma("unroll") for (int k = 0; k < 2; ++k) \
;     acc[ai][bj][m][n] = __builtin_amdgcn_mfma_f32_16x16x32_f16(Bt_[n][k], At[m][k], acc[ai][bj][m][n], 0, 0, 0); __builtin_amdgcn_s_setprio(0); } while (0)
; #define G8_WAIT_V(n) asm volatile("s_waitcnt vmcnt(" #n ")" ::: "memory")
; #define G8_WAIT_L(n) asm volatile("s_waitcnt lgkmcnt(" #n ")" ::: "memory")
; #define G8_BAR __builtin_amdgcn_s_barrier()
; #define G8_SCHED __builtin_amdgcn_sched_barrier(0)
; template <class Epi>
; __device__ __forceinline__ void gemm_phase(LAS unsigned char* lds, const h16* A, const h16* Bt, int K, const Order& S, const Epi& E) {
;     ...
;       G8_LDA(At, 0, 1); G8_STAGE(G8_SA(0, 0), a2);
;       G8_BAR; G8_WAIT_L(0); G8_MMA(1, 0, At, B0); G8_BAR; G8_SCHED;
;       G8_STAGE(G8_SB(0, 1), b2 + hstep);
;       G8_WAIT_V(6); G8_BAR; G8_MMA(1, 1, At, B1); G8_BAR;
;       G8_LDB(B0, 1, 0); G8_SCHED; G8_LDA(At, 1, 0); G8_STAGE(G8_SA(0, 1), a2 + hstep);
;       G8_WAIT_L(8); G8_BAR; G8_WAIT_L(0); G8_MMA(0, 0, At, B0); G8_BAR; G8_SCHED;
;       G8_LDB(B1, 1, 1); G8_STAGE(G8_SB(1, 0), b3);
;       G8_BAR; G8_WAIT_L(0); G8_MMA(0, 1, At, B1); G8_BAR;
;       G8_LDA(At, 1, 1); G8_STAGE(G8_SA(1, 0), a3);
;       G8_BAR; G8_WAIT_L(0); G8_MMA(1, 0, At, B0); G8_BAR; G8_SCHED;
;       G8_STAGE(G8_SB(1, 1), b3 + hstep);
;       G8_WAIT_V(6); G8_BAR; G8_MMA(1, 1, At, B1); G8_BAR;
	s_add_u32 s56, s26, 0x20000
	s_addc_u32 s57, s27, 0
	s_mov_b32 m0, s41
	v_lshl_add_u64 v[34:35], s[56:57], 0, v[0:1]
	global_load_lds_dwordx4 v[34:35], off
	v_lshl_add_u64 v[34:35], s[56:57], 0, v[152:153]
	s_mov_b32 m0, s42
	s_nop 0
	global_load_lds_dwordx4 v[34:35], off
	s_waitcnt vmcnt(6)
	s_barrier
	v_mfma_f32_16x16x32_f16 v[38:41], v[214:217], v[178:181], v[38:41]
	v_mfma_f32_16x16x32_f16 v[42:45], v[222:225], v[178:181], v[42:45]
	v_mfma_f32_16x16x32_f16 v[18:21], v[214:217], v[186:189], v[18:21]
	v_mfma_f32_16x16x32_f16 v[22:25], v[222:225], v[186:189], v[22:25]
	v_mfma_f32_16x16x32_f16 v[2:5], v[214:217], v[206:209], v[2:5]
	v_mfma_f32_16x16x32_f16 v[6:9], v[222:225], v[206:209], v[6:9]
	v_mfma_f32_16x16x32_f16 v[34:37], v[214:217], v[164:167], v[66:69]
	v_mfma_f32_16x16x32_f16 v[46:49], v[222:225], v[164:167], v[70:73]
	v_mfma_f32_16x16x32_f16 v[38:41], v[218:221], v[182:185], v[38:41]
	v_mfma_f32_16x16x32_f16 v[42:45], v[226:229], v[182:185], v[42:45]
	v_mfma_f32_16x16x32_f16 v[18:21], v[218:221], v[202:205], v[18:21]
	v_mfma_f32_16x16x32_f16 v[22:25], v[226:229], v[202:205], v[22:25]
	v_mfma_f32_16x16x32_f16 v[2:5], v[218:221], v[210:213], v[2:5]
	v_mfma_f32_16x16x32_f16 v[6:9], v[226:229], v[210:213], v[6:9]
	v_mfma_f32_16x16x32_f16 v[34:37], v[218:221], v[174:177], v[34:37]
	v_mfma_f32_16x16x32_f16 v[46:49], v[226:229], v[174:177], v[46:49]
	v_or_b32_e32 v50, 0x18000, v171
	v_add_u32_e32 v66, 0x18400, v171
	v_add_u32_e32 v70, 0x18800, v171
	v_add_u32_e32 v160, 0x18c00, v171
	s_barrier
	ds_read_b128 v[50:53], v50
	ds_read_b128 v[66:69], v66
	ds_read_b128 v[70:73], v70
	ds_read_b128 v[160:163], v160
	s_add_u32 s28, s28, 0x20000
	s_addc_u32 s29, s29, 0
	s_mov_b32 m0, s43
	v_lshl_add_u64 v[214:215], s[28:29], 0, v[0:1]
	ds_read_b128 v[164:167], v170 offset:32768
	ds_read_b128 v[174:177], v170 offset:33792
	ds_read_b128 v[178:181], v170 offset:34816
	ds_read_b128 v[182:185], v170 offset:35840
	ds_read_b128 v[186:189], v170 offset:36864
	ds_read_b128 v[202:205], v170 offset:37888
	ds_read_b128 v[206:209], v170 offset:38912
	ds_read_b128 v[210:213], v170 offset:39936
	global_load_lds_dwordx4 v[214:215], off
	v_lshl_add_u64 v[214:215], s[28:29], 0, v[152:153]
	s_mov_b32 m0, s44
	s_nop 0
	global_load_lds_dwordx4 v[214:215], off
	s_waitcnt lgkmcnt(8)
	s_barrier
	s_waitcnt lgkmcnt(0)
	v_mfma_f32_16x16x32_f16 v[62:65], v[50:53], v[164:167], v[62:65]
	v_mfma_f32_16x16x32_f16 v[138:141], v[70:73], v[164:167], v[138:141]
	v_mfma_f32_16x16x32_f16 v[122:125], v[50:53], v[178:181], v[122:125]
	v_mfma_f32_16x16x32_f16 v[126:129], v[70:73], v[178:181], v[126:129]
	v_mfma_f32_16x16x32_f16 v[106:109], v[50:53], v[186:189], v[106:109]
	v_mfma_f32_16x16x32_f16 v[110:113], v[70:73], v[186:189], v[110:113]
	v_mfma_f32_16x16x32_f16 v[90:93], v[50:53], v[206:209], v[90:93]
	v_mfma_f32_16x16x32_f16 v[94:97], v[70:73], v[206:209], v[94:97]
	v_mfma_f32_16x16x32_f16 v[62:65], v[66:69], v[174:177], v[62:65]
	v_mfma_f32_16x16x32_f16 v[138:141], v[160:163], v[174:177], v[138:141]
	v_mfma_f32_16x16x32_f16 v[122:125], v[66:69], v[182:185], v[122:125]
	v_mfma_f32_16x16x32_f16 v[126:129], v[160:163], v[182:185], v[126:129]
	v_mfma_f32_16x16x32_f16 v[106:109], v[66:69], v[202:205], v[106:109]
	v_mfma_f32_16x16x32_f16 v[110:113], v[160:163], v[202:205], v[110:113]
	v_mfma_f32_16x16x32_f16 v[90:93], v[66:69], v[210:213], v[90:93]
	v_mfma_f32_16x16x32_f16 v[94:97], v[160:163], v[210:213], v[94:97]
	s_barrier
	v_or_b32_e32 v173, 0x1c000, v171
	s_mov_b32 m0, s46
	v_add_u32_e32 v195, 0x1c400, v171
	ds_read_b128 v[214:217], v173
	ds_read_b128 v[218:221], v195
	v_add_u32_e32 v173, 0x1c800, v171
	v_lshl_add_u64 v[168:169], v[168:169], 0, s[94:95]
	v_add_u32_e32 v195, 0x1cc00, v171
	ds_read_b128 v[222:225], v173
	ds_read_b128 v[226:229], v195
	global_load_lds_dwordx4 v[168:169], off
	v_lshl_add_u64 v[168:169], v[230:231], 0, s[94:95]
	s_mov_b32 m0, s47
	s_nop 0
	global_load_lds_dwordx4 v[168:169], off
	s_barrier
	s_waitcnt lgkmcnt(0)
	v_mfma_f32_16x16x32_f16 v[130:133], v[214:217], v[164:167], v[130:133]
	v_mfma_f32_16x16x32_f16 v[134:137], v[222:225], v[164:167], v[134:137]
	v_mfma_f32_16x16x32_f16 v[114:117], v[214:217], v[178:181], v[114:117]
	v_mfma_f32_16x16x32_f16 v[118:121], v[222:225], v[178:181], v[118:121]
	v_mfma_f32_16x16x32_f16 v[98:101], v[214:217], v[186:189], v[98:101]
	v_mfma_f32_16x16x32_f16 v[102:105], v[222:225], v[186:189], v[102:105]
	v_mfma_f32_16x16x32_f16 v[82:85], v[214:217], v[206:209], v[82:85]
	v_mfma_f32_16x16x32_f16 v[86:89], v[222:225], v[206:209], v[86:89]
	v_mfma_f32_16x16x32_f16 v[130:133], v[218:221], v[174:177], v[130:133]
	v_mfma_f32_16x16x32_f16 v[134:137], v[226:229], v[174:177], v[134:137]
	v_mfma_f32_16x16x32_f16 v[114:117], v[218:221], v[182:185], v[114:117]
	v_mfma_f32_16x16x32_f16 v[118:121], v[226:229], v[182:185], v[118:121]
	v_mfma_f32_16x16x32_f16 v[98:101], v[218:221], v[202:205], v[98:101]
	v_mfma_f32_16x16x32_f16 v[102:105], v[226:229], v[202:205], v[102:105]
	v_mfma_f32_16x16x32_f16 v[82:85], v[218:221], v[210:213], v[82:85]
	v_mfma_f32_16x16x32_f16 v[86:89], v[226:229], v[210:213], v[86:89]
	s_mov_b32 m0, s48
	v_lshl_add_u64 v[168:169], v[232:233], 0, s[94:95]
	s_barrier
	ds_read_b128 v[164:167], v170 offset:49152
	ds_read_b128 v[174:177], v170 offset:50176
	ds_read_b128 v[178:181], v170 offset:51200
	ds_read_b128 v[182:185], v170 offset:52224
	ds_read_b128 v[186:189], v170 offset:53248
	ds_read_b128 v[202:205], v170 offset:54272
	ds_read_b128 v[206:209], v170 offset:55296
	ds_read_b128 v[210:213], v170 offset:56320
	global_load_lds_dwordx4 v[168:169], off
	v_lshl_add_u64 v[168:169], v[234:235], 0, s[94:95]
	s_mov_b32 m0, s49
	s_nop 0
	global_load_lds_dwordx4 v[168:169], off
	s_barrier
; #define G8_STAGE(bufoff, gbase) do { _Pragma("unroll") for (int _i = 0; _i < 2; ++_i) \
;     __builtin_amdgcn_global_load_lds((const unsigned*)((const char*)(gbase) + voffA[_i]), (LAS unsigned*)(lds + (bufoff) + ldsw + _i * 8192), 16, 0, 0); } while (0)
; #define G8_LDA(dst, b, h) do { _Pragma("unroll") for (int m = 0; m < 4; ++m) _Pragma("unroll") for (int k = 0; k < 2; ++k) dst[m][k] = *(const LAS h16x8*)(lds + G8_SA(b, h) + aoff + m * 2048 + k * 1024); } while (0)
; #define G8_LDB(dst, b, h) do { _Pragma("unroll") for (int n = 0; n < 2; ++n) _Pragma("unroll") for (int k = 0; k < 2; ++k) dst[n][k] = *(const LAS h16x8*)(lds + G8_SB(b, h) + boff + n * 2048 + k * 1024); } while (0)
; #define G8_MMA(ai, bj, At, Bt_) do { __builtin_amdgcn_s_setprio(1); _Pragma("unroll") for (int m = 0; m < 4; ++m) _Pragma("unroll") for (int n = 0; n < 2; ++n) _Pragma("unroll") for (int k = 0; k < 2; ++k) \
;     acc[ai][bj][m][n] = __builtin_amdgcn_mfma_f32_16x16x32_f16(Bt_[n][k], At[m][k], acc[ai][bj][m][n], 0, 0, 0); __builtin_amdgcn_s_setprio(0); } while (0)
; #define G8_WAIT_V(n) asm volatile("s_waitcnt vmcnt(" #n ")" ::: "memory")
; #define G8_WAIT_L(n) asm volatile("s_waitcnt lgkmcnt(" #n ")" ::: "memory")
; #define G8_BAR __builtin_amdgcn_s_barrier()
; #define G8_SCHED __builtin_amdgcn_sched_barrier(0)
; template <class Epi>
; __device__ __forceinline__ void gemm_phase(LAS unsigned char* lds, const h16* A, const h16* Bt, int K, const Order& S, const Epi& E) {
;     ...
;       G8_WAIT_L(8); G8_BAR; G8_WAIT_L(0); G8_MMA(0, 0, At, B0); G8_BAR; G8_SCHED;
;       G8_LDB(B1, 1, 1); G8_STAGE(G8_SB(1, 0), b3);
;       G8_BAR; G8_WAIT_L(0); G8_MMA(0, 1, At, B1); G8_BAR;
;       G8_LDA(At, 1, 1); G8_STAGE(G8_SA(1, 0), a3);
;       G8_BAR; G8_WAIT_L(0); G8_MMA(1, 0, At, B0); G8_BAR; G8_SCHED;
;       G8_STAGE(G8_SB(1, 1), b3 + hstep);
;       G8_WAIT_V(6); G8_BAR; G8_MMA(1, 1, At, B1); G8_BAR;
;     }
	s_waitcnt lgkmcnt(0)
	v_mfma_f32_16x16x32_f16 v[74:77], v[50:53], v[164:167], v[74:77]
	v_mfma_f32_16x16x32_f16 v[78:81], v[70:73], v[164:167], v[78:81]
	v_mfma_f32_16x16x32_f16 v[54:57], v[50:53], v[178:181], v[54:57]
	v_mfma_f32_16x16x32_f16 v[58:61], v[70:73], v[178:181], v[58:61]
	v_mfma_f32_16x16x32_f16 v[26:29], v[50:53], v[186:189], v[26:29]
	v_mfma_f32_16x16x32_f16 v[30:33], v[70:73], v[186:189], v[30:33]
	v_mfma_f32_16x16x32_f16 v[10:13], v[50:53], v[206:209], v[10:13]
	v_mfma_f32_16x16x32_f16 v[14:17], v[70:73], v[206:209], v[14:17]
	v_mfma_f32_16x16x32_f16 v[74:77], v[66:69], v[174:177], v[74:77]
	v_mfma_f32_16x16x32_f16 v[78:81], v[160:163], v[174:177], v[78:81]
	v_mfma_f32_16x16x32_f16 v[54:57], v[66:69], v[182:185], v[54:57]
	v_mfma_f32_16x16x32_f16 v[58:61], v[160:163], v[182:185], v[58:61]
	v_mfma_f32_16x16x32_f16 v[26:29], v[66:69], v[202:205], v[26:29]
	v_mfma_f32_16x16x32_f16 v[30:33], v[160:163], v[202:205], v[30:33]
	v_mfma_f32_16x16x32_f16 v[10:13], v[66:69], v[210:213], v[10:13]
	v_mfma_f32_16x16x32_f16 v[14:17], v[160:163], v[210:213], v[14:17]
	s_barrier
	s_add_u32 s26, s26, 0x20080
	s_addc_u32 s27, s27, 0
	s_mov_b32 m0, s50
	v_lshl_add_u64 v[50:51], s[26:27], 0, v[0:1]
	global_load_lds_dwordx4 v[50:51], off
	v_lshl_add_u64 v[50:51], s[26:27], 0, v[152:153]
	s_mov_b32 m0, s51
	s_nop 0
	global_load_lds_dwordx4 v[50:51], off
	s_waitcnt vmcnt(6)
	s_barrier
	v_mfma_f32_16x16x32_f16 v[34:37], v[214:217], v[164:167], v[34:37]
	v_mfma_f32_16x16x32_f16 v[66:69], v[218:221], v[174:177], v[34:37]
	v_mfma_f32_16x16x32_f16 v[34:37], v[222:225], v[164:167], v[46:49]
	v_mfma_f32_16x16x32_f16 v[70:73], v[226:229], v[174:177], v[34:37]
	v_mfma_f32_16x16x32_f16 v[34:37], v[214:217], v[178:181], v[38:41]
	v_mfma_f32_16x16x32_f16 v[38:41], v[218:221], v[182:185], v[34:37]
	v_mfma_f32_16x16x32_f16 v[34:37], v[222:225], v[178:181], v[42:45]
	v_mfma_f32_16x16x32_f16 v[18:21], v[214:217], v[186:189], v[18:21]
	v_mfma_f32_16x16x32_f16 v[22:25], v[222:225], v[186:189], v[22:25]
	v_mfma_f32_16x16x32_f16 v[2:5], v[214:217], v[206:209], v[2:5]
	v_mfma_f32_16x16x32_f16 v[6:9], v[222:225], v[206:209], v[6:9]
	v_mfma_f32_16x16x32_f16 v[42:45], v[226:229], v[182:185], v[34:37]
	v_mfma_f32_16x16x32_f16 v[18:21], v[218:221], v[202:205], v[18:21]
	v_mfma_f32_16x16x32_f16 v[22:25], v[226:229], v[202:205], v[22:25]
	v_mfma_f32_16x16x32_f16 v[2:5], v[218:221], v[210:213], v[2:5]
	v_mfma_f32_16x16x32_f16 v[6:9], v[226:229], v[210:213], v[6:9]
	s_add_i32 s55, s55, 2
	s_add_u32 s24, s24, 0x100
	s_addc_u32 s25, s25, 0
	s_add_u32 s53, s53, 0x100
	s_addc_u32 s54, s54, 0
	s_cmp_gt_u32 s55, 5
	s_barrier
	s_cbranch_scc0 .LBB0_2284
; __device__ __forceinline__ float xor16(float v) { return __int_as_float(__builtin_amdgcn_ds_swizzle(__float_as_int(v), 0x401F)); }
; __device__ __forceinline__ float sigmoidf(float x) { return 1.f / (1.f + __expf(-x)); }
;   __device__ __forceinline__ void operator()(const f32x4 (&acc)[2][2][4][2], const g8::Unit& u, int ui, int wr, int wc, int fr, int fq) const {
;     const int ocb = 128 * u.pn + 16 * wc + 4 * fq;
;     float4 ba[2], bb[2];
; #pragma unroll
;     for (int bj = 0; bj < 2; ++bj) { ba[bj] = *(const float4*)(gb + ocb + 64 * bj); bb[bj] = *(const float4*)(gb + 512 + ocb + 64 * bj); }
; #pragma unroll
;     for (int ai = 0; ai < 2; ++ai)
; #pragma unroll
;       for (int m = 0; m < 4; ++m) {
;         const size_t row = (size_t)u.pm * 256 + 128 * ai + 64 * wr + 16 * m + fr;
;         float ss = 0.f;
; #pragma unroll
;         for (int bj = 0; bj < 2; ++bj) {
;           const f32x4 a = acc[ai][bj][m][0], b = acc[ai][bj][m][1];
;           float o0 = (a[0] + ba[bj].x) * sigmoidf(b[0] + bb[bj].x);
;           float o1 = (a[1] + ba[bj].y) * sigmoidf(b[1] + bb[bj].y);
;           float o2 = (a[2] + ba[bj].z) * sigmoidf(b[2] + bb[bj].z);
;           float o3 = (a[3] + ba[bj].w) * sigmoidf(b[3] + bb[bj].w);
;           *(h16x4*)(OB + row * 1024 + ocb + 64 * bj) = pack4(o0, o1, o2, o3);
;           ss += o0 * o0 + o1 * o1 + o2 * o2 + o3 * o3;
;         }
;         ss += xor16(ss);
;         ss += __shfl_xor(ss, 32);
;         if (fq == 0) ssqb[row * 16 + u.pn * 4 + wc] = ss;
;       }
	v_lshl_or_b32 v160, s2, 7, v172
	v_ashrrev_i32_e32 v161, 31, v160
	v_lshl_add_u64 v[166:167], v[160:161], 2, s[12:13]
	global_load_dwordx4 v[46:49], v[166:167], off offset:2048
	global_load_dwordx4 v[34:37], v[166:167], off offset:2304
	v_and_b32_e32 v51, 64, v199
	v_xor_b32_e32 v50, 32, v199
	v_add_u32_e32 v51, 64, v51
	v_cmp_lt_i32_e32 vcc, v50, v51
	s_ashr_i32 s23, s22, 31
	s_lshl_b64 s[22:23], s[22:23], 8
	v_cndmask_b32_e32 v50, v199, v50, vcc
	v_lshlrev_b32_e32 v173, 2, v50
	v_lshl_add_u64 v[162:163], s[22:23], 0, v[154:155]
	s_lshl_b32 s22, s2, 2
	v_lshlrev_b64 v[164:165], 11, v[162:163]
	s_ashr_i32 s23, s22, 31
	s_waitcnt vmcnt(0)
	v_add_f32_e32 v50, v138, v46
	v_mul_f32_e32 v50, 0xbfb8aa3b, v50
	v_exp_f32_e32 v138, v50
	global_load_dwordx4 v[50:53], v[166:167], off
	v_add_f32_e32 v139, v139, v47
	v_mul_f32_e32 v139, 0xbfb8aa3b, v139
	v_exp_f32_e32 v139, v139
	v_add_f32_e32 v140, v140, v48
	v_add_f32_e32 v141, v141, v49
	v_mul_f32_e32 v140, 0xbfb8aa3b, v140
	v_pk_add_f32 v[138:139], v[138:139], 1.0 op_sel_hi:[1,0]
	v_mul_f32_e32 v141, 0xbfb8aa3b, v141
	v_div_scale_f32 v168, s[2:3], v139, v139, 1.0
	v_rcp_f32_e32 v169, v168
	v_exp_f32_e32 v140, v140
	v_exp_f32_e32 v141, v141
	v_add_f32_e32 v135, v135, v35
	v_fma_f32 v174, -v168, v169, 1.0
	v_fmac_f32_e32 v169, v174, v169
	v_div_scale_f32 v174, vcc, 1.0, v139, 1.0
	v_mul_f32_e32 v175, v174, v169
	v_fma_f32 v176, -v168, v175, v174
	v_fmac_f32_e32 v175, v176, v169
	v_fma_f32 v168, -v168, v175, v174
	v_div_fmas_f32 v168, v168, v169, v175
	v_div_fixup_f32 v139, v168, v139, 1.0
	v_div_scale_f32 v168, s[2:3], v138, v138, 1.0
	v_rcp_f32_e32 v169, v168
	v_mul_f32_e32 v135, 0xbfb8aa3b, v135
	v_exp_f32_e32 v135, v135
	v_add_f32_e32 v136, v136, v36
	v_fma_f32 v174, -v168, v169, 1.0
	v_fmac_f32_e32 v169, v174, v169
	v_div_scale_f32 v174, vcc, 1.0, v138, 1.0
	v_mul_f32_e32 v175, v174, v169
	v_fma_f32 v176, -v168, v175, v174
	v_fmac_f32_e32 v175, v176, v169
	v_fma_f32 v168, -v168, v175, v174
	v_div_fmas_f32 v168, v168, v169, v175
	v_div_fixup_f32 v138, v168, v138, 1.0
	v_add_f32_e32 v137, v137, v37
	v_mul_f32_e32 v136, 0xbfb8aa3b, v136
	v_mul_f32_e32 v137, 0xbfb8aa3b, v137
	v_exp_f32_e32 v136, v136
	v_exp_f32_e32 v137, v137
	s_waitcnt vmcnt(0)
	v_pk_add_f32 v[62:63], v[62:63], v[50:51]
	s_nop 0
	v_pk_mul_f32 v[62:63], v[62:63], v[138:139]
	v_pk_add_f32 v[138:139], v[140:141], 1.0 op_sel_hi:[1,0]
	v_cvt_pk_f16_f32 v168, v62, v63
	v_div_scale_f32 v140, s[2:3], v139, v139, 1.0
	v_rcp_f32_e32 v141, v140
	v_pk_add_f32 v[64:65], v[64:65], v[52:53]
	v_pk_add_f32 v[136:137], v[136:137], 1.0 op_sel_hi:[1,0]
	v_fma_f32 v169, -v140, v141, 1.0
	v_fmac_f32_e32 v141, v169, v141
	v_div_scale_f32 v169, vcc, 1.0, v139, 1.0
	v_mul_f32_e32 v174, v169, v141
	v_fma_f32 v175, -v140, v174, v169
	v_fmac_f32_e32 v174, v175, v141
	v_fma_f32 v140, -v140, v174, v169
	v_div_fmas_f32 v140, v140, v141, v174
	v_div_fixup_f32 v139, v140, v139, 1.0
	v_div_scale_f32 v140, s[2:3], v138, v138, 1.0
	v_rcp_f32_e32 v141, v140
	s_nop 0
	v_fma_f32 v169, -v140, v141, 1.0
	v_fmac_f32_e32 v141, v169, v141
	v_div_scale_f32 v169, vcc, 1.0, v138, 1.0
	v_mul_f32_e32 v174, v169, v141
	v_fma_f32 v175, -v140, v174, v169
	v_fmac_f32_e32 v174, v175, v141
	v_fma_f32 v140, -v140, v174, v169
	v_div_fmas_f32 v140, v140, v141, v174
	v_div_fixup_f32 v138, v140, v138, 1.0
	v_pk_mul_f32 v[140:141], v[62:63], v[62:63]
	v_add_f32_e32 v62, v134, v34
	v_pk_mul_f32 v[64:65], v[64:65], v[138:139]
	v_lshl_add_u64 v[138:139], s[0:1], 0, v[164:165]
	v_mul_f32_e32 v62, 0xbfb8aa3b, v62
	v_cvt_pk_f16_f32 v169, v64, v65
	v_lshl_add_u64 v[164:165], v[160:161], 1, v[138:139]
	v_pk_mul_f32 v[138:139], v[64:65], v[64:65]
	v_exp_f32_e32 v134, v62
	global_load_dwordx4 v[62:65], v[166:167], off offset:256
	v_pk_add_f32 v[134:135], v[134:135], 1.0 op_sel_hi:[1,0]
	s_nop 0
	v_div_scale_f32 v166, s[2:3], v135, v135, 1.0
	v_rcp_f32_e32 v167, v166
	global_store_dwordx2 v[164:165], v[168:169], off
	v_fma_f32 v168, -v166, v167, 1.0
	v_fmac_f32_e32 v167, v168, v167
	v_div_scale_f32 v168, vcc, 1.0, v135, 1.0
	v_mul_f32_e32 v169, v168, v167
	v_fma_f32 v174, -v166, v169, v168
	v_fmac_f32_e32 v169, v174, v167
	v_fma_f32 v166, -v166, v169, v168
	v_div_fmas_f32 v166, v166, v167, v169
	v_div_fixup_f32 v135, v166, v135, 1.0
	v_div_scale_f32 v166, s[2:3], v134, v134, 1.0
	v_rcp_f32_e32 v167, v166
	s_waitcnt vmcnt(0)
	v_pk_add_f32 v[130:131], v[130:131], v[62:63]
	v_fma_f32 v168, -v166, v167, 1.0
	v_fmac_f32_e32 v167, v168, v167
	v_div_scale_f32 v168, vcc, 1.0, v134, 1.0
	v_mul_f32_e32 v169, v168, v167
	v_fma_f32 v174, -v166, v169, v168
	v_fmac_f32_e32 v169, v174, v167
	v_fma_f32 v166, -v166, v169, v168
	v_div_fmas_f32 v166, v166, v167, v169
	v_div_fixup_f32 v134, v166, v134, 1.0
	v_pk_mul_f32 v[130:131], v[130:131], v[134:135]
	v_div_scale_f32 v135, s[2:3], v137, v137, 1.0
	v_rcp_f32_e32 v166, v135
	v_pk_add_f32 v[132:133], v[132:133], v[64:65]
	v_cvt_pk_f16_f32 v134, v130, v131
	v_pk_mul_f32 v[130:131], v[130:131], v[130:131]
	v_fma_f32 v167, -v135, v166, 1.0
	v_fmac_f32_e32 v166, v167, v166
	v_div_scale_f32 v167, vcc, 1.0, v137, 1.0
	v_mul_f32_e32 v168, v167, v166
	v_fma_f32 v169, -v135, v168, v167
	v_fmac_f32_e32 v168, v169, v166
	v_fma_f32 v135, -v135, v168, v167
	v_div_fmas_f32 v135, v135, v166, v168
	v_div_fixup_f32 v137, v135, v137, 1.0
	v_div_scale_f32 v135, s[2:3], v136, v136, 1.0
	v_rcp_f32_e32 v166, v135
	v_add_f32_e32 v130, v130, v131
	v_add_f32_e32 v131, v140, v141
	v_add_f32_e32 v131, v138, v131
	v_fma_f32 v167, -v135, v166, 1.0
	v_fmac_f32_e32 v166, v167, v166
	v_div_scale_f32 v167, vcc, 1.0, v136, 1.0
	v_mul_f32_e32 v168, v167, v166
	v_fma_f32 v169, -v135, v168, v167
	v_fmac_f32_e32 v168, v169, v166
	v_fma_f32 v135, -v135, v168, v167
	v_div_fmas_f32 v135, v135, v166, v168
	v_div_fixup_f32 v136, v135, v136, 1.0
	v_pk_mul_f32 v[132:133], v[132:133], v[136:137]
	v_add_f32_e32 v131, v139, v131
	v_cvt_pk_f16_f32 v135, v132, v133
	v_pk_mul_f32 v[132:133], v[132:133], v[132:133]
	global_store_dwordx2 v[164:165], v[134:135], off offset:128
	v_add_f32_e32 v130, v132, v130
	v_add_f32_e32 v130, v133, v130
	v_add_f32_e32 v130, v131, v130
	v_mov_b32_e32 v131, v130
	s_nop 1
	v_permlane16_swap_b32_e32 v131, v130
	s_waitcnt lgkmcnt(0)
	v_add_f32_e32 v130, v130, v131
	v_mov_b32_e32 v131, v130
	s_nop 1
	v_permlane32_swap_b32_e32 v131, v130
	s_and_saveexec_b64 s[24:25], s[6:7]
	s_cbranch_execz .LBB0_2287
	s_waitcnt lgkmcnt(0)
	v_add_f32_e32 v132, v130, v131
	v_lshlrev_b64 v[130:131], 6, v[162:163]
	v_lshl_add_u64 v[130:131], s[10:11], 0, v[130:131]
	v_lshl_add_u64 v[130:131], s[22:23], 2, v[130:131]
	s_lshl_b32 s92, s45, 2
	v_lshl_add_u64 v[130:131], v[130:131], 0, s[92:93]
	global_store_dword v[130:131], v132, off

; #define G8_STAGE(bufoff, gbase) do { _Pragma("unroll") for (int _i = 0; _i < 2; ++_i) \
;     __builtin_amdgcn_global_load_lds((const unsigned*)((const char*)(gbase) + voffA[_i]), (LAS unsigned*)(lds + (bufoff) + ldsw + _i * 8192), 16, 0, 0); } while (0)
; #define G8_LDA(dst, b, h) do { _Pragma("unroll") for (int m = 0; m < 4; ++m) _Pragma("unroll") for (int k = 0; k < 2; ++k) dst[m][k] = *(const LAS h16x8*)(lds + G8_SA(b, h) + aoff + m * 2048 + k * 1024); } while (0)
; #define G8_LDB(dst, b, h) do { _Pragma("unroll") for (int n = 0; n < 2; ++n) _Pragma("unroll") for (int k = 0; k < 2; ++k) dst[n][k] = *(const LAS h16x8*)(lds + G8_SB(b, h) + boff + n * 2048 + k * 1024); } while (0)
; #define G8_MMA(ai, bj, At, Bt_) do { __builtin_amdgcn_s_setprio(1); _Pragma("unroll") for (int m = 0; m < 4; ++m) _Pragma("unroll") for (int n = 0; n < 2; ++n) _Pragma("unroll") for (int k = 0; k < 2; ++k) \
;     acc[ai][bj][m][n] = __builtin_amdgcn_mfma_f32_16x16x32_f16(Bt_[n][k], At[m][k], acc[ai][bj][m][n], 0, 0, 0); __builtin_amdgcn_s_setprio(0); } while (0)
; #define G8_WAIT_V(n) asm volatile("s_waitcnt vmcnt(" #n ")" ::: "memory")
; #define G8_WAIT_L(n) asm volatile("s_waitcnt lgkmcnt(" #n ")" ::: "memory")
; #define G8_BAR __builtin_amdgcn_s_barrier()
; template <class Epi>
; __device__ __forceinline__ void gemm_phase(LAS unsigned char* lds, const h16* A, const h16* Bt, int K, const Order& S, const Epi& E) {
;     ...
;     for (int t = 0; t < nt; t += 2) {
;       const bool last = (t == nt - 2);
;       const char* a1 = cA + (size_t)(t + 1) * kstep;
;       const char* a2 = last ? nA : cA + (size_t)(t + 2) * kstep;
;       const char* b2 = last ? nB : cB + (size_t)(t + 2) * kstep;
;       const char* a3 = a2 + kstep;
;       const char* b3 = b2 + kstep;
;       if (Epi::MID_T >= 0 && t == Epi::MID_T) E.mid(acc, ui, wr, fr);
;       G8_LDB(B0, 0, 0); G8_SCHED; G8_LDA(At, 0, 0); G8_STAGE(G8_SA(1, 1), a1 + hstep);
;       G8_WAIT_L(8); G8_BAR; G8_WAIT_L(0); G8_MMA(0, 0, At, B0); G8_BAR; G8_SCHED;
;       G8_LDB(B1, 0, 1); G8_STAGE(G8_SB(0, 0), b2);
;       G8_BAR; G8_WAIT_L(0); G8_MMA(0, 1, At, B1); G8_BAR;
;       G8_LDA(At, 0, 1); G8_STAGE(G8_SA(0, 0), a2);
;       G8_BAR; G8_WAIT_L(0); G8_MMA(1, 0, At, B0); G8_BAR; G8_SCHED;
;       G8_STAGE(G8_SB(0, 1), b2 + hstep);
;       G8_WAIT_V(6); G8_BAR; G8_MMA(1, 1, At, B1); G8_BAR;
.LBB0_2378:
	s_add_u32 s26, s20, s24
	v_or_b32_e32 v0, 0x10000, v158
	s_addc_u32 s27, s21, s25
	v_add_u32_e32 v2, 0x10400, v158
	ds_read_b128 v[162:165], v0
	ds_read_b128 v[166:169], v2
	v_add_u32_e32 v0, 0x10800, v158
	s_add_u32 s26, s26, 0x100
	v_add_u32_e32 v2, 0x10c00, v158
	ds_read_b128 v[170:173], v0
	ds_read_b128 v[174:177], v2
	s_addc_u32 s27, s27, 0
	s_add_u32 s56, s53, s24
	s_addc_u32 s57, s54, s25
	s_cmpk_eq_i32 s24, 0x700
	s_cselect_b32 s29, s3, s27
	s_cselect_b32 s28, s15, s26
	s_cselect_b32 s27, s13, s57
	s_cselect_b32 s26, s23, s56
	v_lshl_add_u64 v[2:3], v[154:155], 0, s[24:25]
	s_add_i32 m0, s37, 0xc000
	ds_read_b128 v[178:181], v139
	ds_read_b128 v[182:185], v139 offset:1024
	ds_read_b128 v[186:189], v139 offset:2048
	ds_read_b128 v[202:205], v139 offset:3072
	ds_read_b128 v[206:209], v139 offset:4096
	ds_read_b128 v[210:213], v139 offset:5120
	ds_read_b128 v[214:217], v139 offset:6144
	ds_read_b128 v[218:221], v139 offset:7168
	global_load_lds_dwordx4 v[2:3], off
	v_lshl_add_u64 v[2:3], v[156:157], 0, s[24:25]
	s_add_i32 m0, s37, 0xe000
	s_nop 0
	global_load_lds_dwordx4 v[2:3], off
	s_waitcnt lgkmcnt(8)
	s_barrier
	s_waitcnt lgkmcnt(0)
	v_mfma_f32_16x16x32_f16 v[128:131], v[162:165], v[178:181], v[128:131]
	v_mfma_f32_16x16x32_f16 v[124:127], v[170:173], v[178:181], v[124:127]
	v_mfma_f32_16x16x32_f16 v[112:115], v[162:165], v[186:189], v[112:115]
	v_mfma_f32_16x16x32_f16 v[108:111], v[170:173], v[186:189], v[108:111]
	v_mfma_f32_16x16x32_f16 v[96:99], v[162:165], v[206:209], v[96:99]
	v_mfma_f32_16x16x32_f16 v[92:95], v[170:173], v[206:209], v[92:95]
	v_mfma_f32_16x16x32_f16 v[80:83], v[162:165], v[214:217], v[80:83]
	v_mfma_f32_16x16x32_f16 v[76:79], v[170:173], v[214:217], v[76:79]
	v_mfma_f32_16x16x32_f16 v[128:131], v[166:169], v[182:185], v[128:131]
	v_mfma_f32_16x16x32_f16 v[124:127], v[174:177], v[182:185], v[124:127]
	v_mfma_f32_16x16x32_f16 v[112:115], v[166:169], v[202:205], v[112:115]
	v_mfma_f32_16x16x32_f16 v[108:111], v[174:177], v[202:205], v[108:111]
	v_mfma_f32_16x16x32_f16 v[96:99], v[166:169], v[210:213], v[96:99]
	v_mfma_f32_16x16x32_f16 v[92:95], v[174:177], v[210:213], v[92:95]
	v_mfma_f32_16x16x32_f16 v[80:83], v[166:169], v[218:221], v[80:83]
	v_mfma_f32_16x16x32_f16 v[76:79], v[174:177], v[218:221], v[76:79]
	s_barrier
	v_or_b32_e32 v0, 0x14000, v158
	s_mov_b32 m0, s38
	v_add_u32_e32 v2, 0x14400, v158
	ds_read_b128 v[222:225], v0
	ds_read_b128 v[226:229], v2
	v_add_u32_e32 v0, 0x14800, v158
	v_lshl_add_u64 v[238:239], s[26:27], 0, v[134:135]
	v_add_u32_e32 v2, 0x14c00, v158
	ds_read_b128 v[230:233], v0
	ds_read_b128 v[234:237], v2
	global_load_lds_dwordx4 v[238:239], off
	v_lshl_add_u64 v[240:241], s[26:27], 0, v[132:133]
	s_mov_b32 m0, s39
	s_nop 0
	global_load_lds_dwordx4 v[240:241], off
	s_barrier
	s_waitcnt lgkmcnt(0)
	v_mfma_f32_16x16x32_f16 v[120:123], v[222:225], v[178:181], v[120:123]
	v_mfma_f32_16x16x32_f16 v[116:119], v[230:233], v[178:181], v[116:119]
	v_mfma_f32_16x16x32_f16 v[104:107], v[222:225], v[186:189], v[104:107]
	v_mfma_f32_16x16x32_f16 v[100:103], v[230:233], v[186:189], v[100:103]
	v_mfma_f32_16x16x32_f16 v[88:91], v[222:225], v[206:209], v[88:91]
	v_mfma_f32_16x16x32_f16 v[84:87], v[230:233], v[206:209], v[84:87]
	v_mfma_f32_16x16x32_f16 v[72:75], v[222:225], v[214:217], v[72:75]
	v_mfma_f32_16x16x32_f16 v[68:71], v[230:233], v[214:217], v[68:71]
	v_mfma_f32_16x16x32_f16 v[120:123], v[226:229], v[182:185], v[120:123]
	v_mfma_f32_16x16x32_f16 v[116:119], v[234:237], v[182:185], v[116:119]
	v_mfma_f32_16x16x32_f16 v[104:107], v[226:229], v[202:205], v[104:107]
	v_mfma_f32_16x16x32_f16 v[100:103], v[234:237], v[202:205], v[100:103]
	v_mfma_f32_16x16x32_f16 v[88:91], v[226:229], v[210:213], v[88:91]
	v_mfma_f32_16x16x32_f16 v[84:87], v[234:237], v[210:213], v[84:87]
	v_mfma_f32_16x16x32_f16 v[72:75], v[226:229], v[218:221], v[72:75]
	v_mfma_f32_16x16x32_f16 v[68:71], v[234:237], v[218:221], v[68:71]
	s_mov_b32 m0, s37
	v_lshl_add_u64 v[242:243], s[28:29], 0, v[134:135]
	s_barrier
	ds_read_b128 v[178:181], v139 offset:16384
	ds_read_b128 v[182:185], v139 offset:17408
	ds_read_b128 v[186:189], v139 offset:18432
	ds_read_b128 v[202:205], v139 offset:19456
	ds_read_b128 v[206:209], v139 offset:20480
	ds_read_b128 v[210:213], v139 offset:21504
	ds_read_b128 v[214:217], v139 offset:22528
	ds_read_b128 v[218:221], v139 offset:23552
	global_load_lds_dwordx4 v[242:243], off
	v_lshl_add_u64 v[244:245], s[28:29], 0, v[132:133]
	s_mov_b32 m0, s40
	s_nop 0
	global_load_lds_dwordx4 v[244:245], off
	s_barrier
	s_waitcnt lgkmcnt(0)
	v_mfma_f32_16x16x32_f16 v[64:67], v[162:165], v[178:181], v[64:67]
	v_mfma_f32_16x16x32_f16 v[60:63], v[170:173], v[178:181], v[60:63]
	v_mfma_f32_16x16x32_f16 v[48:51], v[162:165], v[186:189], v[48:51]
	v_mfma_f32_16x16x32_f16 v[44:47], v[170:173], v[186:189], v[44:47]
	v_mfma_f32_16x16x32_f16 v[32:35], v[162:165], v[206:209], v[32:35]
	v_mfma_f32_16x16x32_f16 v[28:31], v[170:173], v[206:209], v[28:31]
	v_mfma_f32_16x16x32_f16 v[16:19], v[162:165], v[214:217], v[16:19]
	v_mfma_f32_16x16x32_f16 v[12:15], v[170:173], v[214:217], v[12:15]
	v_mfma_f32_16x16x32_f16 v[64:67], v[166:169], v[182:185], v[64:67]
	v_mfma_f32_16x16x32_f16 v[60:63], v[174:177], v[182:185], v[60:63]
	v_mfma_f32_16x16x32_f16 v[48:51], v[166:169], v[202:205], v[48:51]
	v_mfma_f32_16x16x32_f16 v[44:47], v[174:177], v[202:205], v[44:47]
	v_mfma_f32_16x16x32_f16 v[32:35], v[166:169], v[210:213], v[32:35]
	v_mfma_f32_16x16x32_f16 v[28:31], v[174:177], v[210:213], v[28:31]
	v_mfma_f32_16x16x32_f16 v[16:19], v[166:169], v[218:221], v[16:19]
	v_mfma_f32_16x16x32_f16 v[12:15], v[174:177], v[218:221], v[12:15]
	s_barrier
; #define G8_STAGE(bufoff, gbase) do { _Pragma("unroll") for (int _i = 0; _i < 2; ++_i) \
;     __builtin_amdgcn_global_load_lds((const unsigned*)((const char*)(gbase) + voffA[_i]), (LAS unsigned*)(lds + (bufoff) + ldsw + _i * 8192), 16, 0, 0); } while (0)
; #define G8_LDA(dst, b, h) do { _Pragma("unroll") for (int m = 0; m < 4; ++m) _Pragma("unroll") for (int k = 0; k < 2; ++k) dst[m][k] = *(const LAS h16x8*)(lds + G8_SA(b, h) + aoff + m * 2048 + k * 1024); } while (0)
; #define G8_LDB(dst, b, h) do { _Pragma("unroll") for (int n = 0; n < 2; ++n) _Pragma("unroll") for (int k = 0; k < 2; ++k) dst[n][k] = *(const LAS h16x8*)(lds + G8_SB(b, h) + boff + n * 2048 + k * 1024); } while (0)
; #define G8_MMA(ai, bj, At, Bt_) do { __builtin_amdgcn_s_setprio(1); _Pragma("unroll") for (int m = 0; m < 4; ++m) _Pragma("unroll") for (int n = 0; n < 2; ++n) _Pragma("unroll") for (int k = 0; k < 2; ++k) \
;     acc[ai][bj][m][n] = __builtin_amdgcn_mfma_f32_16x16x32_f16(Bt_[n][k], At[m][k], acc[ai][bj][m][n], 0, 0, 0); __builtin_amdgcn_s_setprio(0); } while (0)
; #define G8_WAIT_V(n) asm volatile("s_waitcnt vmcnt(" #n ")" ::: "memory")
; #define G8_WAIT_L(n) asm volatile("s_waitcnt lgkmcnt(" #n ")" ::: "memory")
; #define G8_BAR __builtin_amdgcn_s_barrier()
; #define G8_SCHED __builtin_amdgcn_sched_barrier(0)
; template <class Epi>
; __device__ __forceinline__ void gemm_phase(LAS unsigned char* lds, const h16* A, const h16* Bt, int K, const Order& S, const Epi& E) {
;     ...
;       G8_LDA(At, 0, 1); G8_STAGE(G8_SA(0, 0), a2);
;       G8_BAR; G8_WAIT_L(0); G8_MMA(1, 0, At, B0); G8_BAR; G8_SCHED;
;       G8_STAGE(G8_SB(0, 1), b2 + hstep);
;       G8_WAIT_V(6); G8_BAR; G8_MMA(1, 1, At, B1); G8_BAR;
;       G8_LDB(B0, 1, 0); G8_SCHED; G8_LDA(At, 1, 0); G8_STAGE(G8_SA(0, 1), a2 + hstep);
;       G8_WAIT_L(8); G8_BAR; G8_WAIT_L(0); G8_MMA(0, 0, At, B0); G8_BAR; G8_SCHED;
;       G8_LDB(B1, 1, 1); G8_STAGE(G8_SB(1, 0), b3);
;       G8_BAR; G8_WAIT_L(0); G8_MMA(0, 1, At, B1); G8_BAR;
;       G8_LDA(At, 1, 1); G8_STAGE(G8_SA(1, 0), a3);
;       G8_BAR; G8_WAIT_L(0); G8_MMA(1, 0, At, B0); G8_BAR; G8_SCHED;
	s_add_u32 s56, s26, 0x40000
	s_addc_u32 s57, s27, 0
	s_mov_b32 m0, s41
	v_lshl_add_u64 v[2:3], s[56:57], 0, v[134:135]
	global_load_lds_dwordx4 v[2:3], off
	v_lshl_add_u64 v[2:3], s[56:57], 0, v[132:133]
	s_mov_b32 m0, s42
	s_nop 0
	global_load_lds_dwordx4 v[2:3], off
	s_waitcnt vmcnt(6)
	s_barrier
	v_mfma_f32_16x16x32_f16 v[56:59], v[222:225], v[178:181], v[56:59]
	v_mfma_f32_16x16x32_f16 v[52:55], v[230:233], v[178:181], v[52:55]
	v_mfma_f32_16x16x32_f16 v[40:43], v[222:225], v[186:189], v[40:43]
	v_mfma_f32_16x16x32_f16 v[36:39], v[230:233], v[186:189], v[36:39]
	v_mfma_f32_16x16x32_f16 v[24:27], v[222:225], v[206:209], v[24:27]
	v_mfma_f32_16x16x32_f16 v[20:23], v[230:233], v[206:209], v[20:23]
	v_mfma_f32_16x16x32_f16 v[8:11], v[222:225], v[214:217], v[8:11]
	v_mfma_f32_16x16x32_f16 v[2:5], v[230:233], v[214:217], v[4:7]
	v_mfma_f32_16x16x32_f16 v[56:59], v[226:229], v[182:185], v[56:59]
	v_mfma_f32_16x16x32_f16 v[52:55], v[234:237], v[182:185], v[52:55]
	v_mfma_f32_16x16x32_f16 v[40:43], v[226:229], v[202:205], v[40:43]
	v_mfma_f32_16x16x32_f16 v[36:39], v[234:237], v[202:205], v[36:39]
	v_mfma_f32_16x16x32_f16 v[24:27], v[226:229], v[210:213], v[24:27]
	v_mfma_f32_16x16x32_f16 v[20:23], v[234:237], v[210:213], v[20:23]
	v_mfma_f32_16x16x32_f16 v[8:11], v[226:229], v[218:221], v[8:11]
	v_mfma_f32_16x16x32_f16 v[2:5], v[234:237], v[218:221], v[2:5]
	v_or_b32_e32 v0, 0x18000, v158
	s_barrier
	v_add_u32_e32 v6, 0x18400, v158
	ds_read_b128 v[162:165], v0
	ds_read_b128 v[166:169], v6
	v_add_u32_e32 v0, 0x18800, v158
	v_add_u32_e32 v6, 0x18c00, v158
	ds_read_b128 v[170:173], v0
	ds_read_b128 v[174:177], v6
	s_add_u32 s28, s28, 0x40000
	s_addc_u32 s29, s29, 0
	s_mov_b32 m0, s43
	v_lshl_add_u64 v[6:7], s[28:29], 0, v[134:135]
	ds_read_b128 v[178:181], v139 offset:32768
	ds_read_b128 v[182:185], v139 offset:33792
	ds_read_b128 v[186:189], v139 offset:34816
	ds_read_b128 v[202:205], v139 offset:35840
	ds_read_b128 v[206:209], v139 offset:36864
	ds_read_b128 v[210:213], v139 offset:37888
	ds_read_b128 v[214:217], v139 offset:38912
	ds_read_b128 v[218:221], v139 offset:39936
	global_load_lds_dwordx4 v[6:7], off
	v_lshl_add_u64 v[6:7], s[28:29], 0, v[132:133]
	s_mov_b32 m0, s44
	s_nop 0
	global_load_lds_dwordx4 v[6:7], off
	s_waitcnt lgkmcnt(8)
	s_barrier
	s_waitcnt lgkmcnt(0)
	v_mfma_f32_16x16x32_f16 v[128:131], v[162:165], v[178:181], v[128:131]
	v_mfma_f32_16x16x32_f16 v[124:127], v[170:173], v[178:181], v[124:127]
	v_mfma_f32_16x16x32_f16 v[112:115], v[162:165], v[186:189], v[112:115]
	v_mfma_f32_16x16x32_f16 v[108:111], v[170:173], v[186:189], v[108:111]
	v_mfma_f32_16x16x32_f16 v[96:99], v[162:165], v[206:209], v[96:99]
	v_mfma_f32_16x16x32_f16 v[92:95], v[170:173], v[206:209], v[92:95]
	v_mfma_f32_16x16x32_f16 v[80:83], v[162:165], v[214:217], v[80:83]
	v_mfma_f32_16x16x32_f16 v[76:79], v[170:173], v[214:217], v[76:79]
	v_mfma_f32_16x16x32_f16 v[128:131], v[166:169], v[182:185], v[128:131]
	v_mfma_f32_16x16x32_f16 v[124:127], v[174:177], v[182:185], v[124:127]
	v_mfma_f32_16x16x32_f16 v[112:115], v[166:169], v[202:205], v[112:115]
	v_mfma_f32_16x16x32_f16 v[108:111], v[174:177], v[202:205], v[108:111]
	v_mfma_f32_16x16x32_f16 v[96:99], v[166:169], v[210:213], v[96:99]
	v_mfma_f32_16x16x32_f16 v[92:95], v[174:177], v[210:213], v[92:95]
	v_mfma_f32_16x16x32_f16 v[80:83], v[166:169], v[218:221], v[80:83]
	v_mfma_f32_16x16x32_f16 v[76:79], v[174:177], v[218:221], v[76:79]
	s_barrier
	v_or_b32_e32 v0, 0x1c000, v158
	v_add_u32_e32 v6, 0x1c400, v158
	ds_read_b128 v[222:225], v0
	ds_read_b128 v[226:229], v6
	v_add_u32_e32 v0, 0x1c800, v158
	v_add_u32_e32 v6, 0x1cc00, v158
	s_mov_b32 m0, s46
	ds_read_b128 v[230:233], v0
	ds_read_b128 v[234:237], v6
	v_lshl_add_u64 v[6:7], v[238:239], 0, s[94:95]
	global_load_lds_dwordx4 v[6:7], off
	v_lshl_add_u64 v[6:7], v[240:241], 0, s[94:95]
	s_mov_b32 m0, s47
	s_nop 0
	global_load_lds_dwordx4 v[6:7], off
	s_barrier
; #define G8_STAGE(bufoff, gbase) do { _Pragma("unroll") for (int _i = 0; _i < 2; ++_i) \
;     __builtin_amdgcn_global_load_lds((const unsigned*)((const char*)(gbase) + voffA[_i]), (LAS unsigned*)(lds + (bufoff) + ldsw + _i * 8192), 16, 0, 0); } while (0)
; #define G8_LDA(dst, b, h) do { _Pragma("unroll") for (int m = 0; m < 4; ++m) _Pragma("unroll") for (int k = 0; k < 2; ++k) dst[m][k] = *(const LAS h16x8*)(lds + G8_SA(b, h) + aoff + m * 2048 + k * 1024); } while (0)
; #define G8_LDB(dst, b, h) do { _Pragma("unroll") for (int n = 0; n < 2; ++n) _Pragma("unroll") for (int k = 0; k < 2; ++k) dst[n][k] = *(const LAS h16x8*)(lds + G8_SB(b, h) + boff + n * 2048 + k * 1024); } while (0)
; #define G8_MMA(ai, bj, At, Bt_) do { __builtin_amdgcn_s_setprio(1); _Pragma("unroll") for (int m = 0; m < 4; ++m) _Pragma("unroll") for (int n = 0; n < 2; ++n) _Pragma("unroll") for (int k = 0; k < 2; ++k) \
;     acc[ai][bj][m][n] = __builtin_amdgcn_mfma_f32_16x16x32_f16(Bt_[n][k], At[m][k], acc[ai][bj][m][n], 0, 0, 0); __builtin_amdgcn_s_setprio(0); } while (0)
; #define G8_WAIT_V(n) asm volatile("s_waitcnt vmcnt(" #n ")" ::: "memory")
; #define G8_WAIT_L(n) asm volatile("s_waitcnt lgkmcnt(" #n ")" ::: "memory")
; #define G8_BAR __builtin_amdgcn_s_barrier()
; #define G8_SCHED __builtin_amdgcn_sched_barrier(0)
; template <class Epi>
; __device__ __forceinline__ void gemm_phase(LAS unsigned char* lds, const h16* A, const h16* Bt, int K, const Order& S, const Epi& E) {
;     ...
;       G8_WAIT_V(6); G8_BAR; G8_MMA(1, 1, At, B1); G8_BAR;
;       G8_LDB(B0, 1, 0); G8_SCHED; G8_LDA(At, 1, 0); G8_STAGE(G8_SA(0, 1), a2 + hstep);
;       G8_WAIT_L(8); G8_BAR; G8_WAIT_L(0); G8_MMA(0, 0, At, B0); G8_BAR; G8_SCHED;
;       G8_LDB(B1, 1, 1); G8_STAGE(G8_SB(1, 0), b3);
;       G8_BAR; G8_WAIT_L(0); G8_MMA(0, 1, At, B1); G8_BAR;
;       G8_LDA(At, 1, 1); G8_STAGE(G8_SA(1, 0), a3);
;       G8_BAR; G8_WAIT_L(0); G8_MMA(1, 0, At, B0); G8_BAR; G8_SCHED;
;       G8_STAGE(G8_SB(1, 1), b3 + hstep);
;       G8_WAIT_V(6); G8_BAR; G8_MMA(1, 1, At, B1); G8_BAR;
;     }
	s_waitcnt lgkmcnt(0)
	v_mfma_f32_16x16x32_f16 v[120:123], v[222:225], v[178:181], v[120:123]
	v_mfma_f32_16x16x32_f16 v[116:119], v[230:233], v[178:181], v[116:119]
	v_mfma_f32_16x16x32_f16 v[104:107], v[222:225], v[186:189], v[104:107]
	v_mfma_f32_16x16x32_f16 v[100:103], v[230:233], v[186:189], v[100:103]
	v_mfma_f32_16x16x32_f16 v[88:91], v[222:225], v[206:209], v[88:91]
	v_mfma_f32_16x16x32_f16 v[84:87], v[230:233], v[206:209], v[84:87]
	v_mfma_f32_16x16x32_f16 v[72:75], v[222:225], v[214:217], v[72:75]
	v_mfma_f32_16x16x32_f16 v[68:71], v[230:233], v[214:217], v[68:71]
	v_mfma_f32_16x16x32_f16 v[120:123], v[226:229], v[182:185], v[120:123]
	v_mfma_f32_16x16x32_f16 v[116:119], v[234:237], v[182:185], v[116:119]
	v_mfma_f32_16x16x32_f16 v[104:107], v[226:229], v[202:205], v[104:107]
	v_mfma_f32_16x16x32_f16 v[100:103], v[234:237], v[202:205], v[100:103]
	v_mfma_f32_16x16x32_f16 v[88:91], v[226:229], v[210:213], v[88:91]
	v_mfma_f32_16x16x32_f16 v[84:87], v[234:237], v[210:213], v[84:87]
	v_mfma_f32_16x16x32_f16 v[72:75], v[226:229], v[218:221], v[72:75]
	v_mfma_f32_16x16x32_f16 v[68:71], v[234:237], v[218:221], v[68:71]
	s_mov_b32 m0, s48
	v_lshl_add_u64 v[6:7], v[242:243], 0, s[94:95]
	s_barrier
	ds_read_b128 v[178:181], v139 offset:49152
	ds_read_b128 v[182:185], v139 offset:50176
	ds_read_b128 v[186:189], v139 offset:51200
	ds_read_b128 v[202:205], v139 offset:52224
	ds_read_b128 v[206:209], v139 offset:53248
	ds_read_b128 v[210:213], v139 offset:54272
	ds_read_b128 v[214:217], v139 offset:55296
	ds_read_b128 v[218:221], v139 offset:56320
	global_load_lds_dwordx4 v[6:7], off
	v_lshl_add_u64 v[6:7], v[244:245], 0, s[94:95]
	s_mov_b32 m0, s49
	s_nop 0
	global_load_lds_dwordx4 v[6:7], off
	s_barrier
	s_waitcnt lgkmcnt(0)
	v_mfma_f32_16x16x32_f16 v[64:67], v[162:165], v[178:181], v[64:67]
	v_mfma_f32_16x16x32_f16 v[60:63], v[170:173], v[178:181], v[60:63]
	v_mfma_f32_16x16x32_f16 v[48:51], v[162:165], v[186:189], v[48:51]
	v_mfma_f32_16x16x32_f16 v[44:47], v[170:173], v[186:189], v[44:47]
	v_mfma_f32_16x16x32_f16 v[32:35], v[162:165], v[206:209], v[32:35]
	v_mfma_f32_16x16x32_f16 v[28:31], v[170:173], v[206:209], v[28:31]
	v_mfma_f32_16x16x32_f16 v[16:19], v[162:165], v[214:217], v[16:19]
	v_mfma_f32_16x16x32_f16 v[12:15], v[170:173], v[214:217], v[12:15]
	v_mfma_f32_16x16x32_f16 v[64:67], v[166:169], v[182:185], v[64:67]
	v_mfma_f32_16x16x32_f16 v[60:63], v[174:177], v[182:185], v[60:63]
	v_mfma_f32_16x16x32_f16 v[48:51], v[166:169], v[202:205], v[48:51]
	v_mfma_f32_16x16x32_f16 v[44:47], v[174:177], v[202:205], v[44:47]
	v_mfma_f32_16x16x32_f16 v[32:35], v[166:169], v[210:213], v[32:35]
	v_mfma_f32_16x16x32_f16 v[28:31], v[174:177], v[210:213], v[28:31]
	v_mfma_f32_16x16x32_f16 v[16:19], v[166:169], v[218:221], v[16:19]
	v_mfma_f32_16x16x32_f16 v[12:15], v[174:177], v[218:221], v[12:15]
	s_barrier
	s_add_u32 s26, s26, 0x40080
	s_addc_u32 s27, s27, 0
	s_mov_b32 m0, s50
	v_lshl_add_u64 v[6:7], s[26:27], 0, v[134:135]
	global_load_lds_dwordx4 v[6:7], off
	v_lshl_add_u64 v[6:7], s[26:27], 0, v[132:133]
	s_mov_b32 m0, s51
	s_nop 0
	global_load_lds_dwordx4 v[6:7], off
	s_waitcnt vmcnt(6)
	s_barrier
	v_mfma_f32_16x16x32_f16 v[56:59], v[222:225], v[178:181], v[56:59]
	v_mfma_f32_16x16x32_f16 v[52:55], v[230:233], v[178:181], v[52:55]
	v_mfma_f32_16x16x32_f16 v[40:43], v[222:225], v[186:189], v[40:43]
	v_mfma_f32_16x16x32_f16 v[36:39], v[230:233], v[186:189], v[36:39]
	v_mfma_f32_16x16x32_f16 v[24:27], v[222:225], v[206:209], v[24:27]
	v_mfma_f32_16x16x32_f16 v[20:23], v[230:233], v[206:209], v[20:23]
	v_mfma_f32_16x16x32_f16 v[6:9], v[222:225], v[214:217], v[8:11]
	v_mfma_f32_16x16x32_f16 v[2:5], v[230:233], v[214:217], v[2:5]
	v_mfma_f32_16x16x32_f16 v[56:59], v[226:229], v[182:185], v[56:59]
	v_mfma_f32_16x16x32_f16 v[52:55], v[234:237], v[182:185], v[52:55]
	v_mfma_f32_16x16x32_f16 v[40:43], v[226:229], v[202:205], v[40:43]
	v_mfma_f32_16x16x32_f16 v[36:39], v[234:237], v[202:205], v[36:39]
	v_mfma_f32_16x16x32_f16 v[24:27], v[226:229], v[210:213], v[24:27]
	v_mfma_f32_16x16x32_f16 v[20:23], v[234:237], v[210:213], v[20:23]
	v_mfma_f32_16x16x32_f16 v[8:11], v[226:229], v[218:221], v[6:9]
	v_mfma_f32_16x16x32_f16 v[4:7], v[234:237], v[218:221], v[2:5]
	s_add_i32 s55, s55, 2
	s_add_u32 s24, s24, 0x100
	s_addc_u32 s25, s25, 0
	s_cmp_gt_u32 s55, 13
	s_barrier
	s_cbranch_scc1 .LBB0_2381

; #define G8_STAGE(bufoff, gbase) do { _Pragma("unroll") for (int _i = 0; _i < 2; ++_i) \
;     __builtin_amdgcn_global_load_lds((const unsigned*)((const char*)(gbase) + voffA[_i]), (LAS unsigned*)(lds + (bufoff) + ldsw + _i * 8192), 16, 0, 0); } while (0)
; #define G8_LDA(dst, b, h) do { _Pragma("unroll") for (int m = 0; m < 4; ++m) _Pragma("unroll") for (int k = 0; k < 2; ++k) dst[m][k] = *(const LAS h16x8*)(lds + G8_SA(b, h) + aoff + m * 2048 + k * 1024); } while (0)
; #define G8_LDB(dst, b, h) do { _Pragma("unroll") for (int n = 0; n < 2; ++n) _Pragma("unroll") for (int k = 0; k < 2; ++k) dst[n][k] = *(const LAS h16x8*)(lds + G8_SB(b, h) + boff + n * 2048 + k * 1024); } while (0)
; #define G8_MMA(ai, bj, At, Bt_) do { __builtin_amdgcn_s_setprio(1); _Pragma("unroll") for (int m = 0; m < 4; ++m) _Pragma("unroll") for (int n = 0; n < 2; ++n) _Pragma("unroll") for (int k = 0; k < 2; ++k) \
;     acc[ai][bj][m][n] = __builtin_amdgcn_mfma_f32_16x16x32_f16(Bt_[n][k], At[m][k], acc[ai][bj][m][n], 0, 0, 0); __builtin_amdgcn_s_setprio(0); } while (0)
; #define G8_WAIT_V(n) asm volatile("s_waitcnt vmcnt(" #n ")" ::: "memory")
; #define G8_WAIT_L(n) asm volatile("s_waitcnt lgkmcnt(" #n ")" ::: "memory")
; #define G8_BAR __builtin_amdgcn_s_barrier()
; template <class Epi>
; __device__ __forceinline__ void gemm_phase(LAS unsigned char* lds, const h16* A, const h16* Bt, int K, const Order& S, const Epi& E) {
;     ...
;     for (int t = 0; t < nt; t += 2) {
;       const bool last = (t == nt - 2);
;       const char* a1 = cA + (size_t)(t + 1) * kstep;
;       const char* a2 = last ? nA : cA + (size_t)(t + 2) * kstep;
;       const char* b2 = last ? nB : cB + (size_t)(t + 2) * kstep;
;       const char* a3 = a2 + kstep;
;       const char* b3 = b2 + kstep;
;       if (Epi::MID_T >= 0 && t == Epi::MID_T) E.mid(acc, ui, wr, fr);
;       G8_LDB(B0, 0, 0); G8_SCHED; G8_LDA(At, 0, 0); G8_STAGE(G8_SA(1, 1), a1 + hstep);
;       G8_WAIT_L(8); G8_BAR; G8_WAIT_L(0); G8_MMA(0, 0, At, B0); G8_BAR; G8_SCHED;
;       G8_LDB(B1, 0, 1); G8_STAGE(G8_SB(0, 0), b2);
;       G8_BAR; G8_WAIT_L(0); G8_MMA(0, 1, At, B1); G8_BAR;
;       G8_LDA(At, 0, 1); G8_STAGE(G8_SA(0, 0), a2);
;       G8_BAR; G8_WAIT_L(0); G8_MMA(1, 0, At, B0); G8_BAR; G8_SCHED;
;       G8_STAGE(G8_SB(0, 1), b2 + hstep);
;       G8_WAIT_V(6); G8_BAR; G8_MMA(1, 1, At, B1); G8_BAR;
.LBB0_2473:
	s_add_u32 s20, s18, 0xfffc0080
	s_addc_u32 s21, s19, -1
	s_cmp_eq_u32 s51, 12
	s_cselect_b32 s23, s13, s21
	s_cselect_b32 s22, s47, s20
	s_cselect_b32 s21, s11, s50
	s_cselect_b32 s20, s48, s49
	v_lshl_add_u64 v[188:189], s[18:19], 0, v[134:135]
	s_add_i32 m0, s27, 0xc000
	ds_read_b128 v[176:179], v139
	ds_read_b128 v[180:183], v139 offset:1024
	ds_read_b128 v[184:187], v139 offset:2048
	ds_read_b128 v[202:205], v139 offset:3072
	ds_read_b128 v[206:209], v139 offset:4096
	ds_read_b128 v[210:213], v139 offset:5120
	ds_read_b128 v[214:217], v139 offset:6144
	ds_read_b128 v[218:221], v139 offset:7168
	global_load_lds_dwordx4 v[188:189], off
	v_lshl_add_u64 v[188:189], s[18:19], 0, v[136:137]
	s_add_i32 m0, s27, 0xe000
	s_nop 0
	global_load_lds_dwordx4 v[188:189], off
	s_waitcnt lgkmcnt(8)
	s_barrier
	s_waitcnt lgkmcnt(0)
	v_mfma_f32_16x16x32_f16 v[126:129], v[160:163], v[176:179], v[126:129]
	v_mfma_f32_16x16x32_f16 v[122:125], v[168:171], v[176:179], v[122:125]
	v_mfma_f32_16x16x32_f16 v[110:113], v[160:163], v[184:187], v[110:113]
	v_mfma_f32_16x16x32_f16 v[106:109], v[168:171], v[184:187], v[106:109]
	v_mfma_f32_16x16x32_f16 v[94:97], v[160:163], v[206:209], v[94:97]
	v_mfma_f32_16x16x32_f16 v[90:93], v[168:171], v[206:209], v[90:93]
	v_mfma_f32_16x16x32_f16 v[78:81], v[160:163], v[214:217], v[78:81]
	v_mfma_f32_16x16x32_f16 v[74:77], v[168:171], v[214:217], v[74:77]
	v_mfma_f32_16x16x32_f16 v[126:129], v[164:167], v[180:183], v[126:129]
	v_mfma_f32_16x16x32_f16 v[122:125], v[172:175], v[180:183], v[122:125]
	v_mfma_f32_16x16x32_f16 v[110:113], v[164:167], v[202:205], v[110:113]
	v_mfma_f32_16x16x32_f16 v[106:109], v[172:175], v[202:205], v[106:109]
	v_mfma_f32_16x16x32_f16 v[94:97], v[164:167], v[210:213], v[94:97]
	v_mfma_f32_16x16x32_f16 v[90:93], v[172:175], v[210:213], v[90:93]
	v_mfma_f32_16x16x32_f16 v[78:81], v[164:167], v[218:221], v[78:81]
	v_mfma_f32_16x16x32_f16 v[74:77], v[172:175], v[218:221], v[74:77]
	s_barrier
	v_or_b32_e32 v159, 0x14000, v140
	v_add_u32_e32 v188, 0x14400, v140
	ds_read_b128 v[222:225], v159
	ds_read_b128 v[226:229], v188
	v_add_u32_e32 v159, 0x14800, v140
	v_add_u32_e32 v188, 0x14c00, v140
	s_mov_b32 m0, s28
	ds_read_b128 v[230:233], v159
	ds_read_b128 v[234:237], v188
	v_lshl_add_u64 v[188:189], s[20:21], 0, v[132:133]
	global_load_lds_dwordx4 v[188:189], off
	v_lshl_add_u64 v[238:239], s[20:21], 0, v[130:131]
	s_mov_b32 m0, s29
	s_nop 0
	global_load_lds_dwordx4 v[238:239], off
	s_barrier
	s_waitcnt lgkmcnt(0)
	v_mfma_f32_16x16x32_f16 v[118:121], v[222:225], v[176:179], v[118:121]
	v_mfma_f32_16x16x32_f16 v[114:117], v[230:233], v[176:179], v[114:117]
	v_mfma_f32_16x16x32_f16 v[102:105], v[222:225], v[184:187], v[102:105]
	v_mfma_f32_16x16x32_f16 v[98:101], v[230:233], v[184:187], v[98:101]
	v_mfma_f32_16x16x32_f16 v[86:89], v[222:225], v[206:209], v[86:89]
	v_mfma_f32_16x16x32_f16 v[82:85], v[230:233], v[206:209], v[82:85]
	v_mfma_f32_16x16x32_f16 v[70:73], v[222:225], v[214:217], v[70:73]
	v_mfma_f32_16x16x32_f16 v[66:69], v[230:233], v[214:217], v[66:69]
	v_mfma_f32_16x16x32_f16 v[118:121], v[226:229], v[180:183], v[118:121]
	v_mfma_f32_16x16x32_f16 v[114:117], v[234:237], v[180:183], v[114:117]
	v_mfma_f32_16x16x32_f16 v[102:105], v[226:229], v[202:205], v[102:105]
	v_mfma_f32_16x16x32_f16 v[98:101], v[234:237], v[202:205], v[98:101]
	v_mfma_f32_16x16x32_f16 v[86:89], v[226:229], v[210:213], v[86:89]
	v_mfma_f32_16x16x32_f16 v[82:85], v[234:237], v[210:213], v[82:85]
	v_mfma_f32_16x16x32_f16 v[70:73], v[226:229], v[218:221], v[70:73]
	v_mfma_f32_16x16x32_f16 v[66:69], v[234:237], v[218:221], v[66:69]
	s_mov_b32 m0, s27
	v_lshl_add_u64 v[240:241], s[22:23], 0, v[132:133]
	s_barrier
	ds_read_b128 v[176:179], v139 offset:16384
	ds_read_b128 v[180:183], v139 offset:17408
	ds_read_b128 v[184:187], v139 offset:18432
	ds_read_b128 v[202:205], v139 offset:19456
	ds_read_b128 v[206:209], v139 offset:20480
	ds_read_b128 v[210:213], v139 offset:21504
	ds_read_b128 v[214:217], v139 offset:22528
	ds_read_b128 v[218:221], v139 offset:23552
	global_load_lds_dwordx4 v[240:241], off
	v_lshl_add_u64 v[242:243], s[22:23], 0, v[130:131]
	s_mov_b32 m0, s30
	s_nop 0
	global_load_lds_dwordx4 v[242:243], off
	s_waitcnt vmcnt(10)
	s_barrier
	s_waitcnt lgkmcnt(0)
	v_mfma_f32_16x16x32_f16 v[62:65], v[160:163], v[176:179], v[62:65]
	v_mfma_f32_16x16x32_f16 v[58:61], v[168:171], v[176:179], v[58:61]
	v_mfma_f32_16x16x32_f16 v[46:49], v[160:163], v[184:187], v[46:49]
	v_mfma_f32_16x16x32_f16 v[42:45], v[168:171], v[184:187], v[42:45]
	v_mfma_f32_16x16x32_f16 v[30:33], v[160:163], v[206:209], v[30:33]
	v_mfma_f32_16x16x32_f16 v[26:29], v[168:171], v[206:209], v[26:29]
	v_mfma_f32_16x16x32_f16 v[14:17], v[160:163], v[214:217], v[14:17]
	v_mfma_f32_16x16x32_f16 v[10:13], v[168:171], v[214:217], v[10:13]
	v_mfma_f32_16x16x32_f16 v[62:65], v[164:167], v[180:183], v[62:65]
	v_mfma_f32_16x16x32_f16 v[58:61], v[172:175], v[180:183], v[58:61]
	v_mfma_f32_16x16x32_f16 v[46:49], v[164:167], v[202:205], v[46:49]
	v_mfma_f32_16x16x32_f16 v[42:45], v[172:175], v[202:205], v[42:45]
	v_mfma_f32_16x16x32_f16 v[30:33], v[164:167], v[210:213], v[30:33]
	v_mfma_f32_16x16x32_f16 v[26:29], v[172:175], v[210:213], v[26:29]
	v_mfma_f32_16x16x32_f16 v[14:17], v[164:167], v[218:221], v[14:17]
	v_mfma_f32_16x16x32_f16 v[10:13], v[172:175], v[218:221], v[10:13]
	s_barrier
; #define G8_STAGE(bufoff, gbase) do { _Pragma("unroll") for (int _i = 0; _i < 2; ++_i) \
;     __builtin_amdgcn_global_load_lds((const unsigned*)((const char*)(gbase) + voffA[_i]), (LAS unsigned*)(lds + (bufoff) + ldsw + _i * 8192), 16, 0, 0); } while (0)
; #define G8_LDA(dst, b, h) do { _Pragma("unroll") for (int m = 0; m < 4; ++m) _Pragma("unroll") for (int k = 0; k < 2; ++k) dst[m][k] = *(const LAS h16x8*)(lds + G8_SA(b, h) + aoff + m * 2048 + k * 1024); } while (0)
; #define G8_LDB(dst, b, h) do { _Pragma("unroll") for (int n = 0; n < 2; ++n) _Pragma("unroll") for (int k = 0; k < 2; ++k) dst[n][k] = *(const LAS h16x8*)(lds + G8_SB(b, h) + boff + n * 2048 + k * 1024); } while (0)
; #define G8_MMA(ai, bj, At, Bt_) do { __builtin_amdgcn_s_setprio(1); _Pragma("unroll") for (int m = 0; m < 4; ++m) _Pragma("unroll") for (int n = 0; n < 2; ++n) _Pragma("unroll") for (int k = 0; k < 2; ++k) \
;     acc[ai][bj][m][n] = __builtin_amdgcn_mfma_f32_16x16x32_f16(Bt_[n][k], At[m][k], acc[ai][bj][m][n], 0, 0, 0); __builtin_amdgcn_s_setprio(0); } while (0)
; #define G8_WAIT_V(n) asm volatile("s_waitcnt vmcnt(" #n ")" ::: "memory")
; #define G8_WAIT_L(n) asm volatile("s_waitcnt lgkmcnt(" #n ")" ::: "memory")
; #define G8_BAR __builtin_amdgcn_s_barrier()
; #define G8_SCHED __builtin_amdgcn_sched_barrier(0)
; template <class Epi>
; __device__ __forceinline__ void gemm_phase(LAS unsigned char* lds, const h16* A, const h16* Bt, int K, const Order& S, const Epi& E) {
;     ...
;       G8_STAGE(G8_SB(0, 1), b2 + hstep);
;       G8_WAIT_V(6); G8_BAR; G8_MMA(1, 1, At, B1); G8_BAR;
;       G8_LDB(B0, 1, 0); G8_SCHED; G8_LDA(At, 1, 0); G8_STAGE(G8_SA(0, 1), a2 + hstep);
;       G8_WAIT_L(8); G8_BAR; G8_WAIT_L(0); G8_MMA(0, 0, At, B0); G8_BAR; G8_SCHED;
;       G8_LDB(B1, 1, 1); G8_STAGE(G8_SB(1, 0), b3);
;       G8_BAR; G8_WAIT_L(0); G8_MMA(0, 1, At, B1); G8_BAR;
;       G8_LDA(At, 1, 1); G8_STAGE(G8_SA(1, 0), a3);
;       G8_BAR; G8_WAIT_L(0); G8_MMA(1, 0, At, B0); G8_BAR; G8_SCHED;
;       G8_STAGE(G8_SB(1, 1), b3 + hstep);
;       G8_WAIT_V(6); G8_BAR; G8_MMA(1, 1, At, B1); G8_BAR;
	s_add_u32 s52, s20, 0x40000
	s_addc_u32 s53, s21, 0
	s_mov_b32 m0, s31
	v_lshl_add_u64 v[160:161], s[52:53], 0, v[132:133]
	global_load_lds_dwordx4 v[160:161], off
	v_lshl_add_u64 v[160:161], s[52:53], 0, v[130:131]
	s_mov_b32 m0, s34
	s_nop 0
	global_load_lds_dwordx4 v[160:161], off
	v_or_b32_e32 v159, 0x18000, v140
	v_add_u32_e32 v164, 0x18400, v140
	ds_read_b128 v[160:163], v159
	ds_read_b128 v[164:167], v164
	v_add_u32_e32 v159, 0x18800, v140
	v_add_u32_e32 v172, 0x18c00, v140
	ds_read_b128 v[168:171], v159
	ds_read_b128 v[172:175], v172
	s_waitcnt vmcnt(6)
	s_barrier
	v_mfma_f32_16x16x32_f16 v[54:57], v[222:225], v[176:179], v[54:57]
	v_mfma_f32_16x16x32_f16 v[50:53], v[230:233], v[176:179], v[50:53]
	v_mfma_f32_16x16x32_f16 v[38:41], v[222:225], v[184:187], v[38:41]
	v_mfma_f32_16x16x32_f16 v[34:37], v[230:233], v[184:187], v[34:37]
	v_mfma_f32_16x16x32_f16 v[22:25], v[222:225], v[206:209], v[22:25]
	v_mfma_f32_16x16x32_f16 v[18:21], v[230:233], v[206:209], v[18:21]
	v_mfma_f32_16x16x32_f16 v[6:9], v[222:225], v[214:217], v[6:9]
	v_mfma_f32_16x16x32_f16 v[2:5], v[230:233], v[214:217], v[2:5]
	v_mfma_f32_16x16x32_f16 v[54:57], v[226:229], v[180:183], v[54:57]
	v_mfma_f32_16x16x32_f16 v[50:53], v[234:237], v[180:183], v[50:53]
	v_mfma_f32_16x16x32_f16 v[38:41], v[226:229], v[202:205], v[38:41]
	v_mfma_f32_16x16x32_f16 v[34:37], v[234:237], v[202:205], v[34:37]
	v_mfma_f32_16x16x32_f16 v[22:25], v[226:229], v[210:213], v[22:25]
	v_mfma_f32_16x16x32_f16 v[18:21], v[234:237], v[210:213], v[18:21]
	v_mfma_f32_16x16x32_f16 v[6:9], v[226:229], v[218:221], v[6:9]
	v_mfma_f32_16x16x32_f16 v[2:5], v[234:237], v[218:221], v[2:5]
	s_barrier
	s_add_u32 s22, s22, 0x40000
	s_addc_u32 s23, s23, 0
	s_mov_b32 m0, s35
	v_lshl_add_u64 v[222:223], s[22:23], 0, v[132:133]
	ds_read_b128 v[176:179], v139 offset:32768
	ds_read_b128 v[180:183], v139 offset:33792
	ds_read_b128 v[184:187], v139 offset:34816
	ds_read_b128 v[202:205], v139 offset:35840
	ds_read_b128 v[206:209], v139 offset:36864
	ds_read_b128 v[210:213], v139 offset:37888
	ds_read_b128 v[214:217], v139 offset:38912
	ds_read_b128 v[218:221], v139 offset:39936
	global_load_lds_dwordx4 v[222:223], off
	v_lshl_add_u64 v[222:223], s[22:23], 0, v[130:131]
	s_mov_b32 m0, s36
	s_nop 0
	global_load_lds_dwordx4 v[222:223], off
	s_waitcnt lgkmcnt(8)
	s_barrier
	s_waitcnt lgkmcnt(0)
	v_mfma_f32_16x16x32_f16 v[126:129], v[160:163], v[176:179], v[126:129]
	v_mfma_f32_16x16x32_f16 v[122:125], v[168:171], v[176:179], v[122:125]
	v_mfma_f32_16x16x32_f16 v[110:113], v[160:163], v[184:187], v[110:113]
	v_mfma_f32_16x16x32_f16 v[106:109], v[168:171], v[184:187], v[106:109]
	v_mfma_f32_16x16x32_f16 v[94:97], v[160:163], v[206:209], v[94:97]
	v_mfma_f32_16x16x32_f16 v[90:93], v[168:171], v[206:209], v[90:93]
	v_mfma_f32_16x16x32_f16 v[78:81], v[160:163], v[214:217], v[78:81]
	v_mfma_f32_16x16x32_f16 v[74:77], v[168:171], v[214:217], v[74:77]
	v_mfma_f32_16x16x32_f16 v[126:129], v[164:167], v[180:183], v[126:129]
	v_mfma_f32_16x16x32_f16 v[122:125], v[172:175], v[180:183], v[122:125]
	v_mfma_f32_16x16x32_f16 v[110:113], v[164:167], v[202:205], v[110:113]
	v_mfma_f32_16x16x32_f16 v[106:109], v[172:175], v[202:205], v[106:109]
	v_mfma_f32_16x16x32_f16 v[94:97], v[164:167], v[210:213], v[94:97]
	v_mfma_f32_16x16x32_f16 v[90:93], v[172:175], v[210:213], v[90:93]
	v_mfma_f32_16x16x32_f16 v[78:81], v[164:167], v[218:221], v[78:81]
	v_mfma_f32_16x16x32_f16 v[74:77], v[172:175], v[218:221], v[74:77]
	s_barrier
	v_or_b32_e32 v159, 0x1c000, v140
	s_mov_b32 m0, s37
	v_add_u32_e32 v195, 0x1c400, v140
	ds_read_b128 v[222:225], v159
	ds_read_b128 v[226:229], v195
	v_add_u32_e32 v159, 0x1c800, v140
	v_lshl_add_u64 v[188:189], v[188:189], 0, s[94:95]
	v_add_u32_e32 v195, 0x1cc00, v140
	ds_read_b128 v[230:233], v159
	ds_read_b128 v[234:237], v195
	global_load_lds_dwordx4 v[188:189], off
	v_lshl_add_u64 v[188:189], v[238:239], 0, s[94:95]
	s_mov_b32 m0, s38
	s_nop 0
	global_load_lds_dwordx4 v[188:189], off
	s_barrier
	s_waitcnt lgkmcnt(0)
	v_mfma_f32_16x16x32_f16 v[118:121], v[222:225], v[176:179], v[118:121]
	v_mfma_f32_16x16x32_f16 v[114:117], v[230:233], v[176:179], v[114:117]
	v_mfma_f32_16x16x32_f16 v[102:105], v[222:225], v[184:187], v[102:105]
	v_mfma_f32_16x16x32_f16 v[98:101], v[230:233], v[184:187], v[98:101]
	v_mfma_f32_16x16x32_f16 v[86:89], v[222:225], v[206:209], v[86:89]
	v_mfma_f32_16x16x32_f16 v[82:85], v[230:233], v[206:209], v[82:85]
	v_mfma_f32_16x16x32_f16 v[70:73], v[222:225], v[214:217], v[70:73]
	v_mfma_f32_16x16x32_f16 v[66:69], v[230:233], v[214:217], v[66:69]
	v_mfma_f32_16x16x32_f16 v[118:121], v[226:229], v[180:183], v[118:121]
	v_mfma_f32_16x16x32_f16 v[114:117], v[234:237], v[180:183], v[114:117]
	v_mfma_f32_16x16x32_f16 v[102:105], v[226:229], v[202:205], v[102:105]
	v_mfma_f32_16x16x32_f16 v[98:101], v[234:237], v[202:205], v[98:101]
	v_mfma_f32_16x16x32_f16 v[86:89], v[226:229], v[210:213], v[86:89]
	v_mfma_f32_16x16x32_f16 v[82:85], v[234:237], v[210:213], v[82:85]
	v_mfma_f32_16x16x32_f16 v[70:73], v[226:229], v[218:221], v[70:73]
	v_mfma_f32_16x16x32_f16 v[66:69], v[234:237], v[218:221], v[66:69]
	s_mov_b32 m0, s39
	v_lshl_add_u64 v[188:189], v[240:241], 0, s[94:95]
	s_barrier
	ds_read_b128 v[176:179], v139 offset:49152
	ds_read_b128 v[180:183], v139 offset:50176
	ds_read_b128 v[184:187], v139 offset:51200
	ds_read_b128 v[202:205], v139 offset:52224
	ds_read_b128 v[206:209], v139 offset:53248
	ds_read_b128 v[210:213], v139 offset:54272
	ds_read_b128 v[214:217], v139 offset:55296
	ds_read_b128 v[218:221], v139 offset:56320
	global_load_lds_dwordx4 v[188:189], off
	v_lshl_add_u64 v[188:189], v[242:243], 0, s[94:95]
	s_mov_b32 m0, s40
	s_nop 0
	global_load_lds_dwordx4 v[188:189], off
	s_waitcnt vmcnt(10)
	s_barrier
; #define G8_STAGE(bufoff, gbase) do { _Pragma("unroll") for (int _i = 0; _i < 2; ++_i) \
;     __builtin_amdgcn_global_load_lds((const unsigned*)((const char*)(gbase) + voffA[_i]), (LAS unsigned*)(lds + (bufoff) + ldsw + _i * 8192), 16, 0, 0); } while (0)
; #define G8_LDA(dst, b, h) do { _Pragma("unroll") for (int m = 0; m < 4; ++m) _Pragma("unroll") for (int k = 0; k < 2; ++k) dst[m][k] = *(const LAS h16x8*)(lds + G8_SA(b, h) + aoff + m * 2048 + k * 1024); } while (0)
; #define G8_LDB(dst, b, h) do { _Pragma("unroll") for (int n = 0; n < 2; ++n) _Pragma("unroll") for (int k = 0; k < 2; ++k) dst[n][k] = *(const LAS h16x8*)(lds + G8_SB(b, h) + boff + n * 2048 + k * 1024); } while (0)
; #define G8_WAIT_V(n) asm volatile("s_waitcnt vmcnt(" #n ")" ::: "memory")
; #define G8_WAIT_L(n) asm volatile("s_waitcnt lgkmcnt(" #n ")" ::: "memory")
; #define G8_BAR __builtin_amdgcn_s_barrier()
; #define G8_SCHED __builtin_amdgcn_sched_barrier(0)
; template <class Epi>
; __device__ __forceinline__ void gemm_phase(LAS unsigned char* lds, const h16* A, const h16* Bt, int K, const Order& S, const Epi& E) {
;     ...
;       G8_WAIT_L(8); G8_BAR; G8_WAIT_L(0); G8_MMA(0, 0, At, B0); G8_BAR; G8_SCHED;
;       G8_LDB(B1, 1, 1); G8_STAGE(G8_SB(1, 0), b3);
;       G8_BAR; G8_WAIT_L(0); G8_MMA(0, 1, At, B1); G8_BAR;
;       G8_LDA(At, 1, 1); G8_STAGE(G8_SA(1, 0), a3);
;       G8_BAR; G8_WAIT_L(0); G8_MMA(1, 0, At, B0); G8_BAR; G8_SCHED;
;       G8_STAGE(G8_SB(1, 1), b3 + hstep);
;       G8_WAIT_V(6); G8_BAR; G8_MMA(1, 1, At, B1); G8_BAR;
;     }
;   __device__ __forceinline__ void operator()(const f32x4 (&acc)[2][2][4][2], const g8::Unit& u, int ui, int wr, int wc, int fr, int fq) const {
; #pragma unroll
;     for (int ai = 0; ai < 2; ++ai)
; #pragma unroll
;       for (int m = 0; m < 4; ++m) {
;         const int rl = 128 * ai + 64 * wr + 16 * m + fr;
;         const float r = rsl[ui * 256 + rl];
;         h16* rowp = hid + (size_t)(u.pm * 256 + rl) * DFF + 256 * u.pn + 32 * wc + 8 * fq;
; #pragma unroll
;         for (int bj = 0; bj < 2; ++bj) {
;           f32x4 v[2];
; #pragma unroll
;           for (int n = 0; n < 2; ++n) {
;             v[n] = acc[ai][bj][m][n] * r;
; #pragma unroll
;             for (int j = 0; j < 4; ++j) { const float t = fmaxf(v[n][j], 0.f); v[n][j] = t * t; }
;           }
;           __builtin_nontemporal_store(pack8(v[0], v[1]), (h16x8*)(rowp + 128 * bj));
	s_waitcnt lgkmcnt(0)
	v_mfma_f32_16x16x32_f16 v[62:65], v[160:163], v[176:179], v[62:65]
	v_mfma_f32_16x16x32_f16 v[58:61], v[168:171], v[176:179], v[58:61]
	v_mfma_f32_16x16x32_f16 v[46:49], v[160:163], v[184:187], v[46:49]
	v_mfma_f32_16x16x32_f16 v[42:45], v[168:171], v[184:187], v[42:45]
	v_mfma_f32_16x16x32_f16 v[30:33], v[160:163], v[206:209], v[30:33]
	v_mfma_f32_16x16x32_f16 v[26:29], v[168:171], v[206:209], v[26:29]
	v_mfma_f32_16x16x32_f16 v[14:17], v[160:163], v[214:217], v[14:17]
	v_mfma_f32_16x16x32_f16 v[10:13], v[168:171], v[214:217], v[10:13]
	v_mfma_f32_16x16x32_f16 v[62:65], v[164:167], v[180:183], v[62:65]
	v_mfma_f32_16x16x32_f16 v[58:61], v[172:175], v[180:183], v[58:61]
	v_mfma_f32_16x16x32_f16 v[46:49], v[164:167], v[202:205], v[46:49]
	v_mfma_f32_16x16x32_f16 v[42:45], v[172:175], v[202:205], v[42:45]
	v_mfma_f32_16x16x32_f16 v[30:33], v[164:167], v[210:213], v[30:33]
	v_mfma_f32_16x16x32_f16 v[26:29], v[172:175], v[210:213], v[26:29]
	v_mfma_f32_16x16x32_f16 v[14:17], v[164:167], v[218:221], v[14:17]
	v_mfma_f32_16x16x32_f16 v[10:13], v[172:175], v[218:221], v[10:13]
	s_barrier
	s_add_u32 s20, s20, 0x40080
	s_addc_u32 s21, s21, 0
	s_mov_b32 m0, s41
	v_lshl_add_u64 v[160:161], s[20:21], 0, v[132:133]
	global_load_lds_dwordx4 v[160:161], off
	v_lshl_add_u64 v[160:161], s[20:21], 0, v[130:131]
	s_mov_b32 m0, s42
	s_nop 0
	global_load_lds_dwordx4 v[160:161], off
	v_or_b32_e32 v159, 0x10000, v140
	v_add_u32_e32 v164, 0x10400, v140
	ds_read_b128 v[160:163], v159
	ds_read_b128 v[164:167], v164
	v_add_u32_e32 v159, 0x10800, v140
	v_add_u32_e32 v172, 0x10c00, v140
	ds_read_b128 v[168:171], v159
	ds_read_b128 v[172:175], v172
	s_waitcnt vmcnt(6)
	s_barrier
	v_mfma_f32_16x16x32_f16 v[54:57], v[222:225], v[176:179], v[54:57]
	v_mfma_f32_16x16x32_f16 v[50:53], v[230:233], v[176:179], v[50:53]
	v_mfma_f32_16x16x32_f16 v[38:41], v[222:225], v[184:187], v[38:41]
	v_mfma_f32_16x16x32_f16 v[34:37], v[230:233], v[184:187], v[34:37]
	v_mfma_f32_16x16x32_f16 v[22:25], v[222:225], v[206:209], v[22:25]
	v_mfma_f32_16x16x32_f16 v[18:21], v[230:233], v[206:209], v[18:21]
	v_mfma_f32_16x16x32_f16 v[6:9], v[222:225], v[214:217], v[6:9]
	v_mfma_f32_16x16x32_f16 v[2:5], v[230:233], v[214:217], v[2:5]
	v_mfma_f32_16x16x32_f16 v[54:57], v[226:229], v[180:183], v[54:57]
	v_mfma_f32_16x16x32_f16 v[50:53], v[234:237], v[180:183], v[50:53]
	v_mfma_f32_16x16x32_f16 v[38:41], v[226:229], v[202:205], v[38:41]
	v_mfma_f32_16x16x32_f16 v[34:37], v[234:237], v[202:205], v[34:37]
	v_mfma_f32_16x16x32_f16 v[22:25], v[226:229], v[210:213], v[22:25]
	v_mfma_f32_16x16x32_f16 v[18:21], v[234:237], v[210:213], v[18:21]
	v_mfma_f32_16x16x32_f16 v[6:9], v[226:229], v[218:221], v[6:9]
	v_mfma_f32_16x16x32_f16 v[2:5], v[234:237], v[218:221], v[2:5]
	s_add_i32 s51, s51, 2
	s_add_u32 s18, s18, 0x100
	s_addc_u32 s19, s19, 0
	s_add_u32 s49, s49, 0x100
	s_addc_u32 s50, s50, 0
	s_cmp_gt_u32 s51, 13
	s_barrier
	s_cbranch_scc0 .LBB0_2473
	s_waitcnt lgkmcnt(0)
	v_lshl_add_u32 v159, s44, 10, v158
	s_waitcnt vmcnt(0)
	ds_read2_b32 v[160:161], v159 offset1:16
	s_lshl_b32 s11, s46, 8
	v_add_u32_e32 v162, s11, v138
	s_lshl_b32 s18, s45, 8
	v_ashrrev_i32_e32 v163, 31, v162
	s_waitcnt lgkmcnt(0)
	v_pk_mul_f32 v[128:129], v[128:129], v[160:161] op_sel_hi:[1,0]
	v_pk_mul_f32 v[126:127], v[126:127], v[160:161] op_sel_hi:[1,0]
	v_pk_mul_f32 v[122:123], v[122:123], v[160:161] op_sel_hi:[1,0]
	v_max_f32_e32 v166, 0, v126
	v_max_f32_e32 v126, 0, v127
	v_max_f32_e32 v127, 0, v128
	v_max_f32_e32 v128, 0, v129
	v_pk_mul_f32 v[124:125], v[124:125], v[160:161] op_sel_hi:[1,0]
	v_max_f32_e32 v129, 0, v122
	v_max_f32_e32 v164, 0, v123
	v_pk_mul_f32 v[122:123], v[126:127], v[126:127]
	v_max_f32_e32 v165, 0, v124
	v_fma_mixlo_f16 v124, v166, v166, 0
	v_cvt_pk_f16_f32 v123, v122, v123
	s_ashr_i32 s19, s18, 31
	v_lshlrev_b64 v[162:163], 13, v[162:163]
	v_max_f32_e32 v167, 0, v125
	v_pack_b32_f16 v122, v124, v123
	v_pk_mul_f32 v[124:125], v[128:129], v[128:129]
	v_lshl_add_u64 v[162:163], s[0:1], 0, v[162:163]
	s_lshl_b64 s[18:19], s[18:19], 1
	v_cvt_pk_f16_f32 v126, v124, v125
	v_pk_mul_f32 v[124:125], v[164:165], v[164:165]
	v_lshl_add_u64 v[162:163], v[162:163], 0, s[18:19]
	v_cvt_pk_f16_f32 v125, v124, v125
	v_lshl_add_u64 v[162:163], v[162:163], 0, s[92:93]
	v_alignbit_b32 v124, v125, v126, 16
	v_lshrrev_b32_e32 v125, 16, v125
	v_lshl_add_u64 v[162:163], v[162:163], 0, v[0:1]
	v_alignbit_b32 v123, v126, v123, 16
	v_fma_mixhi_f16 v125, v167, v167, 0
	v_pk_mul_f32 v[120:121], v[120:121], v[160:161] op_sel_hi:[1,0]
	v_pk_mul_f32 v[118:119], v[118:119], v[160:161] op_sel_hi:[1,0]
	global_store_dwordx4 v[162:163], v[122:125], off nt
	v_pk_mul_f32 v[114:115], v[114:115], v[160:161] op_sel_hi:[1,0]
	v_pk_mul_f32 v[116:117], v[116:117], v[160:161] op_sel_hi:[1,0]
	v_max_f32_e32 v124, 0, v118
	v_max_f32_e32 v118, 0, v119
	v_max_f32_e32 v119, 0, v120
	v_max_f32_e32 v120, 0, v121
	v_max_f32_e32 v121, 0, v114
	v_max_f32_e32 v122, 0, v115
	v_pk_mul_f32 v[114:115], v[118:119], v[118:119]
	v_max_f32_e32 v123, 0, v116
	v_fma_mixlo_f16 v116, v124, v124, 0
	v_cvt_pk_f16_f32 v115, v114, v115
	v_max_f32_e32 v125, 0, v117
	v_pack_b32_f16 v114, v116, v115
	v_pk_mul_f32 v[116:117], v[120:121], v[120:121]
	s_and_b64 vcc, exec, s[6:7]
	v_cvt_pk_f16_f32 v118, v116, v117
	v_pk_mul_f32 v[116:117], v[122:123], v[122:123]
	v_alignbit_b32 v115, v118, v115, 16
	v_cvt_pk_f16_f32 v117, v116, v117
	v_alignbit_b32 v116, v117, v118, 16
	v_lshrrev_b32_e32 v117, 16, v117
	v_fma_mixhi_f16 v117, v125, v125, 0
	global_store_dwordx4 v[162:163], v[114:117], off offset:256 nt
	s_mov_b32 s45, s10
	s_mov_b32 s46, s12
	v_mov_b32_e32 v116, v161
;   __device__ __forceinline__ void operator()(const f32x4 (&acc)[2][2][4][2], const g8::Unit& u, int ui, int wr, int wc, int fr, int fq) const {
; #pragma unroll
;     for (int ai = 0; ai < 2; ++ai)
; #pragma unroll
;       for (int m = 0; m < 4; ++m) {
;         const int rl = 128 * ai + 64 * wr + 16 * m + fr;
;         const float r = rsl[ui * 256 + rl];
;         h16* rowp = hid + (size_t)(u.pm * 256 + rl) * DFF + 256 * u.pn + 32 * wc + 8 * fq;
; #pragma unroll
;         for (int bj = 0; bj < 2; ++bj) {
;           f32x4 v[2];
; #pragma unroll
;           for (int n = 0; n < 2; ++n) {
;             v[n] = acc[ai][bj][m][n] * r;
; #pragma unroll
;             for (int j = 0; j < 4; ++j) { const float t = fmaxf(v[n][j], 0.f); v[n][j] = t * t; }
;           }
;           __builtin_nontemporal_store(pack8(v[0], v[1]), (h16x8*)(rowp + 128 * bj));
;         }
;       }
	v_pk_mul_f32 v[110:111], v[110:111], v[116:117] op_sel_hi:[1,0]
	v_pk_mul_f32 v[112:113], v[112:113], v[116:117] op_sel_hi:[1,0]
	v_max_f32_e32 v117, 0, v110
	v_max_f32_e32 v110, 0, v111
	v_max_f32_e32 v111, 0, v112
	v_pk_mul_f32 v[106:107], v[106:107], v[116:117] op_sel_hi:[1,0]
	v_add_u32_e32 v114, s11, v141
	v_max_f32_e32 v112, 0, v113
	v_pk_mul_f32 v[108:109], v[108:109], v[116:117] op_sel_hi:[1,0]
	v_max_f32_e32 v113, 0, v106
	v_max_f32_e32 v118, 0, v107
	v_pk_mul_f32 v[106:107], v[110:111], v[110:111]
	v_ashrrev_i32_e32 v115, 31, v114
	v_max_f32_e32 v119, 0, v108
	v_fma_mixlo_f16 v108, v117, v117, 0
	v_cvt_pk_f16_f32 v107, v106, v107
	v_lshlrev_b64 v[114:115], 13, v[114:115]
	v_max_f32_e32 v120, 0, v109
	v_pack_b32_f16 v106, v108, v107
	v_pk_mul_f32 v[108:109], v[112:113], v[112:113]
	v_lshl_add_u64 v[114:115], s[0:1], 0, v[114:115]
	v_cvt_pk_f16_f32 v110, v108, v109
	v_pk_mul_f32 v[108:109], v[118:119], v[118:119]
	v_lshl_add_u64 v[114:115], v[114:115], 0, s[18:19]
	v_cvt_pk_f16_f32 v109, v108, v109
	v_lshl_add_u64 v[114:115], v[114:115], 0, s[92:93]
	v_alignbit_b32 v108, v109, v110, 16
	v_lshrrev_b32_e32 v109, 16, v109
	v_lshl_add_u64 v[114:115], v[114:115], 0, v[0:1]
	v_alignbit_b32 v107, v110, v107, 16
	v_fma_mixhi_f16 v109, v120, v120, 0
	v_pk_mul_f32 v[104:105], v[104:105], v[116:117] op_sel_hi:[1,0]
	v_pk_mul_f32 v[102:103], v[102:103], v[116:117] op_sel_hi:[1,0]
	global_store_dwordx4 v[114:115], v[106:109], off nt
	v_pk_mul_f32 v[98:99], v[98:99], v[116:117] op_sel_hi:[1,0]
	v_pk_mul_f32 v[100:101], v[100:101], v[116:117] op_sel_hi:[1,0]
	v_max_f32_e32 v108, 0, v102
	v_max_f32_e32 v102, 0, v103
	v_max_f32_e32 v103, 0, v104
	v_max_f32_e32 v104, 0, v105
	v_max_f32_e32 v105, 0, v98
	v_max_f32_e32 v106, 0, v99
	v_pk_mul_f32 v[98:99], v[102:103], v[102:103]
	v_max_f32_e32 v107, 0, v100
	v_fma_mixlo_f16 v100, v108, v108, 0
	v_cvt_pk_f16_f32 v99, v98, v99
	v_max_f32_e32 v109, 0, v101
	v_pack_b32_f16 v98, v100, v99
	v_pk_mul_f32 v[100:101], v[104:105], v[104:105]
	s_mov_b64 s[20:21], s[16:17]
	v_cvt_pk_f16_f32 v102, v100, v101
	v_pk_mul_f32 v[100:101], v[106:107], v[106:107]
	v_alignbit_b32 v99, v102, v99, 16
	v_cvt_pk_f16_f32 v101, v100, v101
	v_alignbit_b32 v100, v101, v102, 16
	v_lshrrev_b32_e32 v101, 16, v101
	v_fma_mixhi_f16 v101, v109, v109, 0
	global_store_dwordx4 v[114:115], v[98:101], off offset:256 nt
	ds_read2_b32 v[98:99], v159 offset0:32 offset1:48
	s_mov_b32 s44, s43
	v_add_u32_e32 v100, s11, v152
	v_ashrrev_i32_e32 v101, 31, v100
	v_lshlrev_b64 v[100:101], 13, v[100:101]
	s_waitcnt lgkmcnt(0)
	v_pk_mul_f32 v[96:97], v[96:97], v[98:99] op_sel_hi:[1,0]
	v_pk_mul_f32 v[94:95], v[94:95], v[98:99] op_sel_hi:[1,0]
	v_pk_mul_f32 v[90:91], v[90:91], v[98:99] op_sel_hi:[1,0]
	v_max_f32_e32 v104, 0, v94
	v_max_f32_e32 v94, 0, v95
	v_max_f32_e32 v95, 0, v96
	v_max_f32_e32 v96, 0, v97
	v_pk_mul_f32 v[92:93], v[92:93], v[98:99] op_sel_hi:[1,0]
	v_max_f32_e32 v97, 0, v90
	v_max_f32_e32 v102, 0, v91
	v_pk_mul_f32 v[90:91], v[94:95], v[94:95]
	v_max_f32_e32 v103, 0, v92
	v_fma_mixlo_f16 v92, v104, v104, 0
	v_cvt_pk_f16_f32 v91, v90, v91
	v_max_f32_e32 v105, 0, v93
	v_pack_b32_f16 v90, v92, v91
	v_pk_mul_f32 v[92:93], v[96:97], v[96:97]
	v_lshl_add_u64 v[100:101], s[0:1], 0, v[100:101]
	v_cvt_pk_f16_f32 v94, v92, v93
	v_pk_mul_f32 v[92:93], v[102:103], v[102:103]
	v_lshl_add_u64 v[100:101], v[100:101], 0, s[18:19]
	v_cvt_pk_f16_f32 v93, v92, v93
	v_lshl_add_u64 v[100:101], v[100:101], 0, s[92:93]
	v_alignbit_b32 v92, v93, v94, 16
	v_lshrrev_b32_e32 v93, 16, v93
	v_lshl_add_u64 v[100:101], v[100:101], 0, v[0:1]
	v_alignbit_b32 v91, v94, v91, 16
	v_fma_mixhi_f16 v93, v105, v105, 0
	v_pk_mul_f32 v[88:89], v[88:89], v[98:99] op_sel_hi:[1,0]
	v_pk_mul_f32 v[86:87], v[86:87], v[98:99] op_sel_hi:[1,0]
	global_store_dwordx4 v[100:101], v[90:93], off nt
	v_pk_mul_f32 v[82:83], v[82:83], v[98:99] op_sel_hi:[1,0]
	v_pk_mul_f32 v[84:85], v[84:85], v[98:99] op_sel_hi:[1,0]
	v_max_f32_e32 v92, 0, v86
	v_max_f32_e32 v86, 0, v87
	v_max_f32_e32 v87, 0, v88
	v_max_f32_e32 v88, 0, v89
	v_max_f32_e32 v89, 0, v82
	v_max_f32_e32 v90, 0, v83
	v_pk_mul_f32 v[82:83], v[86:87], v[86:87]
	v_max_f32_e32 v91, 0, v84
	v_fma_mixlo_f16 v84, v92, v92, 0
	v_cvt_pk_f16_f32 v83, v82, v83
	v_max_f32_e32 v93, 0, v85
	v_pack_b32_f16 v82, v84, v83
	v_pk_mul_f32 v[84:85], v[88:89], v[88:89]
	s_nop 0
	v_cvt_pk_f16_f32 v86, v84, v85
	v_pk_mul_f32 v[84:85], v[90:91], v[90:91]
	v_alignbit_b32 v83, v86, v83, 16
	v_cvt_pk_f16_f32 v85, v84, v85
	v_alignbit_b32 v84, v85, v86, 16
	v_lshrrev_b32_e32 v85, 16, v85
	v_fma_mixhi_f16 v85, v93, v93, 0
	global_store_dwordx4 v[100:101], v[82:85], off offset:256 nt
	s_nop 1
	v_mov_b32_e32 v84, v99
	v_pk_mul_f32 v[78:79], v[78:79], v[84:85] op_sel_hi:[1,0]
	v_pk_mul_f32 v[80:81], v[80:81], v[84:85] op_sel_hi:[1,0]
	v_max_f32_e32 v85, 0, v78
	v_max_f32_e32 v78, 0, v79
	v_max_f32_e32 v79, 0, v80
	v_pk_mul_f32 v[74:75], v[74:75], v[84:85] op_sel_hi:[1,0]
	v_add_u32_e32 v82, s11, v153
	v_max_f32_e32 v80, 0, v81
	v_pk_mul_f32 v[76:77], v[76:77], v[84:85] op_sel_hi:[1,0]
	v_max_f32_e32 v81, 0, v74
	v_max_f32_e32 v86, 0, v75
	v_pk_mul_f32 v[74:75], v[78:79], v[78:79]
	v_ashrrev_i32_e32 v83, 31, v82
	v_max_f32_e32 v87, 0, v76
	v_fma_mixlo_f16 v76, v85, v85, 0
	v_cvt_pk_f16_f32 v75, v74, v75
	v_lshlrev_b64 v[82:83], 13, v[82:83]
	v_max_f32_e32 v88, 0, v77
	v_pack_b32_f16 v74, v76, v75
	v_pk_mul_f32 v[76:77], v[80:81], v[80:81]
	v_lshl_add_u64 v[82:83], s[0:1], 0, v[82:83]
	v_cvt_pk_f16_f32 v78, v76, v77
	v_pk_mul_f32 v[76:77], v[86:87], v[86:87]
	v_lshl_add_u64 v[82:83], v[82:83], 0, s[18:19]
	v_cvt_pk_f16_f32 v77, v76, v77
	v_lshl_add_u64 v[82:83], v[82:83], 0, s[92:93]
	v_alignbit_b32 v76, v77, v78, 16
	v_lshrrev_b32_e32 v77, 16, v77
	v_lshl_add_u64 v[82:83], v[82:83], 0, v[0:1]
	v_alignbit_b32 v75, v78, v75, 16
	v_fma_mixhi_f16 v77, v88, v88, 0
	v_pk_mul_f32 v[72:73], v[72:73], v[84:85] op_sel_hi:[1,0]
	v_pk_mul_f32 v[70:71], v[70:71], v[84:85] op_sel_hi:[1,0]
	global_store_dwordx4 v[82:83], v[74:77], off nt
	v_pk_mul_f32 v[66:67], v[66:67], v[84:85] op_sel_hi:[1,0]
	v_pk_mul_f32 v[68:69], v[68:69], v[84:85] op_sel_hi:[1,0]
	v_max_f32_e32 v76, 0, v70
	v_max_f32_e32 v70, 0, v71
	v_max_f32_e32 v71, 0, v72
	v_max_f32_e32 v72, 0, v73
	v_max_f32_e32 v73, 0, v66
	v_max_f32_e32 v74, 0, v67
	v_pk_mul_f32 v[66:67], v[70:71], v[70:71]
	v_max_f32_e32 v75, 0, v68
	v_fma_mixlo_f16 v68, v76, v76, 0
	v_cvt_pk_f16_f32 v67, v66, v67
	v_max_f32_e32 v77, 0, v69
	v_pack_b32_f16 v66, v68, v67
	v_pk_mul_f32 v[68:69], v[72:73], v[72:73]
	s_nop 0
	v_cvt_pk_f16_f32 v70, v68, v69
	v_pk_mul_f32 v[68:69], v[74:75], v[74:75]
	v_alignbit_b32 v67, v70, v67, 16
	v_cvt_pk_f16_f32 v69, v68, v69
	v_alignbit_b32 v68, v69, v70, 16
	v_lshrrev_b32_e32 v69, 16, v69
	v_fma_mixhi_f16 v69, v77, v77, 0
	global_store_dwordx4 v[82:83], v[66:69], off offset:256 nt
	ds_read2_b32 v[66:67], v159 offset0:128 offset1:144
	s_waitcnt lgkmcnt(0)
;   __device__ __forceinline__ void operator()(const f32x4 (&acc)[2][2][4][2], const g8::Unit& u, int ui, int wr, int wc, int fr, int fq) const {
; #pragma unroll
;     for (int ai = 0; ai < 2; ++ai)
; #pragma unroll
;       for (int m = 0; m < 4; ++m) {
;         const int rl = 128 * ai + 64 * wr + 16 * m + fr;
;         const float r = rsl[ui * 256 + rl];
;         h16* rowp = hid + (size_t)(u.pm * 256 + rl) * DFF + 256 * u.pn + 32 * wc + 8 * fq;
; #pragma unroll
;         for (int bj = 0; bj < 2; ++bj) {
;           f32x4 v[2];
; #pragma unroll
;           for (int n = 0; n < 2; ++n) {
;             v[n] = acc[ai][bj][m][n] * r;
; #pragma unroll
;             for (int j = 0; j < 4; ++j) { const float t = fmaxf(v[n][j], 0.f); v[n][j] = t * t; }
;           }
;           __builtin_nontemporal_store(pack8(v[0], v[1]), (h16x8*)(rowp + 128 * bj));
;         }
;       }
	v_pk_mul_f32 v[64:65], v[64:65], v[66:67] op_sel_hi:[1,0]
	v_pk_mul_f32 v[62:63], v[62:63], v[66:67] op_sel_hi:[1,0]
	v_pk_mul_f32 v[58:59], v[58:59], v[66:67] op_sel_hi:[1,0]
	v_max_f32_e32 v72, 0, v62
	v_max_f32_e32 v62, 0, v63
	v_max_f32_e32 v63, 0, v64
	v_add_u32_e32 v68, s11, v154
	v_max_f32_e32 v64, 0, v65
	v_pk_mul_f32 v[60:61], v[60:61], v[66:67] op_sel_hi:[1,0]
	v_max_f32_e32 v65, 0, v58
	v_max_f32_e32 v70, 0, v59
	v_pk_mul_f32 v[58:59], v[62:63], v[62:63]
	v_ashrrev_i32_e32 v69, 31, v68
	v_max_f32_e32 v71, 0, v60
	v_fma_mixlo_f16 v60, v72, v72, 0
	v_cvt_pk_f16_f32 v59, v58, v59
	v_lshlrev_b64 v[68:69], 13, v[68:69]
	v_max_f32_e32 v73, 0, v61
	v_pack_b32_f16 v58, v60, v59
	v_pk_mul_f32 v[60:61], v[64:65], v[64:65]
	v_lshl_add_u64 v[68:69], s[0:1], 0, v[68:69]
	v_cvt_pk_f16_f32 v62, v60, v61
	v_pk_mul_f32 v[60:61], v[70:71], v[70:71]
	v_lshl_add_u64 v[68:69], v[68:69], 0, s[18:19]
	v_cvt_pk_f16_f32 v61, v60, v61
	v_lshl_add_u64 v[68:69], v[68:69], 0, s[92:93]
	v_alignbit_b32 v60, v61, v62, 16
	v_lshrrev_b32_e32 v61, 16, v61
	v_lshl_add_u64 v[68:69], v[68:69], 0, v[0:1]
	v_alignbit_b32 v59, v62, v59, 16
	v_fma_mixhi_f16 v61, v73, v73, 0
	v_pk_mul_f32 v[56:57], v[56:57], v[66:67] op_sel_hi:[1,0]
	v_pk_mul_f32 v[54:55], v[54:55], v[66:67] op_sel_hi:[1,0]
	global_store_dwordx4 v[68:69], v[58:61], off nt
	v_pk_mul_f32 v[50:51], v[50:51], v[66:67] op_sel_hi:[1,0]
	v_pk_mul_f32 v[52:53], v[52:53], v[66:67] op_sel_hi:[1,0]
	v_max_f32_e32 v60, 0, v54
	v_max_f32_e32 v54, 0, v55
	v_max_f32_e32 v55, 0, v56
	v_max_f32_e32 v56, 0, v57
	v_max_f32_e32 v57, 0, v50
	v_max_f32_e32 v58, 0, v51
	v_pk_mul_f32 v[50:51], v[54:55], v[54:55]
	v_max_f32_e32 v59, 0, v52
	v_fma_mixlo_f16 v52, v60, v60, 0
	v_cvt_pk_f16_f32 v51, v50, v51
	v_max_f32_e32 v61, 0, v53
	v_pack_b32_f16 v50, v52, v51
	v_pk_mul_f32 v[52:53], v[56:57], v[56:57]
	s_nop 0
	v_cvt_pk_f16_f32 v54, v52, v53
	v_pk_mul_f32 v[52:53], v[58:59], v[58:59]
	v_alignbit_b32 v51, v54, v51, 16
	v_cvt_pk_f16_f32 v53, v52, v53
	v_alignbit_b32 v52, v53, v54, 16
	v_lshrrev_b32_e32 v53, 16, v53
	v_fma_mixhi_f16 v53, v61, v61, 0
	global_store_dwordx4 v[68:69], v[50:53], off offset:256 nt
	s_nop 1
	v_mov_b32_e32 v52, v67
	v_pk_mul_f32 v[46:47], v[46:47], v[52:53] op_sel_hi:[1,0]
	v_pk_mul_f32 v[48:49], v[48:49], v[52:53] op_sel_hi:[1,0]
	v_max_f32_e32 v53, 0, v46
	v_max_f32_e32 v46, 0, v47
	v_max_f32_e32 v47, 0, v48
	v_pk_mul_f32 v[42:43], v[42:43], v[52:53] op_sel_hi:[1,0]
	v_add_u32_e32 v50, s11, v155
	v_max_f32_e32 v48, 0, v49
	v_pk_mul_f32 v[44:45], v[44:45], v[52:53] op_sel_hi:[1,0]
	v_max_f32_e32 v49, 0, v42
	v_max_f32_e32 v54, 0, v43
	v_pk_mul_f32 v[42:43], v[46:47], v[46:47]
	v_ashrrev_i32_e32 v51, 31, v50
	v_max_f32_e32 v55, 0, v44
	v_fma_mixlo_f16 v44, v53, v53, 0
	v_cvt_pk_f16_f32 v43, v42, v43
	v_lshlrev_b64 v[50:51], 13, v[50:51]
	v_max_f32_e32 v56, 0, v45
	v_pack_b32_f16 v42, v44, v43
	v_pk_mul_f32 v[44:45], v[48:49], v[48:49]
	v_lshl_add_u64 v[50:51], s[0:1], 0, v[50:51]
	v_cvt_pk_f16_f32 v46, v44, v45
	v_pk_mul_f32 v[44:45], v[54:55], v[54:55]
	v_lshl_add_u64 v[50:51], v[50:51], 0, s[18:19]
	v_cvt_pk_f16_f32 v45, v44, v45
	v_lshl_add_u64 v[50:51], v[50:51], 0, s[92:93]
	v_alignbit_b32 v44, v45, v46, 16
	v_lshrrev_b32_e32 v45, 16, v45
	v_lshl_add_u64 v[50:51], v[50:51], 0, v[0:1]
	v_alignbit_b32 v43, v46, v43, 16
	v_fma_mixhi_f16 v45, v56, v56, 0
	v_pk_mul_f32 v[40:41], v[40:41], v[52:53] op_sel_hi:[1,0]
	v_pk_mul_f32 v[38:39], v[38:39], v[52:53] op_sel_hi:[1,0]
	global_store_dwordx4 v[50:51], v[42:45], off nt
	v_pk_mul_f32 v[34:35], v[34:35], v[52:53] op_sel_hi:[1,0]
	v_pk_mul_f32 v[36:37], v[36:37], v[52:53] op_sel_hi:[1,0]
	v_max_f32_e32 v44, 0, v38
	v_max_f32_e32 v38, 0, v39
	v_max_f32_e32 v39, 0, v40
	v_max_f32_e32 v40, 0, v41
	v_max_f32_e32 v41, 0, v34
	v_max_f32_e32 v42, 0, v35
	v_pk_mul_f32 v[34:35], v[38:39], v[38:39]
	v_max_f32_e32 v43, 0, v36
	v_fma_mixlo_f16 v36, v44, v44, 0
	v_cvt_pk_f16_f32 v35, v34, v35
	v_max_f32_e32 v45, 0, v37
	v_pack_b32_f16 v34, v36, v35
	v_pk_mul_f32 v[36:37], v[40:41], v[40:41]
	s_nop 0
	v_cvt_pk_f16_f32 v38, v36, v37
	v_pk_mul_f32 v[36:37], v[42:43], v[42:43]
	v_alignbit_b32 v35, v38, v35, 16
	v_cvt_pk_f16_f32 v37, v36, v37
	v_alignbit_b32 v36, v37, v38, 16
	v_lshrrev_b32_e32 v37, 16, v37
	v_fma_mixhi_f16 v37, v45, v45, 0
	global_store_dwordx4 v[50:51], v[34:37], off offset:256 nt
	ds_read2_b32 v[34:35], v159 offset0:160 offset1:176
	s_waitcnt lgkmcnt(0)
; #define G8_WAIT_V(n) asm volatile("s_waitcnt vmcnt(" #n ")" ::: "memory")
; #define G8_BAR __builtin_amdgcn_s_barrier()
; template <class Epi>
; __device__ __forceinline__ void gemm_phase(LAS unsigned char* lds, const h16* A, const h16* Bt, int K, const Order& S, const Epi& E) {
;     ...
;   G8_WAIT_V(0);
;   if (wr == 0) G8_BAR;
;   G8_BAR;
;   __device__ __forceinline__ void operator()(const f32x4 (&acc)[2][2][4][2], const g8::Unit& u, int ui, int wr, int wc, int fr, int fq) const {
; #pragma unroll
;     for (int ai = 0; ai < 2; ++ai)
; #pragma unroll
;       for (int m = 0; m < 4; ++m) {
;         const int rl = 128 * ai + 64 * wr + 16 * m + fr;
;         const float r = rsl[ui * 256 + rl];
;         h16* rowp = hid + (size_t)(u.pm * 256 + rl) * DFF + 256 * u.pn + 32 * wc + 8 * fq;
; #pragma unroll
;         for (int bj = 0; bj < 2; ++bj) {
;           f32x4 v[2];
; #pragma unroll
;           for (int n = 0; n < 2; ++n) {
;             v[n] = acc[ai][bj][m][n] * r;
; #pragma unroll
;             for (int j = 0; j < 4; ++j) { const float t = fmaxf(v[n][j], 0.f); v[n][j] = t * t; }
;           }
;           __builtin_nontemporal_store(pack8(v[0], v[1]), (h16x8*)(rowp + 128 * bj));
;         }
;       }
	v_pk_mul_f32 v[32:33], v[32:33], v[34:35] op_sel_hi:[1,0]
	v_pk_mul_f32 v[30:31], v[30:31], v[34:35] op_sel_hi:[1,0]
	v_pk_mul_f32 v[26:27], v[26:27], v[34:35] op_sel_hi:[1,0]
	v_max_f32_e32 v40, 0, v30
	v_max_f32_e32 v30, 0, v31
	v_max_f32_e32 v31, 0, v32
	v_add_u32_e32 v36, s11, v156
	v_max_f32_e32 v32, 0, v33
	v_pk_mul_f32 v[28:29], v[28:29], v[34:35] op_sel_hi:[1,0]
	v_max_f32_e32 v33, 0, v26
	v_max_f32_e32 v38, 0, v27
	v_pk_mul_f32 v[26:27], v[30:31], v[30:31]
	v_ashrrev_i32_e32 v37, 31, v36
	v_max_f32_e32 v39, 0, v28
	v_fma_mixlo_f16 v28, v40, v40, 0
	v_cvt_pk_f16_f32 v27, v26, v27
	v_lshlrev_b64 v[36:37], 13, v[36:37]
	v_max_f32_e32 v41, 0, v29
	v_pack_b32_f16 v26, v28, v27
	v_pk_mul_f32 v[28:29], v[32:33], v[32:33]
	v_lshl_add_u64 v[36:37], s[0:1], 0, v[36:37]
	v_cvt_pk_f16_f32 v30, v28, v29
	v_pk_mul_f32 v[28:29], v[38:39], v[38:39]
	v_lshl_add_u64 v[36:37], v[36:37], 0, s[18:19]
	v_cvt_pk_f16_f32 v29, v28, v29
	v_lshl_add_u64 v[36:37], v[36:37], 0, s[92:93]
	v_alignbit_b32 v28, v29, v30, 16
	v_lshrrev_b32_e32 v29, 16, v29
	v_lshl_add_u64 v[36:37], v[36:37], 0, v[0:1]
	v_alignbit_b32 v27, v30, v27, 16
	v_fma_mixhi_f16 v29, v41, v41, 0
	v_pk_mul_f32 v[24:25], v[24:25], v[34:35] op_sel_hi:[1,0]
	v_pk_mul_f32 v[22:23], v[22:23], v[34:35] op_sel_hi:[1,0]
	global_store_dwordx4 v[36:37], v[26:29], off nt
	v_pk_mul_f32 v[18:19], v[18:19], v[34:35] op_sel_hi:[1,0]
	v_pk_mul_f32 v[20:21], v[20:21], v[34:35] op_sel_hi:[1,0]
	v_max_f32_e32 v28, 0, v22
	v_max_f32_e32 v22, 0, v23
	v_max_f32_e32 v23, 0, v24
	v_max_f32_e32 v24, 0, v25
	v_max_f32_e32 v25, 0, v18
	v_max_f32_e32 v26, 0, v19
	v_pk_mul_f32 v[18:19], v[22:23], v[22:23]
	v_max_f32_e32 v27, 0, v20
	v_fma_mixlo_f16 v20, v28, v28, 0
	v_cvt_pk_f16_f32 v19, v18, v19
	v_max_f32_e32 v29, 0, v21
	v_pack_b32_f16 v18, v20, v19
	v_pk_mul_f32 v[20:21], v[24:25], v[24:25]
	s_nop 0
	v_cvt_pk_f16_f32 v22, v20, v21
	v_pk_mul_f32 v[20:21], v[26:27], v[26:27]
	v_alignbit_b32 v19, v22, v19, 16
	v_cvt_pk_f16_f32 v21, v20, v21
	v_alignbit_b32 v20, v21, v22, 16
	v_lshrrev_b32_e32 v21, 16, v21
	v_fma_mixhi_f16 v21, v29, v29, 0
	global_store_dwordx4 v[36:37], v[18:21], off offset:256 nt
	s_nop 1
	v_mov_b32_e32 v20, v35
	v_pk_mul_f32 v[14:15], v[14:15], v[20:21] op_sel_hi:[1,0]
	v_pk_mul_f32 v[16:17], v[16:17], v[20:21] op_sel_hi:[1,0]
	v_max_f32_e32 v21, 0, v14
	v_max_f32_e32 v14, 0, v15
	v_max_f32_e32 v15, 0, v16
	v_pk_mul_f32 v[10:11], v[10:11], v[20:21] op_sel_hi:[1,0]
	v_add_u32_e32 v18, s11, v157
	v_max_f32_e32 v16, 0, v17
	v_pk_mul_f32 v[12:13], v[12:13], v[20:21] op_sel_hi:[1,0]
	v_max_f32_e32 v17, 0, v10
	v_max_f32_e32 v22, 0, v11
	v_pk_mul_f32 v[10:11], v[14:15], v[14:15]
	v_ashrrev_i32_e32 v19, 31, v18
	v_max_f32_e32 v23, 0, v12
	v_fma_mixlo_f16 v12, v21, v21, 0
	v_cvt_pk_f16_f32 v11, v10, v11
	v_lshlrev_b64 v[18:19], 13, v[18:19]
	v_max_f32_e32 v24, 0, v13
	v_pack_b32_f16 v10, v12, v11
	v_pk_mul_f32 v[12:13], v[16:17], v[16:17]
	v_lshl_add_u64 v[18:19], s[0:1], 0, v[18:19]
	v_cvt_pk_f16_f32 v14, v12, v13
	v_pk_mul_f32 v[12:13], v[22:23], v[22:23]
	v_lshl_add_u64 v[18:19], v[18:19], 0, s[18:19]
	v_cvt_pk_f16_f32 v13, v12, v13
	v_lshl_add_u64 v[18:19], v[18:19], 0, s[92:93]
	v_alignbit_b32 v12, v13, v14, 16
	v_lshrrev_b32_e32 v13, 16, v13
	v_lshl_add_u64 v[18:19], v[18:19], 0, v[0:1]
	v_alignbit_b32 v11, v14, v11, 16
	v_fma_mixhi_f16 v13, v24, v24, 0
	v_pk_mul_f32 v[8:9], v[8:9], v[20:21] op_sel_hi:[1,0]
	v_pk_mul_f32 v[6:7], v[6:7], v[20:21] op_sel_hi:[1,0]
	global_store_dwordx4 v[18:19], v[10:13], off nt
	v_pk_mul_f32 v[2:3], v[2:3], v[20:21] op_sel_hi:[1,0]
	v_pk_mul_f32 v[4:5], v[4:5], v[20:21] op_sel_hi:[1,0]
	v_max_f32_e32 v12, 0, v6
	v_max_f32_e32 v6, 0, v7
	v_max_f32_e32 v7, 0, v8
	v_max_f32_e32 v8, 0, v9
	v_max_f32_e32 v9, 0, v2
	v_max_f32_e32 v10, 0, v3
	v_pk_mul_f32 v[2:3], v[6:7], v[6:7]
	v_max_f32_e32 v11, 0, v4
	v_fma_mixlo_f16 v4, v12, v12, 0
	v_cvt_pk_f16_f32 v3, v2, v3
	v_max_f32_e32 v13, 0, v5
	v_pack_b32_f16 v2, v4, v3
	v_pk_mul_f32 v[4:5], v[8:9], v[8:9]
	s_mov_b64 s[18:19], s[14:15]
	v_cvt_pk_f16_f32 v6, v4, v5
	v_pk_mul_f32 v[4:5], v[10:11], v[10:11]
	v_alignbit_b32 v3, v6, v3, 16
	v_cvt_pk_f16_f32 v5, v4, v5
	v_alignbit_b32 v4, v5, v6, 16
	v_lshrrev_b32_e32 v5, 16, v5
	v_fma_mixhi_f16 v5, v13, v13, 0
	global_store_dwordx4 v[18:19], v[2:5], off offset:256 nt
	s_cbranch_vccz .LBB0_2466
	s_waitcnt vmcnt(0)
	s_cmpk_gt_u32 s2, 0xff
	s_cbranch_scc1 .LBB0_2477
	s_barrier

; #define G8_STAGE(bufoff, gbase) do { _Pragma("unroll") for (int _i = 0; _i < 2; ++_i) \
;     __builtin_amdgcn_global_load_lds((const unsigned*)((const char*)(gbase) + voffA[_i]), (LAS unsigned*)(lds + (bufoff) + ldsw + _i * 8192), 16, 0, 0); } while (0)
; #define G8_LDA(dst, b, h) do { _Pragma("unroll") for (int m = 0; m < 4; ++m) _Pragma("unroll") for (int k = 0; k < 2; ++k) dst[m][k] = *(const LAS h16x8*)(lds + G8_SA(b, h) + aoff + m * 2048 + k * 1024); } while (0)
; #define G8_LDB(dst, b, h) do { _Pragma("unroll") for (int n = 0; n < 2; ++n) _Pragma("unroll") for (int k = 0; k < 2; ++k) dst[n][k] = *(const LAS h16x8*)(lds + G8_SB(b, h) + boff + n * 2048 + k * 1024); } while (0)
; #define G8_MMA(ai, bj, At, Bt_) do { __builtin_amdgcn_s_setprio(1); _Pragma("unroll") for (int m = 0; m < 4; ++m) _Pragma("unroll") for (int n = 0; n < 2; ++n) _Pragma("unroll") for (int k = 0; k < 2; ++k) \
;     acc[ai][bj][m][n] = __builtin_amdgcn_mfma_f32_16x16x32_f16(Bt_[n][k], At[m][k], acc[ai][bj][m][n], 0, 0, 0); __builtin_amdgcn_s_setprio(0); } while (0)
; #define G8_WAIT_V(n) asm volatile("s_waitcnt vmcnt(" #n ")" ::: "memory")
; #define G8_WAIT_L(n) asm volatile("s_waitcnt lgkmcnt(" #n ")" ::: "memory")
; #define G8_BAR __builtin_amdgcn_s_barrier()
; template <class Epi>
; __device__ __forceinline__ void gemm_phase(LAS unsigned char* lds, const h16* A, const h16* Bt, int K, const Order& S, const Epi& E) {
;     ...
;     for (int t = 0; t < nt; t += 2) {
;       const bool last = (t == nt - 2);
;       const char* a1 = cA + (size_t)(t + 1) * kstep;
;       const char* a2 = last ? nA : cA + (size_t)(t + 2) * kstep;
;       const char* b2 = last ? nB : cB + (size_t)(t + 2) * kstep;
;       const char* a3 = a2 + kstep;
;       const char* b3 = b2 + kstep;
;       if (Epi::MID_T >= 0 && t == Epi::MID_T) E.mid(acc, ui, wr, fr);
;       G8_LDB(B0, 0, 0); G8_SCHED; G8_LDA(At, 0, 0); G8_STAGE(G8_SA(1, 1), a1 + hstep);
;       G8_WAIT_L(8); G8_BAR; G8_WAIT_L(0); G8_MMA(0, 0, At, B0); G8_BAR; G8_SCHED;
;       G8_LDB(B1, 0, 1); G8_STAGE(G8_SB(0, 0), b2);
;       G8_BAR; G8_WAIT_L(0); G8_MMA(0, 1, At, B1); G8_BAR;
;       G8_LDA(At, 0, 1); G8_STAGE(G8_SA(0, 0), a2);
;       G8_BAR; G8_WAIT_L(0); G8_MMA(1, 0, At, B0); G8_BAR; G8_SCHED;
;       G8_STAGE(G8_SB(0, 1), b2 + hstep);
;       G8_WAIT_V(6); G8_BAR; G8_MMA(1, 1, At, B1); G8_BAR;
.LBB0_2542:
	s_add_u32 s24, s22, 0xfff00080
	s_addc_u32 s25, s23, -1
	s_cmp_eq_u32 s53, 60
	s_cselect_b32 s27, s3, s25
	s_cselect_b32 s26, s9, s24
	s_cselect_b32 s25, s15, s52
	s_cselect_b32 s24, s17, s51
	v_lshl_add_u64 v[140:141], s[22:23], 0, v[136:137]
	s_add_i32 m0, s35, 0xc000
	ds_read_b128 v[172:175], v135
	ds_read_b128 v[176:179], v135 offset:1024
	ds_read_b128 v[180:183], v135 offset:2048
	ds_read_b128 v[184:187], v135 offset:3072
	ds_read_b128 v[202:205], v135 offset:4096
	ds_read_b128 v[206:209], v135 offset:5120
	ds_read_b128 v[210:213], v135 offset:6144
	ds_read_b128 v[214:217], v135 offset:7168
	global_load_lds_dwordx4 v[140:141], off
	v_lshl_add_u64 v[140:141], s[22:23], 0, v[138:139]
	s_add_i32 m0, s35, 0xe000
	s_nop 0
	global_load_lds_dwordx4 v[140:141], off
	s_waitcnt lgkmcnt(8)
	s_barrier
	s_waitcnt lgkmcnt(0)
	v_mfma_f32_16x16x32_f16 v[126:129], v[152:155], v[172:175], v[126:129]
	v_mfma_f32_16x16x32_f16 v[122:125], v[164:167], v[172:175], v[122:125]
	v_mfma_f32_16x16x32_f16 v[110:113], v[152:155], v[180:183], v[110:113]
	v_mfma_f32_16x16x32_f16 v[106:109], v[164:167], v[180:183], v[106:109]
	v_mfma_f32_16x16x32_f16 v[94:97], v[152:155], v[202:205], v[94:97]
	v_mfma_f32_16x16x32_f16 v[90:93], v[164:167], v[202:205], v[90:93]
	v_mfma_f32_16x16x32_f16 v[78:81], v[152:155], v[210:213], v[78:81]
	v_mfma_f32_16x16x32_f16 v[74:77], v[164:167], v[210:213], v[74:77]
	v_mfma_f32_16x16x32_f16 v[126:129], v[160:163], v[176:179], v[126:129]
	v_mfma_f32_16x16x32_f16 v[122:125], v[168:171], v[176:179], v[122:125]
	v_mfma_f32_16x16x32_f16 v[110:113], v[160:163], v[184:187], v[110:113]
	v_mfma_f32_16x16x32_f16 v[106:109], v[168:171], v[184:187], v[106:109]
	v_mfma_f32_16x16x32_f16 v[94:97], v[160:163], v[206:209], v[94:97]
	v_mfma_f32_16x16x32_f16 v[90:93], v[168:171], v[206:209], v[90:93]
	v_mfma_f32_16x16x32_f16 v[78:81], v[160:163], v[214:217], v[78:81]
	v_mfma_f32_16x16x32_f16 v[74:77], v[168:171], v[214:217], v[74:77]
	s_barrier
	v_or_b32_e32 v140, 0x14000, v158
	v_add_u32_e32 v141, 0x14400, v158
	ds_read_b128 v[218:221], v140
	ds_read_b128 v[222:225], v141
	v_add_u32_e32 v140, 0x14800, v158
	v_add_u32_e32 v141, 0x14c00, v158
	s_mov_b32 m0, s36
	ds_read_b128 v[226:229], v140
	ds_read_b128 v[230:233], v141
	v_lshl_add_u64 v[140:141], s[24:25], 0, v[0:1]
	global_load_lds_dwordx4 v[140:141], off
	v_lshl_add_u64 v[156:157], s[24:25], 0, v[130:131]
	s_mov_b32 m0, s37
	s_nop 0
	global_load_lds_dwordx4 v[156:157], off
	s_barrier
	s_waitcnt lgkmcnt(0)
	v_mfma_f32_16x16x32_f16 v[118:121], v[218:221], v[172:175], v[118:121]
	v_mfma_f32_16x16x32_f16 v[114:117], v[226:229], v[172:175], v[114:117]
	v_mfma_f32_16x16x32_f16 v[102:105], v[218:221], v[180:183], v[102:105]
	v_mfma_f32_16x16x32_f16 v[98:101], v[226:229], v[180:183], v[98:101]
	v_mfma_f32_16x16x32_f16 v[86:89], v[218:221], v[202:205], v[86:89]
	v_mfma_f32_16x16x32_f16 v[82:85], v[226:229], v[202:205], v[82:85]
	v_mfma_f32_16x16x32_f16 v[70:73], v[218:221], v[210:213], v[70:73]
	v_mfma_f32_16x16x32_f16 v[66:69], v[226:229], v[210:213], v[66:69]
	v_mfma_f32_16x16x32_f16 v[118:121], v[222:225], v[176:179], v[118:121]
	v_mfma_f32_16x16x32_f16 v[114:117], v[230:233], v[176:179], v[114:117]
	v_mfma_f32_16x16x32_f16 v[102:105], v[222:225], v[184:187], v[102:105]
	v_mfma_f32_16x16x32_f16 v[98:101], v[230:233], v[184:187], v[98:101]
	v_mfma_f32_16x16x32_f16 v[86:89], v[222:225], v[206:209], v[86:89]
	v_mfma_f32_16x16x32_f16 v[82:85], v[230:233], v[206:209], v[82:85]
	v_mfma_f32_16x16x32_f16 v[70:73], v[222:225], v[214:217], v[70:73]
	v_mfma_f32_16x16x32_f16 v[66:69], v[230:233], v[214:217], v[66:69]
	s_mov_b32 m0, s35
	v_lshl_add_u64 v[188:189], s[26:27], 0, v[0:1]
	s_barrier
	ds_read_b128 v[172:175], v135 offset:16384
	ds_read_b128 v[176:179], v135 offset:17408
	ds_read_b128 v[180:183], v135 offset:18432
	ds_read_b128 v[184:187], v135 offset:19456
	ds_read_b128 v[202:205], v135 offset:20480
	ds_read_b128 v[206:209], v135 offset:21504
	ds_read_b128 v[210:213], v135 offset:22528
	ds_read_b128 v[214:217], v135 offset:23552
	global_load_lds_dwordx4 v[188:189], off
	v_lshl_add_u64 v[234:235], s[26:27], 0, v[130:131]
	s_mov_b32 m0, s38
	s_nop 0
	global_load_lds_dwordx4 v[234:235], off
	s_waitcnt vmcnt(10)
	s_barrier
	s_waitcnt lgkmcnt(0)
	v_mfma_f32_16x16x32_f16 v[62:65], v[152:155], v[172:175], v[62:65]
	v_mfma_f32_16x16x32_f16 v[58:61], v[164:167], v[172:175], v[58:61]
	v_mfma_f32_16x16x32_f16 v[46:49], v[152:155], v[180:183], v[46:49]
	v_mfma_f32_16x16x32_f16 v[42:45], v[164:167], v[180:183], v[42:45]
	v_mfma_f32_16x16x32_f16 v[30:33], v[152:155], v[202:205], v[30:33]
	v_mfma_f32_16x16x32_f16 v[26:29], v[164:167], v[202:205], v[26:29]
	v_mfma_f32_16x16x32_f16 v[14:17], v[152:155], v[210:213], v[14:17]
	v_mfma_f32_16x16x32_f16 v[10:13], v[164:167], v[210:213], v[10:13]
	v_mfma_f32_16x16x32_f16 v[62:65], v[160:163], v[176:179], v[62:65]
	v_mfma_f32_16x16x32_f16 v[58:61], v[168:171], v[176:179], v[58:61]
	v_mfma_f32_16x16x32_f16 v[46:49], v[160:163], v[184:187], v[46:49]
	v_mfma_f32_16x16x32_f16 v[42:45], v[168:171], v[184:187], v[42:45]
	v_mfma_f32_16x16x32_f16 v[30:33], v[160:163], v[206:209], v[30:33]
	v_mfma_f32_16x16x32_f16 v[26:29], v[168:171], v[206:209], v[26:29]
	v_mfma_f32_16x16x32_f16 v[14:17], v[160:163], v[214:217], v[14:17]
	v_mfma_f32_16x16x32_f16 v[10:13], v[168:171], v[214:217], v[10:13]
	s_barrier
; #define G8_STAGE(bufoff, gbase) do { _Pragma("unroll") for (int _i = 0; _i < 2; ++_i) \
;     __builtin_amdgcn_global_load_lds((const unsigned*)((const char*)(gbase) + voffA[_i]), (LAS unsigned*)(lds + (bufoff) + ldsw + _i * 8192), 16, 0, 0); } while (0)
; #define G8_LDA(dst, b, h) do { _Pragma("unroll") for (int m = 0; m < 4; ++m) _Pragma("unroll") for (int k = 0; k < 2; ++k) dst[m][k] = *(const LAS h16x8*)(lds + G8_SA(b, h) + aoff + m * 2048 + k * 1024); } while (0)
; #define G8_LDB(dst, b, h) do { _Pragma("unroll") for (int n = 0; n < 2; ++n) _Pragma("unroll") for (int k = 0; k < 2; ++k) dst[n][k] = *(const LAS h16x8*)(lds + G8_SB(b, h) + boff + n * 2048 + k * 1024); } while (0)
; #define G8_MMA(ai, bj, At, Bt_) do { __builtin_amdgcn_s_setprio(1); _Pragma("unroll") for (int m = 0; m < 4; ++m) _Pragma("unroll") for (int n = 0; n < 2; ++n) _Pragma("unroll") for (int k = 0; k < 2; ++k) \
;     acc[ai][bj][m][n] = __builtin_amdgcn_mfma_f32_16x16x32_f16(Bt_[n][k], At[m][k], acc[ai][bj][m][n], 0, 0, 0); __builtin_amdgcn_s_setprio(0); } while (0)
; #define G8_WAIT_V(n) asm volatile("s_waitcnt vmcnt(" #n ")" ::: "memory")
; #define G8_WAIT_L(n) asm volatile("s_waitcnt lgkmcnt(" #n ")" ::: "memory")
; #define G8_BAR __builtin_amdgcn_s_barrier()
; #define G8_SCHED __builtin_amdgcn_sched_barrier(0)
; template <class Epi>
; __device__ __forceinline__ void gemm_phase(LAS unsigned char* lds, const h16* A, const h16* Bt, int K, const Order& S, const Epi& E) {
;     ...
;       G8_STAGE(G8_SB(0, 1), b2 + hstep);
;       G8_WAIT_V(6); G8_BAR; G8_MMA(1, 1, At, B1); G8_BAR;
;       G8_LDB(B0, 1, 0); G8_SCHED; G8_LDA(At, 1, 0); G8_STAGE(G8_SA(0, 1), a2 + hstep);
;       G8_WAIT_L(8); G8_BAR; G8_WAIT_L(0); G8_MMA(0, 0, At, B0); G8_BAR; G8_SCHED;
;       G8_LDB(B1, 1, 1); G8_STAGE(G8_SB(1, 0), b3);
;       G8_BAR; G8_WAIT_L(0); G8_MMA(0, 1, At, B1); G8_BAR;
;       G8_LDA(At, 1, 1); G8_STAGE(G8_SA(1, 0), a3);
;       G8_BAR; G8_WAIT_L(0); G8_MMA(1, 0, At, B0); G8_BAR; G8_SCHED;
;       G8_STAGE(G8_SB(1, 1), b3 + hstep);
;       G8_WAIT_V(6); G8_BAR; G8_MMA(1, 1, At, B1); G8_BAR;
	s_add_u32 s54, s24, 0x100000
	s_addc_u32 s55, s25, 0
	s_mov_b32 m0, s39
	v_lshl_add_u64 v[152:153], s[54:55], 0, v[0:1]
	global_load_lds_dwordx4 v[152:153], off
	v_lshl_add_u64 v[152:153], s[54:55], 0, v[130:131]
	s_mov_b32 m0, s40
	s_nop 0
	global_load_lds_dwordx4 v[152:153], off
	v_or_b32_e32 v152, 0x18000, v158
	v_add_u32_e32 v159, 0x18400, v158
	ds_read_b128 v[152:155], v152
	ds_read_b128 v[160:163], v159
	v_add_u32_e32 v159, 0x18800, v158
	v_add_u32_e32 v168, 0x18c00, v158
	ds_read_b128 v[164:167], v159
	ds_read_b128 v[168:171], v168
	s_waitcnt vmcnt(6)
	s_barrier
	v_mfma_f32_16x16x32_f16 v[54:57], v[218:221], v[172:175], v[54:57]
	v_mfma_f32_16x16x32_f16 v[50:53], v[226:229], v[172:175], v[50:53]
	v_mfma_f32_16x16x32_f16 v[38:41], v[218:221], v[180:183], v[38:41]
	v_mfma_f32_16x16x32_f16 v[34:37], v[226:229], v[180:183], v[34:37]
	v_mfma_f32_16x16x32_f16 v[22:25], v[218:221], v[202:205], v[22:25]
	v_mfma_f32_16x16x32_f16 v[18:21], v[226:229], v[202:205], v[18:21]
	v_mfma_f32_16x16x32_f16 v[6:9], v[218:221], v[210:213], v[6:9]
	v_mfma_f32_16x16x32_f16 v[2:5], v[226:229], v[210:213], v[2:5]
	v_mfma_f32_16x16x32_f16 v[54:57], v[222:225], v[176:179], v[54:57]
	v_mfma_f32_16x16x32_f16 v[50:53], v[230:233], v[176:179], v[50:53]
	v_mfma_f32_16x16x32_f16 v[38:41], v[222:225], v[184:187], v[38:41]
	v_mfma_f32_16x16x32_f16 v[34:37], v[230:233], v[184:187], v[34:37]
	v_mfma_f32_16x16x32_f16 v[22:25], v[222:225], v[206:209], v[22:25]
	v_mfma_f32_16x16x32_f16 v[18:21], v[230:233], v[206:209], v[18:21]
	v_mfma_f32_16x16x32_f16 v[6:9], v[222:225], v[214:217], v[6:9]
	v_mfma_f32_16x16x32_f16 v[2:5], v[230:233], v[214:217], v[2:5]
	s_barrier
	s_add_u32 s26, s26, 0x100000
	s_addc_u32 s27, s27, 0
	s_mov_b32 m0, s41
	v_lshl_add_u64 v[218:219], s[26:27], 0, v[0:1]
	ds_read_b128 v[172:175], v135 offset:32768
	ds_read_b128 v[176:179], v135 offset:33792
	ds_read_b128 v[180:183], v135 offset:34816
	ds_read_b128 v[184:187], v135 offset:35840
	ds_read_b128 v[202:205], v135 offset:36864
	ds_read_b128 v[206:209], v135 offset:37888
	ds_read_b128 v[210:213], v135 offset:38912
	ds_read_b128 v[214:217], v135 offset:39936
	global_load_lds_dwordx4 v[218:219], off
	v_lshl_add_u64 v[218:219], s[26:27], 0, v[130:131]
	s_mov_b32 m0, s42
	s_nop 0
	global_load_lds_dwordx4 v[218:219], off
	s_waitcnt lgkmcnt(8)
	s_barrier
	s_waitcnt lgkmcnt(0)
	v_mfma_f32_16x16x32_f16 v[126:129], v[152:155], v[172:175], v[126:129]
	v_mfma_f32_16x16x32_f16 v[122:125], v[164:167], v[172:175], v[122:125]
	v_mfma_f32_16x16x32_f16 v[110:113], v[152:155], v[180:183], v[110:113]
	v_mfma_f32_16x16x32_f16 v[106:109], v[164:167], v[180:183], v[106:109]
	v_mfma_f32_16x16x32_f16 v[94:97], v[152:155], v[202:205], v[94:97]
	v_mfma_f32_16x16x32_f16 v[90:93], v[164:167], v[202:205], v[90:93]
	v_mfma_f32_16x16x32_f16 v[78:81], v[152:155], v[210:213], v[78:81]
	v_mfma_f32_16x16x32_f16 v[74:77], v[164:167], v[210:213], v[74:77]
	v_mfma_f32_16x16x32_f16 v[126:129], v[160:163], v[176:179], v[126:129]
	v_mfma_f32_16x16x32_f16 v[122:125], v[168:171], v[176:179], v[122:125]
	v_mfma_f32_16x16x32_f16 v[110:113], v[160:163], v[184:187], v[110:113]
	v_mfma_f32_16x16x32_f16 v[106:109], v[168:171], v[184:187], v[106:109]
	v_mfma_f32_16x16x32_f16 v[94:97], v[160:163], v[206:209], v[94:97]
	v_mfma_f32_16x16x32_f16 v[90:93], v[168:171], v[206:209], v[90:93]
	v_mfma_f32_16x16x32_f16 v[78:81], v[160:163], v[214:217], v[78:81]
	v_mfma_f32_16x16x32_f16 v[74:77], v[168:171], v[214:217], v[74:77]
	s_barrier
	v_or_b32_e32 v159, 0x1c000, v158
	s_mov_b32 m0, s44
	v_add_u32_e32 v195, 0x1c400, v158
	ds_read_b128 v[218:221], v159
	ds_read_b128 v[222:225], v195
	v_add_u32_e32 v159, 0x1c800, v158
	v_lshl_add_u64 v[140:141], v[140:141], 0, s[94:95]
	v_add_u32_e32 v195, 0x1cc00, v158
	ds_read_b128 v[226:229], v159
	ds_read_b128 v[230:233], v195
	global_load_lds_dwordx4 v[140:141], off
	v_lshl_add_u64 v[140:141], v[156:157], 0, s[94:95]
	s_mov_b32 m0, s45
	s_nop 0
	global_load_lds_dwordx4 v[140:141], off
	s_barrier
	s_waitcnt lgkmcnt(0)
	v_mfma_f32_16x16x32_f16 v[118:121], v[218:221], v[172:175], v[118:121]
	v_mfma_f32_16x16x32_f16 v[114:117], v[226:229], v[172:175], v[114:117]
	v_mfma_f32_16x16x32_f16 v[102:105], v[218:221], v[180:183], v[102:105]
	v_mfma_f32_16x16x32_f16 v[98:101], v[226:229], v[180:183], v[98:101]
	v_mfma_f32_16x16x32_f16 v[86:89], v[218:221], v[202:205], v[86:89]
	v_mfma_f32_16x16x32_f16 v[82:85], v[226:229], v[202:205], v[82:85]
	v_mfma_f32_16x16x32_f16 v[70:73], v[218:221], v[210:213], v[70:73]
	v_mfma_f32_16x16x32_f16 v[66:69], v[226:229], v[210:213], v[66:69]
	v_mfma_f32_16x16x32_f16 v[118:121], v[222:225], v[176:179], v[118:121]
	v_mfma_f32_16x16x32_f16 v[114:117], v[230:233], v[176:179], v[114:117]
	v_mfma_f32_16x16x32_f16 v[102:105], v[222:225], v[184:187], v[102:105]
	v_mfma_f32_16x16x32_f16 v[98:101], v[230:233], v[184:187], v[98:101]
	v_mfma_f32_16x16x32_f16 v[86:89], v[222:225], v[206:209], v[86:89]
	v_mfma_f32_16x16x32_f16 v[82:85], v[230:233], v[206:209], v[82:85]
	v_mfma_f32_16x16x32_f16 v[70:73], v[222:225], v[214:217], v[70:73]
	v_mfma_f32_16x16x32_f16 v[66:69], v[230:233], v[214:217], v[66:69]
	s_mov_b32 m0, s46
	v_lshl_add_u64 v[140:141], v[188:189], 0, s[94:95]
	s_barrier
	ds_read_b128 v[172:175], v135 offset:49152
	ds_read_b128 v[176:179], v135 offset:50176
	ds_read_b128 v[180:183], v135 offset:51200
	ds_read_b128 v[184:187], v135 offset:52224
	ds_read_b128 v[202:205], v135 offset:53248
	ds_read_b128 v[206:209], v135 offset:54272
	ds_read_b128 v[210:213], v135 offset:55296
	ds_read_b128 v[214:217], v135 offset:56320
	global_load_lds_dwordx4 v[140:141], off
	v_lshl_add_u64 v[140:141], v[234:235], 0, s[94:95]
	s_mov_b32 m0, s47
	s_nop 0
	global_load_lds_dwordx4 v[140:141], off
	s_waitcnt vmcnt(10)
	s_barrier
; #define G8_STAGE(bufoff, gbase) do { _Pragma("unroll") for (int _i = 0; _i < 2; ++_i) \
;     __builtin_amdgcn_global_load_lds((const unsigned*)((const char*)(gbase) + voffA[_i]), (LAS unsigned*)(lds + (bufoff) + ldsw + _i * 8192), 16, 0, 0); } while (0)
; #define G8_LDA(dst, b, h) do { _Pragma("unroll") for (int m = 0; m < 4; ++m) _Pragma("unroll") for (int k = 0; k < 2; ++k) dst[m][k] = *(const LAS h16x8*)(lds + G8_SA(b, h) + aoff + m * 2048 + k * 1024); } while (0)
; #define G8_LDB(dst, b, h) do { _Pragma("unroll") for (int n = 0; n < 2; ++n) _Pragma("unroll") for (int k = 0; k < 2; ++k) dst[n][k] = *(const LAS h16x8*)(lds + G8_SB(b, h) + boff + n * 2048 + k * 1024); } while (0)
; #define G8_BAR __builtin_amdgcn_s_barrier()
; template <class Epi>
; __device__ __forceinline__ void gemm_phase(LAS unsigned char* lds, const h16* A, const h16* Bt, int K, const Order& S, const Epi& E) {
;     ...
;       G8_WAIT_L(8); G8_BAR; G8_WAIT_L(0); G8_MMA(0, 0, At, B0); G8_BAR; G8_SCHED;
;       G8_LDB(B1, 1, 1); G8_STAGE(G8_SB(1, 0), b3);
;       G8_BAR; G8_WAIT_L(0); G8_MMA(0, 1, At, B1); G8_BAR;
;       G8_LDA(At, 1, 1); G8_STAGE(G8_SA(1, 0), a3);
;       G8_BAR; G8_WAIT_L(0); G8_MMA(1, 0, At, B0); G8_BAR; G8_SCHED;
;       G8_STAGE(G8_SB(1, 1), b3 + hstep);
;       G8_WAIT_V(6); G8_BAR; G8_MMA(1, 1, At, B1); G8_BAR;
;     }
;   __device__ __forceinline__ void operator()(const f32x4 (&acc)[2][2][4][2], const g8::Unit& u, int ui, int wr, int wc, int fr, int fq) const {
; #pragma unroll
;     for (int ai = 0; ai < 2; ++ai)
; #pragma unroll
;       for (int m = 0; m < 4; ++m) {
;         const size_t row = (size_t)u.pm * 256 + 128 * ai + 64 * wr + 16 * m + fr;
;         const size_t base = row * DM + 256 * u.pn + 32 * wc + 8 * fq;
;         float ss = 0.f;
; #pragma unroll
;         for (int bj = 0; bj < 2; ++bj) {
;           const size_t idx = base + 128 * bj;
;           const h16x8 xv = *(const h16x8*)(xb + idx);
;           f32x4 x0 = acc[ai][bj][m][0], x1 = acc[ai][bj][m][1];
; #pragma unroll
;           for (int j = 0; j < 4; ++j) { x0[j] += (float)xv[j]; x1[j] += (float)xv[4 + j]; ss += x0[j] * x0[j] + x1[j] * x1[j]; }
;           if (final_out) {
;             __builtin_nontemporal_store(x0, (f32x4*)(xo + idx));
;             __builtin_nontemporal_store(x1, (f32x4*)(xo + idx + 4));
;           } else {
;             *(h16x8*)(xb + idx) = pack8(x0, x1);
;           }
	s_waitcnt lgkmcnt(0)
	v_mfma_f32_16x16x32_f16 v[62:65], v[152:155], v[172:175], v[62:65]
	v_mfma_f32_16x16x32_f16 v[58:61], v[164:167], v[172:175], v[58:61]
	v_mfma_f32_16x16x32_f16 v[46:49], v[152:155], v[180:183], v[46:49]
	v_mfma_f32_16x16x32_f16 v[42:45], v[164:167], v[180:183], v[42:45]
	v_mfma_f32_16x16x32_f16 v[30:33], v[152:155], v[202:205], v[30:33]
	v_mfma_f32_16x16x32_f16 v[26:29], v[164:167], v[202:205], v[26:29]
	v_mfma_f32_16x16x32_f16 v[14:17], v[152:155], v[210:213], v[14:17]
	v_mfma_f32_16x16x32_f16 v[10:13], v[164:167], v[210:213], v[10:13]
	v_mfma_f32_16x16x32_f16 v[62:65], v[160:163], v[176:179], v[62:65]
	v_mfma_f32_16x16x32_f16 v[58:61], v[168:171], v[176:179], v[58:61]
	v_mfma_f32_16x16x32_f16 v[46:49], v[160:163], v[184:187], v[46:49]
	v_mfma_f32_16x16x32_f16 v[42:45], v[168:171], v[184:187], v[42:45]
	v_mfma_f32_16x16x32_f16 v[30:33], v[160:163], v[206:209], v[30:33]
	v_mfma_f32_16x16x32_f16 v[26:29], v[168:171], v[206:209], v[26:29]
	v_mfma_f32_16x16x32_f16 v[14:17], v[160:163], v[214:217], v[14:17]
	v_mfma_f32_16x16x32_f16 v[10:13], v[168:171], v[214:217], v[10:13]
	s_barrier
	s_add_u32 s24, s24, 0x100080
	s_addc_u32 s25, s25, 0
	s_mov_b32 m0, s48
	v_lshl_add_u64 v[140:141], s[24:25], 0, v[0:1]
	global_load_lds_dwordx4 v[140:141], off
	v_lshl_add_u64 v[140:141], s[24:25], 0, v[130:131]
	s_mov_b32 m0, s49
	s_nop 0
	global_load_lds_dwordx4 v[140:141], off
	v_or_b32_e32 v140, 0x10000, v158
	v_add_u32_e32 v141, 0x10400, v158
	ds_read_b128 v[152:155], v140
	ds_read_b128 v[160:163], v141
	v_add_u32_e32 v140, 0x10800, v158
	v_add_u32_e32 v141, 0x10c00, v158
	ds_read_b128 v[164:167], v140
	ds_read_b128 v[168:171], v141
	s_waitcnt vmcnt(6)
	s_barrier
	v_mfma_f32_16x16x32_f16 v[54:57], v[218:221], v[172:175], v[54:57]
	v_mfma_f32_16x16x32_f16 v[50:53], v[226:229], v[172:175], v[50:53]
	v_mfma_f32_16x16x32_f16 v[38:41], v[218:221], v[180:183], v[38:41]
	v_mfma_f32_16x16x32_f16 v[34:37], v[226:229], v[180:183], v[34:37]
	v_mfma_f32_16x16x32_f16 v[22:25], v[218:221], v[202:205], v[22:25]
	v_mfma_f32_16x16x32_f16 v[18:21], v[226:229], v[202:205], v[18:21]
	v_mfma_f32_16x16x32_f16 v[6:9], v[218:221], v[210:213], v[6:9]
	v_mfma_f32_16x16x32_f16 v[2:5], v[226:229], v[210:213], v[2:5]
	v_mfma_f32_16x16x32_f16 v[54:57], v[222:225], v[176:179], v[54:57]
	v_mfma_f32_16x16x32_f16 v[50:53], v[230:233], v[176:179], v[50:53]
	v_mfma_f32_16x16x32_f16 v[38:41], v[222:225], v[184:187], v[38:41]
	v_mfma_f32_16x16x32_f16 v[34:37], v[230:233], v[184:187], v[34:37]
	v_mfma_f32_16x16x32_f16 v[22:25], v[222:225], v[206:209], v[22:25]
	v_mfma_f32_16x16x32_f16 v[18:21], v[230:233], v[206:209], v[18:21]
	v_mfma_f32_16x16x32_f16 v[6:9], v[222:225], v[214:217], v[6:9]
	v_mfma_f32_16x16x32_f16 v[2:5], v[230:233], v[214:217], v[2:5]
	s_add_i32 s53, s53, 2
	s_add_u32 s22, s22, 0x100
	s_addc_u32 s23, s23, 0
	s_add_u32 s51, s51, 0x100
	s_addc_u32 s52, s52, 0
	s_cmp_gt_u32 s53, 61
	s_barrier
	s_cbranch_scc0 .LBB0_2542
	s_waitcnt lgkmcnt(0)
	s_ashr_i32 s9, s8, 31
	s_lshl_b64 s[8:9], s[8:9], 8
	s_lshl_b32 s3, s2, 8
	v_lshl_add_u64 v[140:141], s[8:9], 0, v[132:133]
	s_ashr_i32 s8, s3, 31
	v_mov_b32_e32 v153, s8
	v_or_b32_e32 v152, s3, v134
	v_lshlrev_b64 v[154:155], 10, v[140:141]
	v_lshl_add_u64 v[156:157], v[154:155], 0, v[152:153]
	v_lshl_add_u64 v[154:155], v[156:157], 1, s[10:11]
	global_load_dwordx4 v[166:169], v[154:155], off
	global_load_dwordx4 v[170:173], v[154:155], off offset:256
	s_mov_b32 s9, 0
	s_mov_b32 s8, 0x8000
	v_lshl_add_u64 v[234:235], v[154:155], 0, s[8:9]
	global_load_dwordx4 v[174:177], v[234:235], off
	global_load_dwordx4 v[178:181], v[234:235], off offset:256
	s_mov_b32 s8, 0x10000
	v_lshl_add_u64 v[234:235], v[154:155], 0, s[8:9]
	global_load_dwordx4 v[182:185], v[234:235], off
	global_load_dwordx4 v[186:189], v[234:235], off offset:256
	s_mov_b32 s8, 0x18000
	v_lshl_add_u64 v[234:235], v[154:155], 0, s[8:9]
	global_load_dwordx4 v[202:205], v[234:235], off
	global_load_dwordx4 v[206:209], v[234:235], off offset:256
	s_mov_b32 s8, 0x40000
	v_lshl_add_u64 v[234:235], v[154:155], 0, s[8:9]
	global_load_dwordx4 v[210:213], v[234:235], off
	global_load_dwordx4 v[214:217], v[234:235], off offset:256
	s_mov_b32 s8, 0x48000
	v_lshl_add_u64 v[234:235], v[154:155], 0, s[8:9]
	global_load_dwordx4 v[218:221], v[234:235], off
	global_load_dwordx4 v[222:225], v[234:235], off offset:256
	s_mov_b32 s8, 0x50000
	v_lshl_add_u64 v[234:235], v[154:155], 0, s[8:9]
	global_load_dwordx4 v[226:229], v[234:235], off
	global_load_dwordx4 v[230:233], v[234:235], off offset:256
	s_mov_b64 s[8:9], -1
	s_and_b64 vcc, exec, s[0:1]
	s_waitcnt vmcnt(13)
	v_cvt_f32_f16_e32 v164, v166
	v_cvt_f32_f16_sdwa v165, v166 dst_sel:DWORD dst_unused:UNUSED_PAD src0_sel:WORD_1
	v_cvt_f32_f16_e32 v160, v167
	v_cvt_f32_f16_sdwa v161, v167 dst_sel:DWORD dst_unused:UNUSED_PAD src0_sel:WORD_1
	v_pk_add_f32 v[126:127], v[126:127], v[164:165]
	v_cvt_f32_f16_e32 v164, v168
	v_cvt_f32_f16_sdwa v165, v168 dst_sel:DWORD dst_unused:UNUSED_PAD src0_sel:WORD_1
	v_pk_add_f32 v[128:129], v[128:129], v[160:161]
	v_cvt_f32_f16_e32 v160, v169
	v_cvt_f32_f16_sdwa v161, v169 dst_sel:DWORD dst_unused:UNUSED_PAD src0_sel:WORD_1
	v_pk_add_f32 v[122:123], v[122:123], v[164:165]
	v_pk_add_f32 v[124:125], v[124:125], v[160:161]
	s_cbranch_vccz .LBB0_2545
	v_cvt_pk_f16_f32 v163, v124, v125
	v_cvt_pk_f16_f32 v162, v122, v123
	v_cvt_pk_f16_f32 v161, v128, v129
	v_cvt_pk_f16_f32 v160, v126, v127
	global_store_dwordx4 v[154:155], v[160:163], off
	s_mov_b64 s[8:9], 0
